# v56 + the redundant s_waitcnt lgkmcnt(0) behind the barrier at the head of every MFMA segment removed (32 places, 8 GEMM loops): one instruction less on the critical MFMA path
# speedup vs baseline: 1.0072x; 1.0072x over previous
;     __device__ __forceinline__ bool next(int i, Unit& u) const { u.seg = 0; u.ks = -1; u.nt = ntk; u.koff = 0; return unit(i, u); }
;     __device__ __forceinline__ bool next(int i, Unit& u) const { const int t = i / 3; u.seg = i - 3 * t; u.ks = -1; u.nt = ntk; u.koff = 0; return unit(t, u); }
;     __device__ __forceinline__ bool next(int i, Unit& u) const { if (i > 0 || c < 80 || c >= 144) return false; const int k = c - 80; u.pm = k & 1; u.pn = k >> 1; u.seg = 0; u.ks = -1; u.nt = DM / BK; u.koff = 0; return true; }
; #define PG8_STAGE(bufoff, gbase, voff) do { _Pragma("unroll") for (int _i = 0; _i < 2; ++_i) \
;         __builtin_amdgcn_global_load_lds((const unsigned*)((const char*)(gbase) + (voff)[_i]), (LAS unsigned*)(lds + (bufoff) + ldsw + _i * 8192), 16, 0, 0); } while (0)
; #define PG8_LDA(dst, b, h) do { _Pragma("unroll") for (int m = 0; m < 4; ++m) _Pragma("unroll") for (int k = 0; k < 2; ++k) dst[m][k] = *(const LAS bf16x8*)(lds + PG8_SA(b, h) + aoff + m * 2048 + k * 1024); } while (0)
; template <class Epi, class Sched, bool I8 = false>
; __device__ __forceinline__ void gemm_phase(LAS unsigned char* lds, const Gemm g, const Sched& S, const Epi& E) {
;     ...
;         const bool has_next = S.next(ui + 1, nxt);
;         const char* nA = has_next ? g.A + (size_t)nxt.seg * g.segA + (size_t)nxt.pm * tstepA + nxt.koff : cA; const char* nB = has_next ? g.Bt + (size_t)nxt.seg * g.segB + (size_t)nxt.pn * tstepB + nxt.koff : cB;
;         const int nt = cur.nt;
;         for (int t = 0; t < nt; t += 2) {
;             const bool last = (t == nt - 2);
;             const char* a1 = cA + (size_t)(t + 1) * kstep;
;             const char* a2 = last ? nA : cA + (size_t)(t + 2) * kstep; const char* b2 = last ? nB : cB + (size_t)(t + 2) * kstep;
;             const char* a3 = a2 + kstep; const char* b3 = b2 + kstep;
;             if (PG8_SP2) {
;             PG8_LDB(B0, 0, 0); PG8_LDB(B1, 0, 1); PG8_SCHED; PG8_LDA(At, 0, 0); PG8_STAGE(PG8_SA(1, 1), a1 + hstepA, voffA);
;             PG8_WAIT_V(8); PG8_WAIT_L(0); PG8_BAR; PG8_MMA(0, 0, At, B0); PG8_MMA(0, 1, At, B1); PG8_BAR; PG8_SCHED;
;             PG8_LDA(At, 0, 1); PG8_STAGE(PG8_SB(0, 0), b2, voffB); PG8_STAGE(PG8_SB(0, 1), b2 + hstepB, voffB); PG8_STAGE(PG8_SA(0, 0), a2, voffA);
;             PG8_WAIT_V(8); PG8_WAIT_L(0); PG8_BAR; PG8_MMA(1, 0, At, B0); PG8_MMA(1, 1, At, B1); PG8_BAR; PG8_SCHED;
.LBB0_281:
	s_add_i32 s4, s0, 0xff840080
	s_cmp_lg_u32 s24, 28
	s_cselect_b32 s4, s4, 0
	s_add_u32 s6, s34, s4
	s_addc_u32 s7, s35, 0
	s_add_i32 s25, 0, 0x10000
	s_add_u32 s4, s30, s4
	s_addc_u32 s5, s31, 0
	s_add_i32 s29, 0, 0x14000
	v_add_u32_e32 v158, s25, v144
	v_add_u32_e32 v174, s29, v144
	ds_read_b128 v[146:149], v158
	ds_read_b128 v[150:153], v158 offset:1024
	ds_read_b128 v[154:157], v158 offset:2048
	ds_read_b128 v[158:161], v158 offset:3072
	ds_read_b128 v[162:165], v174
	ds_read_b128 v[166:169], v174 offset:1024
	ds_read_b128 v[170:173], v174 offset:2048
	ds_read_b128 v[174:177], v174 offset:3072
	v_lshl_add_u64 v[202:203], v[138:139], 0, s[0:1]
	s_add_i32 m0, s8, 0xc000
	ds_read_b128 v[178:181], v145
	ds_read_b128 v[182:185], v145 offset:1024
	ds_read_b128 v[186:189], v145 offset:2048
	ds_read_b128 v[190:193], v145 offset:3072
	ds_read_b128 v[194:197], v145 offset:4096
	ds_read_b128 v[198:201], v145 offset:5120
	ds_read_b128 v[212:215], v145 offset:6144
	ds_read_b128 v[216:219], v145 offset:7168
	global_load_lds_dwordx4 v[202:203], off
	v_lshl_add_u64 v[202:203], v[140:141], 0, s[0:1]
	s_add_i32 m0, s8, 0xe000
	s_nop 0
	global_load_lds_dwordx4 v[202:203], off
	s_waitcnt vmcnt(8)
	s_waitcnt lgkmcnt(0)
	s_barrier
	s_setprio 1
	v_mfma_f32_16x16x32_bf16 v[126:129], v[146:149], v[178:181], v[126:129]
	v_mfma_f32_16x16x32_bf16 v[122:125], v[154:157], v[178:181], v[122:125]
	v_mfma_f32_16x16x32_bf16 v[110:113], v[146:149], v[186:189], v[110:113]
	v_mfma_f32_16x16x32_bf16 v[106:109], v[154:157], v[186:189], v[106:109]
	v_mfma_f32_16x16x32_bf16 v[94:97], v[146:149], v[194:197], v[94:97]
	v_mfma_f32_16x16x32_bf16 v[90:93], v[154:157], v[194:197], v[90:93]
	v_mfma_f32_16x16x32_bf16 v[78:81], v[146:149], v[212:215], v[78:81]
	v_mfma_f32_16x16x32_bf16 v[74:77], v[154:157], v[212:215], v[74:77]
	v_mfma_f32_16x16x32_bf16 v[126:129], v[150:153], v[182:185], v[126:129]
	v_mfma_f32_16x16x32_bf16 v[122:125], v[158:161], v[182:185], v[122:125]
	v_mfma_f32_16x16x32_bf16 v[110:113], v[150:153], v[190:193], v[110:113]
	v_mfma_f32_16x16x32_bf16 v[106:109], v[158:161], v[190:193], v[106:109]
	v_mfma_f32_16x16x32_bf16 v[94:97], v[150:153], v[198:201], v[94:97]
	v_mfma_f32_16x16x32_bf16 v[90:93], v[158:161], v[198:201], v[90:93]
	v_mfma_f32_16x16x32_bf16 v[78:81], v[150:153], v[216:219], v[78:81]
	v_mfma_f32_16x16x32_bf16 v[74:77], v[158:161], v[216:219], v[74:77]
	s_setprio 0
	s_setprio 1
	v_mfma_f32_16x16x32_bf16 v[118:121], v[162:165], v[178:181], v[118:121]
	v_mfma_f32_16x16x32_bf16 v[114:117], v[170:173], v[178:181], v[114:117]
	v_mfma_f32_16x16x32_bf16 v[102:105], v[162:165], v[186:189], v[102:105]
	v_mfma_f32_16x16x32_bf16 v[98:101], v[170:173], v[186:189], v[98:101]
	v_mfma_f32_16x16x32_bf16 v[86:89], v[162:165], v[194:197], v[86:89]
	v_mfma_f32_16x16x32_bf16 v[82:85], v[170:173], v[194:197], v[82:85]
	v_mfma_f32_16x16x32_bf16 v[70:73], v[162:165], v[212:215], v[70:73]
	v_mfma_f32_16x16x32_bf16 v[66:69], v[170:173], v[212:215], v[66:69]
	v_mfma_f32_16x16x32_bf16 v[118:121], v[166:169], v[182:185], v[118:121]
	v_mfma_f32_16x16x32_bf16 v[114:117], v[174:177], v[182:185], v[114:117]
	v_mfma_f32_16x16x32_bf16 v[102:105], v[166:169], v[190:193], v[102:105]
	v_mfma_f32_16x16x32_bf16 v[98:101], v[174:177], v[190:193], v[98:101]
	v_mfma_f32_16x16x32_bf16 v[86:89], v[166:169], v[198:201], v[86:89]
	v_mfma_f32_16x16x32_bf16 v[82:85], v[174:177], v[198:201], v[82:85]
	v_mfma_f32_16x16x32_bf16 v[70:73], v[166:169], v[216:219], v[70:73]
	v_mfma_f32_16x16x32_bf16 v[66:69], v[174:177], v[216:219], v[66:69]
	s_setprio 0
	s_barrier
	s_add_i32 s25, s25, s3
	v_lshl_add_u64 v[202:203], s[4:5], 0, v[130:131]
	s_mov_b32 m0, s25
	ds_read_b128 v[178:181], v145 offset:16384
	ds_read_b128 v[182:185], v145 offset:17408
	ds_read_b128 v[186:189], v145 offset:18432
	ds_read_b128 v[190:193], v145 offset:19456
	ds_read_b128 v[194:197], v145 offset:20480
	ds_read_b128 v[198:201], v145 offset:21504
	ds_read_b128 v[212:215], v145 offset:22528
	ds_read_b128 v[216:219], v145 offset:23552
	global_load_lds_dwordx4 v[202:203], off
	s_add_i32 m0, s25, 0x2000
	s_add_u32 s26, s4, 0x20000
	v_lshl_add_u64 v[220:221], s[4:5], 0, v[132:133]
	s_addc_u32 s27, s5, 0
	s_add_i32 s25, s29, s3
	global_load_lds_dwordx4 v[220:221], off
	v_lshl_add_u64 v[222:223], s[26:27], 0, v[130:131]
	s_mov_b32 m0, s25
	v_lshl_add_u64 v[224:225], s[6:7], 0, v[134:135]
	global_load_lds_dwordx4 v[222:223], off
	v_lshl_add_u64 v[222:223], s[26:27], 0, v[132:133]
	s_add_i32 m0, s25, 0x2000
	s_nop 0
	global_load_lds_dwordx4 v[222:223], off
	v_lshl_add_u64 v[222:223], s[6:7], 0, v[136:137]
	s_mov_b32 m0, s8
	s_nop 0
	global_load_lds_dwordx4 v[222:223], off
	s_mov_b32 m0, s9
	s_nop 0
	global_load_lds_dwordx4 v[224:225], off
	s_waitcnt vmcnt(8)
	s_waitcnt lgkmcnt(0)
	s_barrier
; #define PG8_STAGE(bufoff, gbase, voff) do { _Pragma("unroll") for (int _i = 0; _i < 2; ++_i) \
;         __builtin_amdgcn_global_load_lds((const unsigned*)((const char*)(gbase) + (voff)[_i]), (LAS unsigned*)(lds + (bufoff) + ldsw + _i * 8192), 16, 0, 0); } while (0)
; #define PG8_LDA(dst, b, h) do { _Pragma("unroll") for (int m = 0; m < 4; ++m) _Pragma("unroll") for (int k = 0; k < 2; ++k) dst[m][k] = *(const LAS bf16x8*)(lds + PG8_SA(b, h) + aoff + m * 2048 + k * 1024); } while (0)
; #define PG8_LDB(dst, b, h) do { _Pragma("unroll") for (int n = 0; n < 2; ++n) _Pragma("unroll") for (int k = 0; k < 2; ++k) dst[n][k] = *(const LAS bf16x8*)(lds + PG8_SB(b, h) + boff + n * 2048 + k * 1024); } while (0)
; #define PG8_MMA(ai, bj, At, Bt) do { __builtin_amdgcn_s_setprio(1); _Pragma("unroll") for (int m = 0; m < 4; ++m) _Pragma("unroll") for (int n = 0; n < 2; ++n) _Pragma("unroll") for (int k = 0; k < 2; ++k) \
;         acc[ai][bj][m][n] = mma16<I8>(Bt[n][k], At[m][k], acc[ai][bj][m][n]); __builtin_amdgcn_s_setprio(0); } while (0)
; #define PG8_WAIT_V(n) asm volatile("s_waitcnt vmcnt(" #n ")" ::: "memory")
; #define PG8_WAIT_L(n) asm volatile("s_waitcnt lgkmcnt(" #n ")" ::: "memory")
; #define PG8_BAR __builtin_amdgcn_s_barrier()
; #define PG8_SCHED __builtin_amdgcn_sched_barrier(0)
; template <class Epi, class Sched, bool I8 = false>
; __device__ __forceinline__ void gemm_phase(LAS unsigned char* lds, const Gemm g, const Sched& S, const Epi& E) {
;     ...
;             PG8_WAIT_V(8); PG8_WAIT_L(0); PG8_BAR; PG8_MMA(1, 0, At, B0); PG8_MMA(1, 1, At, B1); PG8_BAR; PG8_SCHED;
;             PG8_LDB(B0, 1, 0); PG8_LDB(B1, 1, 1); PG8_SCHED; PG8_LDA(At, 1, 0); PG8_STAGE(PG8_SA(0, 1), a2 + hstepA, voffA);
;             PG8_WAIT_V(8); PG8_WAIT_L(0); PG8_BAR; PG8_MMA(0, 0, At, B0); PG8_MMA(0, 1, At, B1); PG8_BAR; PG8_SCHED;
	s_setprio 1
	v_mfma_f32_16x16x32_bf16 v[62:65], v[146:149], v[178:181], v[62:65]
	v_mfma_f32_16x16x32_bf16 v[58:61], v[154:157], v[178:181], v[58:61]
	v_mfma_f32_16x16x32_bf16 v[46:49], v[146:149], v[186:189], v[46:49]
	v_mfma_f32_16x16x32_bf16 v[42:45], v[154:157], v[186:189], v[42:45]
	v_mfma_f32_16x16x32_bf16 v[30:33], v[146:149], v[194:197], v[30:33]
	v_mfma_f32_16x16x32_bf16 v[26:29], v[154:157], v[194:197], v[26:29]
	v_mfma_f32_16x16x32_bf16 v[14:17], v[146:149], v[212:215], v[14:17]
	v_mfma_f32_16x16x32_bf16 v[10:13], v[154:157], v[212:215], v[10:13]
	v_mfma_f32_16x16x32_bf16 v[62:65], v[150:153], v[182:185], v[62:65]
	v_mfma_f32_16x16x32_bf16 v[58:61], v[158:161], v[182:185], v[58:61]
	v_mfma_f32_16x16x32_bf16 v[46:49], v[150:153], v[190:193], v[46:49]
	v_mfma_f32_16x16x32_bf16 v[42:45], v[158:161], v[190:193], v[42:45]
	v_mfma_f32_16x16x32_bf16 v[30:33], v[150:153], v[198:201], v[30:33]
	v_mfma_f32_16x16x32_bf16 v[26:29], v[158:161], v[198:201], v[26:29]
	v_mfma_f32_16x16x32_bf16 v[14:17], v[150:153], v[216:219], v[14:17]
	v_mfma_f32_16x16x32_bf16 v[10:13], v[158:161], v[216:219], v[10:13]
	s_setprio 0
	s_setprio 1
	v_mfma_f32_16x16x32_bf16 v[54:57], v[162:165], v[178:181], v[54:57]
	v_mfma_f32_16x16x32_bf16 v[50:53], v[170:173], v[178:181], v[50:53]
	v_mfma_f32_16x16x32_bf16 v[38:41], v[162:165], v[186:189], v[38:41]
	v_mfma_f32_16x16x32_bf16 v[34:37], v[170:173], v[186:189], v[34:37]
	v_mfma_f32_16x16x32_bf16 v[22:25], v[162:165], v[194:197], v[22:25]
	v_mfma_f32_16x16x32_bf16 v[18:21], v[170:173], v[194:197], v[18:21]
	v_mfma_f32_16x16x32_bf16 v[6:9], v[162:165], v[212:215], v[6:9]
	v_mfma_f32_16x16x32_bf16 v[2:5], v[170:173], v[212:215], v[2:5]
	v_mfma_f32_16x16x32_bf16 v[54:57], v[166:169], v[182:185], v[54:57]
	v_mfma_f32_16x16x32_bf16 v[50:53], v[174:177], v[182:185], v[50:53]
	v_mfma_f32_16x16x32_bf16 v[38:41], v[166:169], v[190:193], v[38:41]
	v_mfma_f32_16x16x32_bf16 v[34:37], v[174:177], v[190:193], v[34:37]
	v_mfma_f32_16x16x32_bf16 v[22:25], v[166:169], v[198:201], v[22:25]
	v_mfma_f32_16x16x32_bf16 v[18:21], v[174:177], v[198:201], v[18:21]
	v_mfma_f32_16x16x32_bf16 v[6:9], v[166:169], v[216:219], v[6:9]
	v_mfma_f32_16x16x32_bf16 v[2:5], v[174:177], v[216:219], v[2:5]
	s_setprio 0
	s_barrier
	s_add_i32 s25, 0, 0x18000
	s_add_i32 s26, 0, 0x1c000
	v_add_u32_e32 v158, s25, v144
	v_add_u32_e32 v174, s26, v144
	ds_read_b128 v[146:149], v158
	ds_read_b128 v[150:153], v158 offset:1024
	ds_read_b128 v[154:157], v158 offset:2048
	ds_read_b128 v[158:161], v158 offset:3072
	ds_read_b128 v[162:165], v174
	ds_read_b128 v[166:169], v174 offset:1024
	ds_read_b128 v[170:173], v174 offset:2048
	ds_read_b128 v[174:177], v174 offset:3072
	s_add_u32 s6, s6, 0x80000
	s_addc_u32 s7, s7, 0
	s_mov_b32 m0, s14
	v_lshl_add_u64 v[226:227], s[6:7], 0, v[136:137]
	ds_read_b128 v[178:181], v145 offset:32768
	ds_read_b128 v[182:185], v145 offset:33792
	ds_read_b128 v[186:189], v145 offset:34816
	ds_read_b128 v[190:193], v145 offset:35840
	ds_read_b128 v[194:197], v145 offset:36864
	ds_read_b128 v[198:201], v145 offset:37888
	ds_read_b128 v[212:215], v145 offset:38912
	ds_read_b128 v[216:219], v145 offset:39936
	global_load_lds_dwordx4 v[226:227], off
	v_lshl_add_u64 v[226:227], s[6:7], 0, v[134:135]
	s_mov_b32 m0, s16
	s_nop 0
	global_load_lds_dwordx4 v[226:227], off
	s_waitcnt vmcnt(8)
	s_waitcnt lgkmcnt(0)
	s_barrier
	s_setprio 1
	v_mfma_f32_16x16x32_bf16 v[126:129], v[146:149], v[178:181], v[126:129]
	v_mfma_f32_16x16x32_bf16 v[122:125], v[154:157], v[178:181], v[122:125]
	v_mfma_f32_16x16x32_bf16 v[110:113], v[146:149], v[186:189], v[110:113]
	v_mfma_f32_16x16x32_bf16 v[106:109], v[154:157], v[186:189], v[106:109]
	v_mfma_f32_16x16x32_bf16 v[94:97], v[146:149], v[194:197], v[94:97]
	v_mfma_f32_16x16x32_bf16 v[90:93], v[154:157], v[194:197], v[90:93]
	v_mfma_f32_16x16x32_bf16 v[78:81], v[146:149], v[212:215], v[78:81]
	v_mfma_f32_16x16x32_bf16 v[74:77], v[154:157], v[212:215], v[74:77]
	v_mfma_f32_16x16x32_bf16 v[126:129], v[150:153], v[182:185], v[126:129]
	v_mfma_f32_16x16x32_bf16 v[122:125], v[158:161], v[182:185], v[122:125]
	v_mfma_f32_16x16x32_bf16 v[110:113], v[150:153], v[190:193], v[110:113]
	v_mfma_f32_16x16x32_bf16 v[106:109], v[158:161], v[190:193], v[106:109]
	v_mfma_f32_16x16x32_bf16 v[94:97], v[150:153], v[198:201], v[94:97]
	v_mfma_f32_16x16x32_bf16 v[90:93], v[158:161], v[198:201], v[90:93]
	v_mfma_f32_16x16x32_bf16 v[78:81], v[150:153], v[216:219], v[78:81]
	v_mfma_f32_16x16x32_bf16 v[74:77], v[158:161], v[216:219], v[74:77]
	s_setprio 0
	s_setprio 1
	v_mfma_f32_16x16x32_bf16 v[118:121], v[162:165], v[178:181], v[118:121]
	v_mfma_f32_16x16x32_bf16 v[114:117], v[170:173], v[178:181], v[114:117]
	v_mfma_f32_16x16x32_bf16 v[102:105], v[162:165], v[186:189], v[102:105]
	v_mfma_f32_16x16x32_bf16 v[98:101], v[170:173], v[186:189], v[98:101]
	v_mfma_f32_16x16x32_bf16 v[86:89], v[162:165], v[194:197], v[86:89]
	v_mfma_f32_16x16x32_bf16 v[82:85], v[170:173], v[194:197], v[82:85]
	v_mfma_f32_16x16x32_bf16 v[70:73], v[162:165], v[212:215], v[70:73]
	v_mfma_f32_16x16x32_bf16 v[66:69], v[170:173], v[212:215], v[66:69]
	v_mfma_f32_16x16x32_bf16 v[118:121], v[166:169], v[182:185], v[118:121]
	v_mfma_f32_16x16x32_bf16 v[114:117], v[174:177], v[182:185], v[114:117]
	v_mfma_f32_16x16x32_bf16 v[102:105], v[166:169], v[190:193], v[102:105]
	v_mfma_f32_16x16x32_bf16 v[98:101], v[174:177], v[190:193], v[98:101]
	v_mfma_f32_16x16x32_bf16 v[86:89], v[166:169], v[198:201], v[86:89]
	v_mfma_f32_16x16x32_bf16 v[82:85], v[174:177], v[198:201], v[82:85]
	v_mfma_f32_16x16x32_bf16 v[70:73], v[166:169], v[216:219], v[70:73]
	v_mfma_f32_16x16x32_bf16 v[66:69], v[174:177], v[216:219], v[66:69]
	s_setprio 0
	s_barrier
; #define PG8_STAGE(bufoff, gbase, voff) do { _Pragma("unroll") for (int _i = 0; _i < 2; ++_i) \
;         __builtin_amdgcn_global_load_lds((const unsigned*)((const char*)(gbase) + (voff)[_i]), (LAS unsigned*)(lds + (bufoff) + ldsw + _i * 8192), 16, 0, 0); } while (0)
; #define PG8_LDA(dst, b, h) do { _Pragma("unroll") for (int m = 0; m < 4; ++m) _Pragma("unroll") for (int k = 0; k < 2; ++k) dst[m][k] = *(const LAS bf16x8*)(lds + PG8_SA(b, h) + aoff + m * 2048 + k * 1024); } while (0)
; #define PG8_MMA(ai, bj, At, Bt) do { __builtin_amdgcn_s_setprio(1); _Pragma("unroll") for (int m = 0; m < 4; ++m) _Pragma("unroll") for (int n = 0; n < 2; ++n) _Pragma("unroll") for (int k = 0; k < 2; ++k) \
;         acc[ai][bj][m][n] = mma16<I8>(Bt[n][k], At[m][k], acc[ai][bj][m][n]); __builtin_amdgcn_s_setprio(0); } while (0)
; #define PG8_WAIT_V(n) asm volatile("s_waitcnt vmcnt(" #n ")" ::: "memory")
; #define PG8_WAIT_L(n) asm volatile("s_waitcnt lgkmcnt(" #n ")" ::: "memory")
; #define PG8_BAR __builtin_amdgcn_s_barrier()
; #define PG8_SCHED __builtin_amdgcn_sched_barrier(0)
; template <class Epi, class Sched, bool I8 = false>
; __device__ __forceinline__ void gemm_phase(LAS unsigned char* lds, const Gemm g, const Sched& S, const Epi& E) {
;     ...
;         for (int t = 0; t < nt; t += 2) {
;             const bool last = (t == nt - 2);
;     ...
;             PG8_LDA(At, 1, 1); PG8_STAGE(PG8_SB(1, 0), b3, voffB); PG8_STAGE(PG8_SB(1, 1), b3 + hstepB, voffB); PG8_STAGE(PG8_SA(1, 0), a3, voffA);
;             PG8_WAIT_V(8); PG8_WAIT_L(0); PG8_BAR; PG8_MMA(1, 0, At, B0); PG8_MMA(1, 1, At, B1); PG8_BAR; PG8_SCHED;
	s_add_i32 s6, s25, s3
	v_lshl_add_u64 v[202:203], v[202:203], 0, s[12:13]
	s_mov_b32 m0, s6
	ds_read_b128 v[178:181], v145 offset:49152
	ds_read_b128 v[182:185], v145 offset:50176
	ds_read_b128 v[186:189], v145 offset:51200
	ds_read_b128 v[190:193], v145 offset:52224
	ds_read_b128 v[194:197], v145 offset:53248
	ds_read_b128 v[198:201], v145 offset:54272
	ds_read_b128 v[212:215], v145 offset:55296
	ds_read_b128 v[216:219], v145 offset:56320
	global_load_lds_dwordx4 v[202:203], off
	s_add_i32 m0, s6, 0x2000
	s_add_u32 s4, s4, 0x20080
	v_lshl_add_u64 v[202:203], v[220:221], 0, s[12:13]
	s_addc_u32 s5, s5, 0
	s_add_i32 s6, s26, s3
	global_load_lds_dwordx4 v[202:203], off
	v_lshl_add_u64 v[202:203], s[4:5], 0, v[130:131]
	s_mov_b32 m0, s6
	s_nop 0
	global_load_lds_dwordx4 v[202:203], off
	v_lshl_add_u64 v[202:203], s[4:5], 0, v[132:133]
	s_add_i32 m0, s6, 0x2000
	s_nop 0
	global_load_lds_dwordx4 v[202:203], off
	v_lshl_add_u64 v[202:203], v[222:223], 0, s[12:13]
	s_mov_b32 m0, s22
	s_nop 0
	global_load_lds_dwordx4 v[202:203], off
	v_lshl_add_u64 v[202:203], v[224:225], 0, s[12:13]
	s_mov_b32 m0, s23
	s_nop 0
	global_load_lds_dwordx4 v[202:203], off
	s_waitcnt vmcnt(8)
	s_waitcnt lgkmcnt(0)
	s_barrier
	s_setprio 1
	v_mfma_f32_16x16x32_bf16 v[62:65], v[146:149], v[178:181], v[62:65]
	v_mfma_f32_16x16x32_bf16 v[58:61], v[154:157], v[178:181], v[58:61]
	v_mfma_f32_16x16x32_bf16 v[46:49], v[146:149], v[186:189], v[46:49]
	v_mfma_f32_16x16x32_bf16 v[42:45], v[154:157], v[186:189], v[42:45]
	v_mfma_f32_16x16x32_bf16 v[30:33], v[146:149], v[194:197], v[30:33]
	v_mfma_f32_16x16x32_bf16 v[26:29], v[154:157], v[194:197], v[26:29]
	v_mfma_f32_16x16x32_bf16 v[14:17], v[146:149], v[212:215], v[14:17]
	v_mfma_f32_16x16x32_bf16 v[10:13], v[154:157], v[212:215], v[10:13]
	v_mfma_f32_16x16x32_bf16 v[62:65], v[150:153], v[182:185], v[62:65]
	v_mfma_f32_16x16x32_bf16 v[58:61], v[158:161], v[182:185], v[58:61]
	v_mfma_f32_16x16x32_bf16 v[46:49], v[150:153], v[190:193], v[46:49]
	v_mfma_f32_16x16x32_bf16 v[42:45], v[158:161], v[190:193], v[42:45]
	v_mfma_f32_16x16x32_bf16 v[30:33], v[150:153], v[198:201], v[30:33]
	v_mfma_f32_16x16x32_bf16 v[26:29], v[158:161], v[198:201], v[26:29]
	v_mfma_f32_16x16x32_bf16 v[14:17], v[150:153], v[216:219], v[14:17]
	v_mfma_f32_16x16x32_bf16 v[10:13], v[158:161], v[216:219], v[10:13]
	s_setprio 0
	s_setprio 1
	v_mfma_f32_16x16x32_bf16 v[54:57], v[162:165], v[178:181], v[54:57]
	v_mfma_f32_16x16x32_bf16 v[50:53], v[170:173], v[178:181], v[50:53]
	v_mfma_f32_16x16x32_bf16 v[38:41], v[162:165], v[186:189], v[38:41]
	v_mfma_f32_16x16x32_bf16 v[34:37], v[170:173], v[186:189], v[34:37]
	v_mfma_f32_16x16x32_bf16 v[22:25], v[162:165], v[194:197], v[22:25]
	v_mfma_f32_16x16x32_bf16 v[18:21], v[170:173], v[194:197], v[18:21]
	v_mfma_f32_16x16x32_bf16 v[6:9], v[162:165], v[212:215], v[6:9]
	v_mfma_f32_16x16x32_bf16 v[2:5], v[170:173], v[212:215], v[2:5]
	v_mfma_f32_16x16x32_bf16 v[54:57], v[166:169], v[182:185], v[54:57]
	v_mfma_f32_16x16x32_bf16 v[50:53], v[174:177], v[182:185], v[50:53]
	v_mfma_f32_16x16x32_bf16 v[38:41], v[166:169], v[190:193], v[38:41]
	v_mfma_f32_16x16x32_bf16 v[34:37], v[174:177], v[190:193], v[34:37]
	v_mfma_f32_16x16x32_bf16 v[22:25], v[166:169], v[198:201], v[22:25]
	v_mfma_f32_16x16x32_bf16 v[18:21], v[174:177], v[198:201], v[18:21]
	v_mfma_f32_16x16x32_bf16 v[6:9], v[166:169], v[216:219], v[6:9]
	v_mfma_f32_16x16x32_bf16 v[2:5], v[174:177], v[216:219], v[2:5]
	s_setprio 0
	s_barrier
	s_add_i32 s24, s24, 2
	s_add_u32 s0, s0, 0x100
	s_addc_u32 s1, s1, 0
	s_cmp_gt_u32 s24, 29
	s_cbranch_scc0 .LBB0_281
	s_cmpk_lt_u32 s2, 0x100
	v_readlane_b32 s22, v249, 31
	v_readlane_b32 s23, v249, 32
	s_cbranch_scc0 .LBB0_284
	s_barrier

;     __device__ __forceinline__ bool next(int i, Unit& u) const { u.seg = 0; u.ks = -1; u.nt = ntk; u.koff = 0; return unit(i, u); }
;     __device__ __forceinline__ bool next(int i, Unit& u) const { const int t = i / 3; u.seg = i - 3 * t; u.ks = -1; u.nt = ntk; u.koff = 0; return unit(t, u); }
;     __device__ __forceinline__ bool next(int i, Unit& u) const { if (i > 0 || c < 80 || c >= 144) return false; const int k = c - 80; u.pm = k & 1; u.pn = k >> 1; u.seg = 0; u.ks = -1; u.nt = DM / BK; u.koff = 0; return true; }
; #define PG8_STAGE(bufoff, gbase, voff) do { _Pragma("unroll") for (int _i = 0; _i < 2; ++_i) \
;         __builtin_amdgcn_global_load_lds((const unsigned*)((const char*)(gbase) + (voff)[_i]), (LAS unsigned*)(lds + (bufoff) + ldsw + _i * 8192), 16, 0, 0); } while (0)
; #define PG8_LDA(dst, b, h) do { _Pragma("unroll") for (int m = 0; m < 4; ++m) _Pragma("unroll") for (int k = 0; k < 2; ++k) dst[m][k] = *(const LAS bf16x8*)(lds + PG8_SA(b, h) + aoff + m * 2048 + k * 1024); } while (0)
; template <class Epi, class Sched, bool I8 = false>
; __device__ __forceinline__ void gemm_phase(LAS unsigned char* lds, const Gemm g, const Sched& S, const Epi& E) {
;     ...
;         const bool has_next = S.next(ui + 1, nxt);
;         const char* nA = has_next ? g.A + (size_t)nxt.seg * g.segA + (size_t)nxt.pm * tstepA + nxt.koff : cA; const char* nB = has_next ? g.Bt + (size_t)nxt.seg * g.segB + (size_t)nxt.pn * tstepB + nxt.koff : cB;
;         const int nt = cur.nt;
;         for (int t = 0; t < nt; t += 2) {
;             const bool last = (t == nt - 2);
;             const char* a1 = cA + (size_t)(t + 1) * kstep;
;             const char* a2 = last ? nA : cA + (size_t)(t + 2) * kstep; const char* b2 = last ? nB : cB + (size_t)(t + 2) * kstep;
;             const char* a3 = a2 + kstep; const char* b3 = b2 + kstep;
;             if (PG8_SP2) {
;             PG8_LDB(B0, 0, 0); PG8_LDB(B1, 0, 1); PG8_SCHED; PG8_LDA(At, 0, 0); PG8_STAGE(PG8_SA(1, 1), a1 + hstepA, voffA);
;             PG8_WAIT_V(8); PG8_WAIT_L(0); PG8_BAR; PG8_MMA(0, 0, At, B0); PG8_MMA(0, 1, At, B1); PG8_BAR; PG8_SCHED;
;             PG8_LDA(At, 0, 1); PG8_STAGE(PG8_SB(0, 0), b2, voffB); PG8_STAGE(PG8_SB(0, 1), b2 + hstepB, voffB); PG8_STAGE(PG8_SA(0, 0), a2, voffA);
;             PG8_WAIT_V(8); PG8_WAIT_L(0); PG8_BAR; PG8_MMA(1, 0, At, B0); PG8_MMA(1, 1, At, B1); PG8_BAR; PG8_SCHED;
.LBB0_356:
	s_add_u32 s4, s0, 0xfff80080
	s_addc_u32 s5, s1, -1
	s_add_i32 s30, 0, 0x10000
	s_cmp_eq_u32 s29, 28
	s_cselect_b32 s7, s14, s5
	s_cselect_b32 s6, s21, s4
	v_add_u32_e32 v130, s30, v141
	s_cselect_b32 s5, s22, s25
	s_cselect_b32 s4, s23, s24
	s_add_i32 s34, 0, 0x14000
	ds_read_b128 v[150:153], v130
	ds_read_b128 v[154:157], v130 offset:1024
	ds_read_b128 v[158:161], v130 offset:2048
	ds_read_b128 v[162:165], v130 offset:3072
	v_add_u32_e32 v130, s34, v141
	ds_read_b128 v[166:169], v130
	ds_read_b128 v[170:173], v130 offset:1024
	ds_read_b128 v[174:177], v130 offset:2048
	ds_read_b128 v[178:181], v130 offset:3072
	v_lshl_add_u64 v[202:203], s[0:1], 0, v[146:147]
	s_add_i32 m0, s41, 0xc000
	ds_read_b128 v[182:185], v143
	ds_read_b128 v[186:189], v143 offset:1024
	ds_read_b128 v[190:193], v143 offset:2048
	ds_read_b128 v[194:197], v143 offset:3072
	ds_read_b128 v[198:201], v143 offset:4096
	ds_read_b128 v[212:215], v143 offset:5120
	ds_read_b128 v[216:219], v143 offset:6144
	ds_read_b128 v[220:223], v143 offset:7168
	global_load_lds_dwordx4 v[202:203], off
	v_lshl_add_u64 v[202:203], s[0:1], 0, v[148:149]
	s_add_i32 m0, s41, 0xe000
	s_nop 0
	global_load_lds_dwordx4 v[202:203], off
	s_waitcnt vmcnt(8)
	s_waitcnt lgkmcnt(0)
	s_barrier
	s_setprio 1
	v_mfma_f32_16x16x32_bf16 v[126:129], v[150:153], v[182:185], v[126:129]
	v_mfma_f32_16x16x32_bf16 v[122:125], v[158:161], v[182:185], v[122:125]
	v_mfma_f32_16x16x32_bf16 v[110:113], v[150:153], v[190:193], v[110:113]
	v_mfma_f32_16x16x32_bf16 v[106:109], v[158:161], v[190:193], v[106:109]
	v_mfma_f32_16x16x32_bf16 v[94:97], v[150:153], v[198:201], v[94:97]
	v_mfma_f32_16x16x32_bf16 v[90:93], v[158:161], v[198:201], v[90:93]
	v_mfma_f32_16x16x32_bf16 v[78:81], v[150:153], v[216:219], v[78:81]
	v_mfma_f32_16x16x32_bf16 v[74:77], v[158:161], v[216:219], v[74:77]
	v_mfma_f32_16x16x32_bf16 v[126:129], v[154:157], v[186:189], v[126:129]
	v_mfma_f32_16x16x32_bf16 v[122:125], v[162:165], v[186:189], v[122:125]
	v_mfma_f32_16x16x32_bf16 v[110:113], v[154:157], v[194:197], v[110:113]
	v_mfma_f32_16x16x32_bf16 v[106:109], v[162:165], v[194:197], v[106:109]
	v_mfma_f32_16x16x32_bf16 v[94:97], v[154:157], v[212:215], v[94:97]
	v_mfma_f32_16x16x32_bf16 v[90:93], v[162:165], v[212:215], v[90:93]
	v_mfma_f32_16x16x32_bf16 v[78:81], v[154:157], v[220:223], v[78:81]
	v_mfma_f32_16x16x32_bf16 v[74:77], v[162:165], v[220:223], v[74:77]
	s_setprio 0
	s_setprio 1
	v_mfma_f32_16x16x32_bf16 v[118:121], v[166:169], v[182:185], v[118:121]
	v_mfma_f32_16x16x32_bf16 v[114:117], v[174:177], v[182:185], v[114:117]
	v_mfma_f32_16x16x32_bf16 v[102:105], v[166:169], v[190:193], v[102:105]
	v_mfma_f32_16x16x32_bf16 v[98:101], v[174:177], v[190:193], v[98:101]
	v_mfma_f32_16x16x32_bf16 v[86:89], v[166:169], v[198:201], v[86:89]
	v_mfma_f32_16x16x32_bf16 v[82:85], v[174:177], v[198:201], v[82:85]
	v_mfma_f32_16x16x32_bf16 v[70:73], v[166:169], v[216:219], v[70:73]
	v_mfma_f32_16x16x32_bf16 v[66:69], v[174:177], v[216:219], v[66:69]
	v_mfma_f32_16x16x32_bf16 v[118:121], v[170:173], v[186:189], v[118:121]
	v_mfma_f32_16x16x32_bf16 v[114:117], v[178:181], v[186:189], v[114:117]
	v_mfma_f32_16x16x32_bf16 v[102:105], v[170:173], v[194:197], v[102:105]
	v_mfma_f32_16x16x32_bf16 v[98:101], v[178:181], v[194:197], v[98:101]
	v_mfma_f32_16x16x32_bf16 v[86:89], v[170:173], v[212:215], v[86:89]
	v_mfma_f32_16x16x32_bf16 v[82:85], v[178:181], v[212:215], v[82:85]
	v_mfma_f32_16x16x32_bf16 v[70:73], v[170:173], v[220:223], v[70:73]
	v_mfma_f32_16x16x32_bf16 v[66:69], v[178:181], v[220:223], v[66:69]
	s_setprio 0
	s_barrier
	s_add_i32 s30, s30, s40
	v_lshl_add_u64 v[202:203], s[4:5], 0, v[136:137]
	s_mov_b32 m0, s30
	ds_read_b128 v[182:185], v143 offset:16384
	ds_read_b128 v[186:189], v143 offset:17408
	ds_read_b128 v[190:193], v143 offset:18432
	ds_read_b128 v[194:197], v143 offset:19456
	ds_read_b128 v[198:201], v143 offset:20480
	ds_read_b128 v[212:215], v143 offset:21504
	ds_read_b128 v[216:219], v143 offset:22528
	ds_read_b128 v[220:223], v143 offset:23552
	global_load_lds_dwordx4 v[202:203], off
	s_add_i32 m0, s30, 0x2000
	s_add_u32 s30, s4, 0x20000
	v_lshl_add_u64 v[224:225], s[4:5], 0, v[132:133]
	s_addc_u32 s31, s5, 0
	s_add_i32 s34, s34, s40
	global_load_lds_dwordx4 v[224:225], off
	v_lshl_add_u64 v[226:227], s[30:31], 0, v[136:137]
	s_mov_b32 m0, s34
	v_lshl_add_u64 v[228:229], s[6:7], 0, v[134:135]
	global_load_lds_dwordx4 v[226:227], off
	v_lshl_add_u64 v[226:227], s[30:31], 0, v[132:133]
	s_add_i32 m0, s34, 0x2000
	s_nop 0
	global_load_lds_dwordx4 v[226:227], off
	v_lshl_add_u64 v[226:227], s[6:7], 0, v[138:139]
	s_mov_b32 m0, s41
	s_nop 0
	global_load_lds_dwordx4 v[226:227], off
	s_mov_b32 m0, s42
	s_nop 0
	global_load_lds_dwordx4 v[228:229], off
	s_waitcnt vmcnt(8)
	s_waitcnt lgkmcnt(0)
	s_barrier
; #define PG8_STAGE(bufoff, gbase, voff) do { _Pragma("unroll") for (int _i = 0; _i < 2; ++_i) \
;         __builtin_amdgcn_global_load_lds((const unsigned*)((const char*)(gbase) + (voff)[_i]), (LAS unsigned*)(lds + (bufoff) + ldsw + _i * 8192), 16, 0, 0); } while (0)
; #define PG8_LDA(dst, b, h) do { _Pragma("unroll") for (int m = 0; m < 4; ++m) _Pragma("unroll") for (int k = 0; k < 2; ++k) dst[m][k] = *(const LAS bf16x8*)(lds + PG8_SA(b, h) + aoff + m * 2048 + k * 1024); } while (0)
; #define PG8_LDB(dst, b, h) do { _Pragma("unroll") for (int n = 0; n < 2; ++n) _Pragma("unroll") for (int k = 0; k < 2; ++k) dst[n][k] = *(const LAS bf16x8*)(lds + PG8_SB(b, h) + boff + n * 2048 + k * 1024); } while (0)
; #define PG8_MMA(ai, bj, At, Bt) do { __builtin_amdgcn_s_setprio(1); _Pragma("unroll") for (int m = 0; m < 4; ++m) _Pragma("unroll") for (int n = 0; n < 2; ++n) _Pragma("unroll") for (int k = 0; k < 2; ++k) \
;         acc[ai][bj][m][n] = mma16<I8>(Bt[n][k], At[m][k], acc[ai][bj][m][n]); __builtin_amdgcn_s_setprio(0); } while (0)
; #define PG8_WAIT_V(n) asm volatile("s_waitcnt vmcnt(" #n ")" ::: "memory")
; #define PG8_WAIT_L(n) asm volatile("s_waitcnt lgkmcnt(" #n ")" ::: "memory")
; #define PG8_BAR __builtin_amdgcn_s_barrier()
; #define PG8_SCHED __builtin_amdgcn_sched_barrier(0)
; template <class Epi, class Sched, bool I8 = false>
; __device__ __forceinline__ void gemm_phase(LAS unsigned char* lds, const Gemm g, const Sched& S, const Epi& E) {
;     ...
;             PG8_WAIT_V(8); PG8_WAIT_L(0); PG8_BAR; PG8_MMA(1, 0, At, B0); PG8_MMA(1, 1, At, B1); PG8_BAR; PG8_SCHED;
;             PG8_LDB(B0, 1, 0); PG8_LDB(B1, 1, 1); PG8_SCHED; PG8_LDA(At, 1, 0); PG8_STAGE(PG8_SA(0, 1), a2 + hstepA, voffA);
;             PG8_WAIT_V(8); PG8_WAIT_L(0); PG8_BAR; PG8_MMA(0, 0, At, B0); PG8_MMA(0, 1, At, B1); PG8_BAR; PG8_SCHED;
	s_setprio 1
	v_mfma_f32_16x16x32_bf16 v[62:65], v[150:153], v[182:185], v[62:65]
	v_mfma_f32_16x16x32_bf16 v[58:61], v[158:161], v[182:185], v[58:61]
	v_mfma_f32_16x16x32_bf16 v[46:49], v[150:153], v[190:193], v[46:49]
	v_mfma_f32_16x16x32_bf16 v[42:45], v[158:161], v[190:193], v[42:45]
	v_mfma_f32_16x16x32_bf16 v[30:33], v[150:153], v[198:201], v[30:33]
	v_mfma_f32_16x16x32_bf16 v[26:29], v[158:161], v[198:201], v[26:29]
	v_mfma_f32_16x16x32_bf16 v[14:17], v[150:153], v[216:219], v[14:17]
	v_mfma_f32_16x16x32_bf16 v[10:13], v[158:161], v[216:219], v[10:13]
	v_mfma_f32_16x16x32_bf16 v[62:65], v[154:157], v[186:189], v[62:65]
	v_mfma_f32_16x16x32_bf16 v[58:61], v[162:165], v[186:189], v[58:61]
	v_mfma_f32_16x16x32_bf16 v[46:49], v[154:157], v[194:197], v[46:49]
	v_mfma_f32_16x16x32_bf16 v[42:45], v[162:165], v[194:197], v[42:45]
	v_mfma_f32_16x16x32_bf16 v[30:33], v[154:157], v[212:215], v[30:33]
	v_mfma_f32_16x16x32_bf16 v[26:29], v[162:165], v[212:215], v[26:29]
	v_mfma_f32_16x16x32_bf16 v[14:17], v[154:157], v[220:223], v[14:17]
	v_mfma_f32_16x16x32_bf16 v[10:13], v[162:165], v[220:223], v[10:13]
	s_setprio 0
	s_setprio 1
	v_mfma_f32_16x16x32_bf16 v[54:57], v[166:169], v[182:185], v[54:57]
	v_mfma_f32_16x16x32_bf16 v[50:53], v[174:177], v[182:185], v[50:53]
	v_mfma_f32_16x16x32_bf16 v[38:41], v[166:169], v[190:193], v[38:41]
	v_mfma_f32_16x16x32_bf16 v[34:37], v[174:177], v[190:193], v[34:37]
	v_mfma_f32_16x16x32_bf16 v[22:25], v[166:169], v[198:201], v[22:25]
	v_mfma_f32_16x16x32_bf16 v[18:21], v[174:177], v[198:201], v[18:21]
	v_mfma_f32_16x16x32_bf16 v[6:9], v[166:169], v[216:219], v[6:9]
	v_mfma_f32_16x16x32_bf16 v[2:5], v[174:177], v[216:219], v[2:5]
	v_mfma_f32_16x16x32_bf16 v[54:57], v[170:173], v[186:189], v[54:57]
	v_mfma_f32_16x16x32_bf16 v[50:53], v[178:181], v[186:189], v[50:53]
	v_mfma_f32_16x16x32_bf16 v[38:41], v[170:173], v[194:197], v[38:41]
	v_mfma_f32_16x16x32_bf16 v[34:37], v[178:181], v[194:197], v[34:37]
	v_mfma_f32_16x16x32_bf16 v[22:25], v[170:173], v[212:215], v[22:25]
	v_mfma_f32_16x16x32_bf16 v[18:21], v[178:181], v[212:215], v[18:21]
	v_mfma_f32_16x16x32_bf16 v[6:9], v[170:173], v[220:223], v[6:9]
	v_mfma_f32_16x16x32_bf16 v[2:5], v[178:181], v[220:223], v[2:5]
	s_setprio 0
	s_barrier
	s_add_i32 s30, 0, 0x18000
	v_add_u32_e32 v130, s30, v141
	s_add_i32 s31, 0, 0x1c000
	ds_read_b128 v[150:153], v130
	ds_read_b128 v[154:157], v130 offset:1024
	ds_read_b128 v[158:161], v130 offset:2048
	ds_read_b128 v[162:165], v130 offset:3072
	v_add_u32_e32 v130, s31, v141
	ds_read_b128 v[166:169], v130
	ds_read_b128 v[170:173], v130 offset:1024
	ds_read_b128 v[174:177], v130 offset:2048
	ds_read_b128 v[178:181], v130 offset:3072
	s_add_u32 s6, s6, 0x80000
	s_addc_u32 s7, s7, 0
	s_mov_b32 m0, s43
	v_lshl_add_u64 v[230:231], s[6:7], 0, v[138:139]
	ds_read_b128 v[182:185], v143 offset:32768
	ds_read_b128 v[186:189], v143 offset:33792
	ds_read_b128 v[190:193], v143 offset:34816
	ds_read_b128 v[194:197], v143 offset:35840
	ds_read_b128 v[198:201], v143 offset:36864
	ds_read_b128 v[212:215], v143 offset:37888
	ds_read_b128 v[216:219], v143 offset:38912
	ds_read_b128 v[220:223], v143 offset:39936
	global_load_lds_dwordx4 v[230:231], off
	v_lshl_add_u64 v[230:231], s[6:7], 0, v[134:135]
	s_mov_b32 m0, s44
	s_nop 0
	global_load_lds_dwordx4 v[230:231], off
	s_waitcnt vmcnt(8)
	s_waitcnt lgkmcnt(0)
	s_barrier
	s_setprio 1
	v_mfma_f32_16x16x32_bf16 v[126:129], v[150:153], v[182:185], v[126:129]
	v_mfma_f32_16x16x32_bf16 v[122:125], v[158:161], v[182:185], v[122:125]
	v_mfma_f32_16x16x32_bf16 v[110:113], v[150:153], v[190:193], v[110:113]
	v_mfma_f32_16x16x32_bf16 v[106:109], v[158:161], v[190:193], v[106:109]
	v_mfma_f32_16x16x32_bf16 v[94:97], v[150:153], v[198:201], v[94:97]
	v_mfma_f32_16x16x32_bf16 v[90:93], v[158:161], v[198:201], v[90:93]
	v_mfma_f32_16x16x32_bf16 v[78:81], v[150:153], v[216:219], v[78:81]
	v_mfma_f32_16x16x32_bf16 v[74:77], v[158:161], v[216:219], v[74:77]
	v_mfma_f32_16x16x32_bf16 v[126:129], v[154:157], v[186:189], v[126:129]
	v_mfma_f32_16x16x32_bf16 v[122:125], v[162:165], v[186:189], v[122:125]
	v_mfma_f32_16x16x32_bf16 v[110:113], v[154:157], v[194:197], v[110:113]
	v_mfma_f32_16x16x32_bf16 v[106:109], v[162:165], v[194:197], v[106:109]
	v_mfma_f32_16x16x32_bf16 v[94:97], v[154:157], v[212:215], v[94:97]
	v_mfma_f32_16x16x32_bf16 v[90:93], v[162:165], v[212:215], v[90:93]
	v_mfma_f32_16x16x32_bf16 v[78:81], v[154:157], v[220:223], v[78:81]
	v_mfma_f32_16x16x32_bf16 v[74:77], v[162:165], v[220:223], v[74:77]
	s_setprio 0
	s_setprio 1
	v_mfma_f32_16x16x32_bf16 v[118:121], v[166:169], v[182:185], v[118:121]
	v_mfma_f32_16x16x32_bf16 v[114:117], v[174:177], v[182:185], v[114:117]
	v_mfma_f32_16x16x32_bf16 v[102:105], v[166:169], v[190:193], v[102:105]
	v_mfma_f32_16x16x32_bf16 v[98:101], v[174:177], v[190:193], v[98:101]
	v_mfma_f32_16x16x32_bf16 v[86:89], v[166:169], v[198:201], v[86:89]
	v_mfma_f32_16x16x32_bf16 v[82:85], v[174:177], v[198:201], v[82:85]
	v_mfma_f32_16x16x32_bf16 v[70:73], v[166:169], v[216:219], v[70:73]
	v_mfma_f32_16x16x32_bf16 v[66:69], v[174:177], v[216:219], v[66:69]
	v_mfma_f32_16x16x32_bf16 v[118:121], v[170:173], v[186:189], v[118:121]
	v_mfma_f32_16x16x32_bf16 v[114:117], v[178:181], v[186:189], v[114:117]
	v_mfma_f32_16x16x32_bf16 v[102:105], v[170:173], v[194:197], v[102:105]
	v_mfma_f32_16x16x32_bf16 v[98:101], v[178:181], v[194:197], v[98:101]
	v_mfma_f32_16x16x32_bf16 v[86:89], v[170:173], v[212:215], v[86:89]
	v_mfma_f32_16x16x32_bf16 v[82:85], v[178:181], v[212:215], v[82:85]
	v_mfma_f32_16x16x32_bf16 v[70:73], v[170:173], v[220:223], v[70:73]
	v_mfma_f32_16x16x32_bf16 v[66:69], v[178:181], v[220:223], v[66:69]
	s_setprio 0
	s_barrier
; #define PG8_STAGE(bufoff, gbase, voff) do { _Pragma("unroll") for (int _i = 0; _i < 2; ++_i) \
;         __builtin_amdgcn_global_load_lds((const unsigned*)((const char*)(gbase) + (voff)[_i]), (LAS unsigned*)(lds + (bufoff) + ldsw + _i * 8192), 16, 0, 0); } while (0)
; #define PG8_LDA(dst, b, h) do { _Pragma("unroll") for (int m = 0; m < 4; ++m) _Pragma("unroll") for (int k = 0; k < 2; ++k) dst[m][k] = *(const LAS bf16x8*)(lds + PG8_SA(b, h) + aoff + m * 2048 + k * 1024); } while (0)
; #define PG8_MMA(ai, bj, At, Bt) do { __builtin_amdgcn_s_setprio(1); _Pragma("unroll") for (int m = 0; m < 4; ++m) _Pragma("unroll") for (int n = 0; n < 2; ++n) _Pragma("unroll") for (int k = 0; k < 2; ++k) \
;         acc[ai][bj][m][n] = mma16<I8>(Bt[n][k], At[m][k], acc[ai][bj][m][n]); __builtin_amdgcn_s_setprio(0); } while (0)
; #define PG8_WAIT_V(n) asm volatile("s_waitcnt vmcnt(" #n ")" ::: "memory")
; #define PG8_WAIT_L(n) asm volatile("s_waitcnt lgkmcnt(" #n ")" ::: "memory")
; #define PG8_BAR __builtin_amdgcn_s_barrier()
; #define PG8_SCHED __builtin_amdgcn_sched_barrier(0)
; template <class Epi, class Sched, bool I8 = false>
; __device__ __forceinline__ void gemm_phase(LAS unsigned char* lds, const Gemm g, const Sched& S, const Epi& E) {
;     ...
;         for (int t = 0; t < nt; t += 2) {
;             const bool last = (t == nt - 2);
;     ...
;             PG8_LDA(At, 1, 1); PG8_STAGE(PG8_SB(1, 0), b3, voffB); PG8_STAGE(PG8_SB(1, 1), b3 + hstepB, voffB); PG8_STAGE(PG8_SA(1, 0), a3, voffA);
;             PG8_WAIT_V(8); PG8_WAIT_L(0); PG8_BAR; PG8_MMA(1, 0, At, B0); PG8_MMA(1, 1, At, B1); PG8_BAR; PG8_SCHED;
	s_add_i32 s6, s30, s40
	v_lshl_add_u64 v[202:203], v[202:203], 0, s[12:13]
	s_mov_b32 m0, s6
	ds_read_b128 v[182:185], v143 offset:49152
	ds_read_b128 v[186:189], v143 offset:50176
	ds_read_b128 v[190:193], v143 offset:51200
	ds_read_b128 v[194:197], v143 offset:52224
	ds_read_b128 v[198:201], v143 offset:53248
	ds_read_b128 v[212:215], v143 offset:54272
	ds_read_b128 v[216:219], v143 offset:55296
	ds_read_b128 v[220:223], v143 offset:56320
	global_load_lds_dwordx4 v[202:203], off
	s_add_i32 m0, s6, 0x2000
	s_add_u32 s4, s4, 0x20080
	v_lshl_add_u64 v[202:203], v[224:225], 0, s[12:13]
	s_addc_u32 s5, s5, 0
	s_add_i32 s6, s31, s40
	global_load_lds_dwordx4 v[202:203], off
	v_lshl_add_u64 v[202:203], s[4:5], 0, v[136:137]
	s_mov_b32 m0, s6
	s_nop 0
	global_load_lds_dwordx4 v[202:203], off
	v_lshl_add_u64 v[202:203], s[4:5], 0, v[132:133]
	s_add_i32 m0, s6, 0x2000
	s_nop 0
	global_load_lds_dwordx4 v[202:203], off
	v_lshl_add_u64 v[202:203], v[226:227], 0, s[12:13]
	s_mov_b32 m0, s80
	s_nop 0
	global_load_lds_dwordx4 v[202:203], off
	v_lshl_add_u64 v[202:203], v[228:229], 0, s[12:13]
	s_mov_b32 m0, s82
	s_nop 0
	global_load_lds_dwordx4 v[202:203], off
	s_waitcnt vmcnt(8)
	s_waitcnt lgkmcnt(0)
	s_barrier
	s_setprio 1
	v_mfma_f32_16x16x32_bf16 v[62:65], v[150:153], v[182:185], v[62:65]
	v_mfma_f32_16x16x32_bf16 v[58:61], v[158:161], v[182:185], v[58:61]
	v_mfma_f32_16x16x32_bf16 v[46:49], v[150:153], v[190:193], v[46:49]
	v_mfma_f32_16x16x32_bf16 v[42:45], v[158:161], v[190:193], v[42:45]
	v_mfma_f32_16x16x32_bf16 v[30:33], v[150:153], v[198:201], v[30:33]
	v_mfma_f32_16x16x32_bf16 v[26:29], v[158:161], v[198:201], v[26:29]
	v_mfma_f32_16x16x32_bf16 v[14:17], v[150:153], v[216:219], v[14:17]
	v_mfma_f32_16x16x32_bf16 v[10:13], v[158:161], v[216:219], v[10:13]
	v_mfma_f32_16x16x32_bf16 v[62:65], v[154:157], v[186:189], v[62:65]
	v_mfma_f32_16x16x32_bf16 v[58:61], v[162:165], v[186:189], v[58:61]
	v_mfma_f32_16x16x32_bf16 v[46:49], v[154:157], v[194:197], v[46:49]
	v_mfma_f32_16x16x32_bf16 v[42:45], v[162:165], v[194:197], v[42:45]
	v_mfma_f32_16x16x32_bf16 v[30:33], v[154:157], v[212:215], v[30:33]
	v_mfma_f32_16x16x32_bf16 v[26:29], v[162:165], v[212:215], v[26:29]
	v_mfma_f32_16x16x32_bf16 v[14:17], v[154:157], v[220:223], v[14:17]
	v_mfma_f32_16x16x32_bf16 v[10:13], v[162:165], v[220:223], v[10:13]
	s_setprio 0
	s_setprio 1
	v_mfma_f32_16x16x32_bf16 v[54:57], v[166:169], v[182:185], v[54:57]
	v_mfma_f32_16x16x32_bf16 v[50:53], v[174:177], v[182:185], v[50:53]
	v_mfma_f32_16x16x32_bf16 v[38:41], v[166:169], v[190:193], v[38:41]
	v_mfma_f32_16x16x32_bf16 v[34:37], v[174:177], v[190:193], v[34:37]
	v_mfma_f32_16x16x32_bf16 v[22:25], v[166:169], v[198:201], v[22:25]
	v_mfma_f32_16x16x32_bf16 v[18:21], v[174:177], v[198:201], v[18:21]
	v_mfma_f32_16x16x32_bf16 v[6:9], v[166:169], v[216:219], v[6:9]
	v_mfma_f32_16x16x32_bf16 v[2:5], v[174:177], v[216:219], v[2:5]
	v_mfma_f32_16x16x32_bf16 v[54:57], v[170:173], v[186:189], v[54:57]
	v_mfma_f32_16x16x32_bf16 v[50:53], v[178:181], v[186:189], v[50:53]
	v_mfma_f32_16x16x32_bf16 v[38:41], v[170:173], v[194:197], v[38:41]
	v_mfma_f32_16x16x32_bf16 v[34:37], v[178:181], v[194:197], v[34:37]
	v_mfma_f32_16x16x32_bf16 v[22:25], v[170:173], v[212:215], v[22:25]
	v_mfma_f32_16x16x32_bf16 v[18:21], v[178:181], v[212:215], v[18:21]
	v_mfma_f32_16x16x32_bf16 v[6:9], v[170:173], v[220:223], v[6:9]
	v_mfma_f32_16x16x32_bf16 v[2:5], v[178:181], v[220:223], v[2:5]
	s_setprio 0
	s_barrier
	s_add_i32 s29, s29, 2
	s_add_u32 s0, s0, 0x100
	s_addc_u32 s1, s1, 0
	s_add_u32 s24, s24, 0x100
	s_addc_u32 s25, s25, 0
	s_cmp_gt_u32 s29, 29
	s_cbranch_scc0 .LBB0_356
	s_and_b64 vcc, exec, s[8:9]
	s_cbranch_vccz .LBB0_359
	s_barrier

;     __device__ __forceinline__ bool next(int i, Unit& u) const { u.seg = 0; u.ks = -1; u.nt = ntk; u.koff = 0; return unit(i, u); }
;     __device__ __forceinline__ bool next(int i, Unit& u) const { const int t = i / 3; u.seg = i - 3 * t; u.ks = -1; u.nt = ntk; u.koff = 0; return unit(t, u); }
;     __device__ __forceinline__ bool next(int i, Unit& u) const { if (i > 0 || c < 80 || c >= 144) return false; const int k = c - 80; u.pm = k & 1; u.pn = k >> 1; u.seg = 0; u.ks = -1; u.nt = DM / BK; u.koff = 0; return true; }
; #define PG8_STAGE(bufoff, gbase, voff) do { _Pragma("unroll") for (int _i = 0; _i < 2; ++_i) \
;         __builtin_amdgcn_global_load_lds((const unsigned*)((const char*)(gbase) + (voff)[_i]), (LAS unsigned*)(lds + (bufoff) + ldsw + _i * 8192), 16, 0, 0); } while (0)
; #define PG8_LDA(dst, b, h) do { _Pragma("unroll") for (int m = 0; m < 4; ++m) _Pragma("unroll") for (int k = 0; k < 2; ++k) dst[m][k] = *(const LAS bf16x8*)(lds + PG8_SA(b, h) + aoff + m * 2048 + k * 1024); } while (0)
; template <class Epi, class Sched, bool I8 = false>
; __device__ __forceinline__ void gemm_phase(LAS unsigned char* lds, const Gemm g, const Sched& S, const Epi& E) {
;     ...
;         const bool has_next = S.next(ui + 1, nxt);
;         const char* nA = has_next ? g.A + (size_t)nxt.seg * g.segA + (size_t)nxt.pm * tstepA + nxt.koff : cA; const char* nB = has_next ? g.Bt + (size_t)nxt.seg * g.segB + (size_t)nxt.pn * tstepB + nxt.koff : cB;
;         const int nt = cur.nt;
;         for (int t = 0; t < nt; t += 2) {
;             const bool last = (t == nt - 2);
;             const char* a1 = cA + (size_t)(t + 1) * kstep;
;             const char* a2 = last ? nA : cA + (size_t)(t + 2) * kstep; const char* b2 = last ? nB : cB + (size_t)(t + 2) * kstep;
;             const char* a3 = a2 + kstep; const char* b3 = b2 + kstep;
;             if (PG8_SP2) {
;             PG8_LDB(B0, 0, 0); PG8_LDB(B1, 0, 1); PG8_SCHED; PG8_LDA(At, 0, 0); PG8_STAGE(PG8_SA(1, 1), a1 + hstepA, voffA);
;             PG8_WAIT_V(8); PG8_WAIT_L(0); PG8_BAR; PG8_MMA(0, 0, At, B0); PG8_MMA(0, 1, At, B1); PG8_BAR; PG8_SCHED;
;             PG8_LDA(At, 0, 1); PG8_STAGE(PG8_SB(0, 0), b2, voffB); PG8_STAGE(PG8_SB(0, 1), b2 + hstepB, voffB); PG8_STAGE(PG8_SA(0, 0), a2, voffA);
;             PG8_WAIT_V(8); PG8_WAIT_L(0); PG8_BAR; PG8_MMA(1, 0, At, B0); PG8_MMA(1, 1, At, B1); PG8_BAR; PG8_SCHED;
.LBB0_539:
	s_add_u32 s6, s0, 0xfffc0080
	s_addc_u32 s7, s1, -1
	s_add_i32 s31, 0, 0x10000
	s_cmp_eq_u32 s30, 12
	s_cselect_b32 s27, s14, s7
	s_cselect_b32 s26, s21, s6
	v_add_u32_e32 v149, s31, v175
	s_cselect_b32 s7, s22, s25
	s_cselect_b32 s6, s23, s24
	s_add_i32 s38, 0, 0x14000
	ds_read_b128 v[152:155], v149
	ds_read_b128 v[156:159], v149 offset:1024
	ds_read_b128 v[160:163], v149 offset:2048
	ds_read_b128 v[164:167], v149 offset:3072
	v_add_u32_e32 v149, s38, v175
	ds_read_b128 v[168:171], v149
	ds_read_b128 v[180:183], v149 offset:1024
	ds_read_b128 v[184:187], v149 offset:2048
	ds_read_b128 v[188:191], v149 offset:3072
	v_lshl_add_u64 v[172:173], s[0:1], 0, v[144:145]
	s_add_i32 m0, s43, 0xc000
	ds_read_b128 v[192:195], v179
	ds_read_b128 v[196:199], v179 offset:1024
	ds_read_b128 v[200:203], v179 offset:2048
	ds_read_b128 v[212:215], v179 offset:3072
	ds_read_b128 v[216:219], v179 offset:4096
	ds_read_b128 v[220:223], v179 offset:5120
	ds_read_b128 v[224:227], v179 offset:6144
	ds_read_b128 v[228:231], v179 offset:7168
	global_load_lds_dwordx4 v[172:173], off
	v_lshl_add_u64 v[172:173], s[0:1], 0, v[146:147]
	s_add_i32 m0, s43, 0xe000
	s_nop 0
	global_load_lds_dwordx4 v[172:173], off
	s_waitcnt vmcnt(8)
	s_waitcnt lgkmcnt(0)
	s_barrier
	s_setprio 1
	v_mfma_i32_16x16x64_i8 v[126:129], v[152:155], v[192:195], v[126:129]
	v_mfma_i32_16x16x64_i8 v[122:125], v[160:163], v[192:195], v[122:125]
	v_mfma_i32_16x16x64_i8 v[118:121], v[152:155], v[200:203], v[118:121]
	v_mfma_i32_16x16x64_i8 v[114:117], v[160:163], v[200:203], v[114:117]
	v_mfma_i32_16x16x64_i8 v[102:105], v[152:155], v[216:219], v[102:105]
	v_mfma_i32_16x16x64_i8 v[98:101], v[160:163], v[216:219], v[98:101]
	v_mfma_i32_16x16x64_i8 v[86:89], v[152:155], v[224:227], v[86:89]
	v_mfma_i32_16x16x64_i8 v[82:85], v[160:163], v[224:227], v[82:85]
	v_mfma_i32_16x16x64_i8 v[126:129], v[156:159], v[196:199], v[126:129]
	v_mfma_i32_16x16x64_i8 v[122:125], v[164:167], v[196:199], v[122:125]
	v_mfma_i32_16x16x64_i8 v[118:121], v[156:159], v[212:215], v[118:121]
	v_mfma_i32_16x16x64_i8 v[114:117], v[164:167], v[212:215], v[114:117]
	v_mfma_i32_16x16x64_i8 v[102:105], v[156:159], v[220:223], v[102:105]
	v_mfma_i32_16x16x64_i8 v[98:101], v[164:167], v[220:223], v[98:101]
	v_mfma_i32_16x16x64_i8 v[86:89], v[156:159], v[228:231], v[86:89]
	v_mfma_i32_16x16x64_i8 v[82:85], v[164:167], v[228:231], v[82:85]
	s_setprio 0
	s_setprio 1
	v_mfma_i32_16x16x64_i8 v[110:113], v[168:171], v[192:195], v[110:113]
	v_mfma_i32_16x16x64_i8 v[106:109], v[184:187], v[192:195], v[106:109]
	v_mfma_i32_16x16x64_i8 v[94:97], v[168:171], v[200:203], v[94:97]
	v_mfma_i32_16x16x64_i8 v[90:93], v[184:187], v[200:203], v[90:93]
	v_mfma_i32_16x16x64_i8 v[78:81], v[168:171], v[216:219], v[78:81]
	v_mfma_i32_16x16x64_i8 v[74:77], v[184:187], v[216:219], v[74:77]
	v_mfma_i32_16x16x64_i8 v[70:73], v[168:171], v[224:227], v[70:73]
	v_mfma_i32_16x16x64_i8 v[66:69], v[184:187], v[224:227], v[66:69]
	v_mfma_i32_16x16x64_i8 v[110:113], v[180:183], v[196:199], v[110:113]
	v_mfma_i32_16x16x64_i8 v[106:109], v[188:191], v[196:199], v[106:109]
	v_mfma_i32_16x16x64_i8 v[94:97], v[180:183], v[212:215], v[94:97]
	v_mfma_i32_16x16x64_i8 v[90:93], v[188:191], v[212:215], v[90:93]
	v_mfma_i32_16x16x64_i8 v[78:81], v[180:183], v[220:223], v[78:81]
	v_mfma_i32_16x16x64_i8 v[74:77], v[188:191], v[220:223], v[74:77]
	v_mfma_i32_16x16x64_i8 v[70:73], v[180:183], v[228:231], v[70:73]
	v_mfma_i32_16x16x64_i8 v[66:69], v[188:191], v[228:231], v[66:69]
	s_setprio 0
	s_barrier
	s_add_i32 s31, s31, s42
	v_lshl_add_u64 v[172:173], s[6:7], 0, v[136:137]
	s_mov_b32 m0, s31
	ds_read_b128 v[192:195], v179 offset:16384
	ds_read_b128 v[196:199], v179 offset:17408
	ds_read_b128 v[200:203], v179 offset:18432
	ds_read_b128 v[212:215], v179 offset:19456
	ds_read_b128 v[216:219], v179 offset:20480
	ds_read_b128 v[220:223], v179 offset:21504
	ds_read_b128 v[224:227], v179 offset:22528
	ds_read_b128 v[228:231], v179 offset:23552
	global_load_lds_dwordx4 v[172:173], off
	s_add_i32 m0, s31, 0x2000
	s_add_u32 s34, s6, 0x10000
	v_lshl_add_u64 v[232:233], s[6:7], 0, v[132:133]
	s_addc_u32 s35, s7, 0
	s_add_i32 s31, s38, s42
	global_load_lds_dwordx4 v[232:233], off
	v_lshl_add_u64 v[234:235], s[34:35], 0, v[136:137]
	s_mov_b32 m0, s31
	v_lshl_add_u64 v[236:237], s[26:27], 0, v[134:135]
	global_load_lds_dwordx4 v[234:235], off
	v_lshl_add_u64 v[234:235], s[34:35], 0, v[132:133]
	s_add_i32 m0, s31, 0x2000
	s_nop 0
	global_load_lds_dwordx4 v[234:235], off
	v_lshl_add_u64 v[234:235], s[26:27], 0, v[138:139]
	s_mov_b32 m0, s43
	s_nop 0
	global_load_lds_dwordx4 v[234:235], off
	s_mov_b32 m0, s44
	s_nop 0
	global_load_lds_dwordx4 v[236:237], off
	s_waitcnt vmcnt(8)
	s_waitcnt lgkmcnt(0)
	s_barrier
; #define PG8_STAGE(bufoff, gbase, voff) do { _Pragma("unroll") for (int _i = 0; _i < 2; ++_i) \
;         __builtin_amdgcn_global_load_lds((const unsigned*)((const char*)(gbase) + (voff)[_i]), (LAS unsigned*)(lds + (bufoff) + ldsw + _i * 8192), 16, 0, 0); } while (0)
; #define PG8_LDA(dst, b, h) do { _Pragma("unroll") for (int m = 0; m < 4; ++m) _Pragma("unroll") for (int k = 0; k < 2; ++k) dst[m][k] = *(const LAS bf16x8*)(lds + PG8_SA(b, h) + aoff + m * 2048 + k * 1024); } while (0)
; #define PG8_LDB(dst, b, h) do { _Pragma("unroll") for (int n = 0; n < 2; ++n) _Pragma("unroll") for (int k = 0; k < 2; ++k) dst[n][k] = *(const LAS bf16x8*)(lds + PG8_SB(b, h) + boff + n * 2048 + k * 1024); } while (0)
; #define PG8_MMA(ai, bj, At, Bt) do { __builtin_amdgcn_s_setprio(1); _Pragma("unroll") for (int m = 0; m < 4; ++m) _Pragma("unroll") for (int n = 0; n < 2; ++n) _Pragma("unroll") for (int k = 0; k < 2; ++k) \
;         acc[ai][bj][m][n] = mma16<I8>(Bt[n][k], At[m][k], acc[ai][bj][m][n]); __builtin_amdgcn_s_setprio(0); } while (0)
; #define PG8_WAIT_V(n) asm volatile("s_waitcnt vmcnt(" #n ")" ::: "memory")
; #define PG8_WAIT_L(n) asm volatile("s_waitcnt lgkmcnt(" #n ")" ::: "memory")
; #define PG8_BAR __builtin_amdgcn_s_barrier()
; #define PG8_SCHED __builtin_amdgcn_sched_barrier(0)
; template <class Epi, class Sched, bool I8 = false>
; __device__ __forceinline__ void gemm_phase(LAS unsigned char* lds, const Gemm g, const Sched& S, const Epi& E) {
;     ...
;             PG8_WAIT_V(8); PG8_WAIT_L(0); PG8_BAR; PG8_MMA(1, 0, At, B0); PG8_MMA(1, 1, At, B1); PG8_BAR; PG8_SCHED;
;             PG8_LDB(B0, 1, 0); PG8_LDB(B1, 1, 1); PG8_SCHED; PG8_LDA(At, 1, 0); PG8_STAGE(PG8_SA(0, 1), a2 + hstepA, voffA);
;             PG8_WAIT_V(8); PG8_WAIT_L(0); PG8_BAR; PG8_MMA(0, 0, At, B0); PG8_MMA(0, 1, At, B1); PG8_BAR; PG8_SCHED;
	s_setprio 1
	v_mfma_i32_16x16x64_i8 v[62:65], v[152:155], v[192:195], v[62:65]
	v_mfma_i32_16x16x64_i8 v[58:61], v[160:163], v[192:195], v[58:61]
	v_mfma_i32_16x16x64_i8 v[54:57], v[152:155], v[200:203], v[54:57]
	v_mfma_i32_16x16x64_i8 v[50:53], v[160:163], v[200:203], v[50:53]
	v_mfma_i32_16x16x64_i8 v[30:33], v[152:155], v[216:219], v[30:33]
	v_mfma_i32_16x16x64_i8 v[26:29], v[160:163], v[216:219], v[26:29]
	v_mfma_i32_16x16x64_i8 v[14:17], v[152:155], v[224:227], v[14:17]
	v_mfma_i32_16x16x64_i8 v[10:13], v[160:163], v[224:227], v[10:13]
	v_mfma_i32_16x16x64_i8 v[62:65], v[156:159], v[196:199], v[62:65]
	v_mfma_i32_16x16x64_i8 v[58:61], v[164:167], v[196:199], v[58:61]
	v_mfma_i32_16x16x64_i8 v[54:57], v[156:159], v[212:215], v[54:57]
	v_mfma_i32_16x16x64_i8 v[50:53], v[164:167], v[212:215], v[50:53]
	v_mfma_i32_16x16x64_i8 v[30:33], v[156:159], v[220:223], v[30:33]
	v_mfma_i32_16x16x64_i8 v[26:29], v[164:167], v[220:223], v[26:29]
	v_mfma_i32_16x16x64_i8 v[14:17], v[156:159], v[228:231], v[14:17]
	v_mfma_i32_16x16x64_i8 v[10:13], v[164:167], v[228:231], v[10:13]
	s_setprio 0
	s_setprio 1
	v_mfma_i32_16x16x64_i8 v[46:49], v[168:171], v[192:195], v[46:49]
	v_mfma_i32_16x16x64_i8 v[42:45], v[184:187], v[192:195], v[42:45]
	v_mfma_i32_16x16x64_i8 v[38:41], v[168:171], v[200:203], v[38:41]
	v_mfma_i32_16x16x64_i8 v[34:37], v[184:187], v[200:203], v[34:37]
	v_mfma_i32_16x16x64_i8 v[22:25], v[168:171], v[216:219], v[22:25]
	v_mfma_i32_16x16x64_i8 v[18:21], v[184:187], v[216:219], v[18:21]
	v_mfma_i32_16x16x64_i8 v[6:9], v[168:171], v[224:227], v[6:9]
	v_mfma_i32_16x16x64_i8 v[2:5], v[184:187], v[224:227], v[2:5]
	v_mfma_i32_16x16x64_i8 v[46:49], v[180:183], v[196:199], v[46:49]
	v_mfma_i32_16x16x64_i8 v[42:45], v[188:191], v[196:199], v[42:45]
	v_mfma_i32_16x16x64_i8 v[38:41], v[180:183], v[212:215], v[38:41]
	v_mfma_i32_16x16x64_i8 v[34:37], v[188:191], v[212:215], v[34:37]
	v_mfma_i32_16x16x64_i8 v[22:25], v[180:183], v[220:223], v[22:25]
	v_mfma_i32_16x16x64_i8 v[18:21], v[188:191], v[220:223], v[18:21]
	v_mfma_i32_16x16x64_i8 v[6:9], v[180:183], v[228:231], v[6:9]
	v_mfma_i32_16x16x64_i8 v[2:5], v[188:191], v[228:231], v[2:5]
	s_setprio 0
	s_barrier
	s_add_i32 s31, 0, 0x18000
	v_add_u32_e32 v149, s31, v175
	s_add_i32 s34, 0, 0x1c000
	ds_read_b128 v[152:155], v149
	ds_read_b128 v[156:159], v149 offset:1024
	ds_read_b128 v[160:163], v149 offset:2048
	ds_read_b128 v[164:167], v149 offset:3072
	v_add_u32_e32 v149, s34, v175
	ds_read_b128 v[168:171], v149
	ds_read_b128 v[180:183], v149 offset:1024
	ds_read_b128 v[184:187], v149 offset:2048
	ds_read_b128 v[188:191], v149 offset:3072
	s_add_u32 s26, s26, 0x40000
	s_addc_u32 s27, s27, 0
	s_mov_b32 m0, s45
	v_lshl_add_u64 v[238:239], s[26:27], 0, v[138:139]
	ds_read_b128 v[192:195], v179 offset:32768
	ds_read_b128 v[196:199], v179 offset:33792
	ds_read_b128 v[200:203], v179 offset:34816
	ds_read_b128 v[212:215], v179 offset:35840
	ds_read_b128 v[216:219], v179 offset:36864
	ds_read_b128 v[220:223], v179 offset:37888
	ds_read_b128 v[224:227], v179 offset:38912
	ds_read_b128 v[228:231], v179 offset:39936
	global_load_lds_dwordx4 v[238:239], off
	v_lshl_add_u64 v[238:239], s[26:27], 0, v[134:135]
	s_mov_b32 m0, s82
	s_nop 0
	global_load_lds_dwordx4 v[238:239], off
	s_waitcnt vmcnt(8)
	s_waitcnt lgkmcnt(0)
	s_barrier
	s_setprio 1
	v_mfma_i32_16x16x64_i8 v[126:129], v[152:155], v[192:195], v[126:129]
	v_mfma_i32_16x16x64_i8 v[122:125], v[160:163], v[192:195], v[122:125]
	v_mfma_i32_16x16x64_i8 v[118:121], v[152:155], v[200:203], v[118:121]
	v_mfma_i32_16x16x64_i8 v[114:117], v[160:163], v[200:203], v[114:117]
	v_mfma_i32_16x16x64_i8 v[102:105], v[152:155], v[216:219], v[102:105]
	v_mfma_i32_16x16x64_i8 v[98:101], v[160:163], v[216:219], v[98:101]
	v_mfma_i32_16x16x64_i8 v[86:89], v[152:155], v[224:227], v[86:89]
	v_mfma_i32_16x16x64_i8 v[82:85], v[160:163], v[224:227], v[82:85]
	v_mfma_i32_16x16x64_i8 v[126:129], v[156:159], v[196:199], v[126:129]
	v_mfma_i32_16x16x64_i8 v[122:125], v[164:167], v[196:199], v[122:125]
	v_mfma_i32_16x16x64_i8 v[118:121], v[156:159], v[212:215], v[118:121]
	v_mfma_i32_16x16x64_i8 v[114:117], v[164:167], v[212:215], v[114:117]
	v_mfma_i32_16x16x64_i8 v[102:105], v[156:159], v[220:223], v[102:105]
	v_mfma_i32_16x16x64_i8 v[98:101], v[164:167], v[220:223], v[98:101]
	v_mfma_i32_16x16x64_i8 v[86:89], v[156:159], v[228:231], v[86:89]
	v_mfma_i32_16x16x64_i8 v[82:85], v[164:167], v[228:231], v[82:85]
	s_setprio 0
	s_setprio 1
	v_mfma_i32_16x16x64_i8 v[110:113], v[168:171], v[192:195], v[110:113]
	v_mfma_i32_16x16x64_i8 v[106:109], v[184:187], v[192:195], v[106:109]
	v_mfma_i32_16x16x64_i8 v[94:97], v[168:171], v[200:203], v[94:97]
	v_mfma_i32_16x16x64_i8 v[90:93], v[184:187], v[200:203], v[90:93]
	v_mfma_i32_16x16x64_i8 v[78:81], v[168:171], v[216:219], v[78:81]
	v_mfma_i32_16x16x64_i8 v[74:77], v[184:187], v[216:219], v[74:77]
	v_mfma_i32_16x16x64_i8 v[70:73], v[168:171], v[224:227], v[70:73]
	v_mfma_i32_16x16x64_i8 v[66:69], v[184:187], v[224:227], v[66:69]
	v_mfma_i32_16x16x64_i8 v[110:113], v[180:183], v[196:199], v[110:113]
	v_mfma_i32_16x16x64_i8 v[106:109], v[188:191], v[196:199], v[106:109]
	v_mfma_i32_16x16x64_i8 v[94:97], v[180:183], v[212:215], v[94:97]
	v_mfma_i32_16x16x64_i8 v[90:93], v[188:191], v[212:215], v[90:93]
	v_mfma_i32_16x16x64_i8 v[78:81], v[180:183], v[220:223], v[78:81]
	v_mfma_i32_16x16x64_i8 v[74:77], v[188:191], v[220:223], v[74:77]
	v_mfma_i32_16x16x64_i8 v[70:73], v[180:183], v[228:231], v[70:73]
	v_mfma_i32_16x16x64_i8 v[66:69], v[188:191], v[228:231], v[66:69]
	s_setprio 0
	s_barrier
; #define PG8_STAGE(bufoff, gbase, voff) do { _Pragma("unroll") for (int _i = 0; _i < 2; ++_i) \
;         __builtin_amdgcn_global_load_lds((const unsigned*)((const char*)(gbase) + (voff)[_i]), (LAS unsigned*)(lds + (bufoff) + ldsw + _i * 8192), 16, 0, 0); } while (0)
; #define PG8_LDA(dst, b, h) do { _Pragma("unroll") for (int m = 0; m < 4; ++m) _Pragma("unroll") for (int k = 0; k < 2; ++k) dst[m][k] = *(const LAS bf16x8*)(lds + PG8_SA(b, h) + aoff + m * 2048 + k * 1024); } while (0)
; #define PG8_MMA(ai, bj, At, Bt) do { __builtin_amdgcn_s_setprio(1); _Pragma("unroll") for (int m = 0; m < 4; ++m) _Pragma("unroll") for (int n = 0; n < 2; ++n) _Pragma("unroll") for (int k = 0; k < 2; ++k) \
;         acc[ai][bj][m][n] = mma16<I8>(Bt[n][k], At[m][k], acc[ai][bj][m][n]); __builtin_amdgcn_s_setprio(0); } while (0)
; #define PG8_WAIT_V(n) asm volatile("s_waitcnt vmcnt(" #n ")" ::: "memory")
; #define PG8_WAIT_L(n) asm volatile("s_waitcnt lgkmcnt(" #n ")" ::: "memory")
; #define PG8_BAR __builtin_amdgcn_s_barrier()
; #define PG8_SCHED __builtin_amdgcn_sched_barrier(0)
; template <class Epi, class Sched, bool I8 = false>
; __device__ __forceinline__ void gemm_phase(LAS unsigned char* lds, const Gemm g, const Sched& S, const Epi& E) {
;     ...
;         for (int t = 0; t < nt; t += 2) {
;             const bool last = (t == nt - 2);
;     ...
;             PG8_LDA(At, 1, 1); PG8_STAGE(PG8_SB(1, 0), b3, voffB); PG8_STAGE(PG8_SB(1, 1), b3 + hstepB, voffB); PG8_STAGE(PG8_SA(1, 0), a3, voffA);
;             PG8_WAIT_V(8); PG8_WAIT_L(0); PG8_BAR; PG8_MMA(1, 0, At, B0); PG8_MMA(1, 1, At, B1); PG8_BAR; PG8_SCHED;
	s_add_i32 s26, s31, s42
	v_lshl_add_u64 v[172:173], v[172:173], 0, s[12:13]
	s_mov_b32 m0, s26
	ds_read_b128 v[192:195], v179 offset:49152
	ds_read_b128 v[196:199], v179 offset:50176
	ds_read_b128 v[200:203], v179 offset:51200
	ds_read_b128 v[212:215], v179 offset:52224
	ds_read_b128 v[216:219], v179 offset:53248
	ds_read_b128 v[220:223], v179 offset:54272
	ds_read_b128 v[224:227], v179 offset:55296
	ds_read_b128 v[228:231], v179 offset:56320
	global_load_lds_dwordx4 v[172:173], off
	s_add_i32 m0, s26, 0x2000
	s_add_u32 s6, s6, 0x10080
	v_lshl_add_u64 v[172:173], v[232:233], 0, s[12:13]
	s_addc_u32 s7, s7, 0
	s_add_i32 s26, s34, s42
	global_load_lds_dwordx4 v[172:173], off
	v_lshl_add_u64 v[172:173], s[6:7], 0, v[136:137]
	s_mov_b32 m0, s26
	s_nop 0
	global_load_lds_dwordx4 v[172:173], off
	v_lshl_add_u64 v[172:173], s[6:7], 0, v[132:133]
	s_add_i32 m0, s26, 0x2000
	s_nop 0
	global_load_lds_dwordx4 v[172:173], off
	v_lshl_add_u64 v[172:173], v[234:235], 0, s[12:13]
	s_mov_b32 m0, s83
	s_nop 0
	global_load_lds_dwordx4 v[172:173], off
	v_lshl_add_u64 v[172:173], v[236:237], 0, s[12:13]
	s_mov_b32 m0, s94
	s_nop 0
	global_load_lds_dwordx4 v[172:173], off
	s_waitcnt vmcnt(8)
	s_waitcnt lgkmcnt(0)
	s_barrier
	s_setprio 1
	v_mfma_i32_16x16x64_i8 v[62:65], v[152:155], v[192:195], v[62:65]
	v_mfma_i32_16x16x64_i8 v[58:61], v[160:163], v[192:195], v[58:61]
	v_mfma_i32_16x16x64_i8 v[54:57], v[152:155], v[200:203], v[54:57]
	v_mfma_i32_16x16x64_i8 v[50:53], v[160:163], v[200:203], v[50:53]
	v_mfma_i32_16x16x64_i8 v[30:33], v[152:155], v[216:219], v[30:33]
	v_mfma_i32_16x16x64_i8 v[26:29], v[160:163], v[216:219], v[26:29]
	v_mfma_i32_16x16x64_i8 v[14:17], v[152:155], v[224:227], v[14:17]
	v_mfma_i32_16x16x64_i8 v[10:13], v[160:163], v[224:227], v[10:13]
	v_mfma_i32_16x16x64_i8 v[62:65], v[156:159], v[196:199], v[62:65]
	v_mfma_i32_16x16x64_i8 v[58:61], v[164:167], v[196:199], v[58:61]
	v_mfma_i32_16x16x64_i8 v[54:57], v[156:159], v[212:215], v[54:57]
	v_mfma_i32_16x16x64_i8 v[50:53], v[164:167], v[212:215], v[50:53]
	v_mfma_i32_16x16x64_i8 v[30:33], v[156:159], v[220:223], v[30:33]
	v_mfma_i32_16x16x64_i8 v[26:29], v[164:167], v[220:223], v[26:29]
	v_mfma_i32_16x16x64_i8 v[14:17], v[156:159], v[228:231], v[14:17]
	v_mfma_i32_16x16x64_i8 v[10:13], v[164:167], v[228:231], v[10:13]
	s_setprio 0
	s_setprio 1
	v_mfma_i32_16x16x64_i8 v[46:49], v[168:171], v[192:195], v[46:49]
	v_mfma_i32_16x16x64_i8 v[42:45], v[184:187], v[192:195], v[42:45]
	v_mfma_i32_16x16x64_i8 v[38:41], v[168:171], v[200:203], v[38:41]
	v_mfma_i32_16x16x64_i8 v[34:37], v[184:187], v[200:203], v[34:37]
	v_mfma_i32_16x16x64_i8 v[22:25], v[168:171], v[216:219], v[22:25]
	v_mfma_i32_16x16x64_i8 v[18:21], v[184:187], v[216:219], v[18:21]
	v_mfma_i32_16x16x64_i8 v[6:9], v[168:171], v[224:227], v[6:9]
	v_mfma_i32_16x16x64_i8 v[2:5], v[184:187], v[224:227], v[2:5]
	v_mfma_i32_16x16x64_i8 v[46:49], v[180:183], v[196:199], v[46:49]
	v_mfma_i32_16x16x64_i8 v[42:45], v[188:191], v[196:199], v[42:45]
	v_mfma_i32_16x16x64_i8 v[38:41], v[180:183], v[212:215], v[38:41]
	v_mfma_i32_16x16x64_i8 v[34:37], v[188:191], v[212:215], v[34:37]
	v_mfma_i32_16x16x64_i8 v[22:25], v[180:183], v[220:223], v[22:25]
	v_mfma_i32_16x16x64_i8 v[18:21], v[188:191], v[220:223], v[18:21]
	v_mfma_i32_16x16x64_i8 v[6:9], v[180:183], v[228:231], v[6:9]
	v_mfma_i32_16x16x64_i8 v[2:5], v[188:191], v[228:231], v[2:5]
	s_setprio 0
	s_barrier
	s_add_i32 s30, s30, 2
	s_add_u32 s0, s0, 0x100
	s_addc_u32 s1, s1, 0
	s_add_u32 s24, s24, 0x100
	s_addc_u32 s25, s25, 0
	s_cmp_gt_u32 s30, 13
	s_cbranch_scc0 .LBB0_539
	s_and_b64 vcc, exec, s[36:37]
	s_cbranch_vccz .LBB0_542
	s_barrier

;     __device__ __forceinline__ bool next(int i, Unit& u) const { u.seg = 0; u.ks = -1; u.nt = ntk; u.koff = 0; return unit(i, u); }
;     __device__ __forceinline__ bool next(int i, Unit& u) const { const int t = i / 3; u.seg = i - 3 * t; u.ks = -1; u.nt = ntk; u.koff = 0; return unit(t, u); }
;     __device__ __forceinline__ bool next(int i, Unit& u) const { if (i > 0 || c < 80 || c >= 144) return false; const int k = c - 80; u.pm = k & 1; u.pn = k >> 1; u.seg = 0; u.ks = -1; u.nt = DM / BK; u.koff = 0; return true; }
; #define PG8_STAGE(bufoff, gbase, voff) do { _Pragma("unroll") for (int _i = 0; _i < 2; ++_i) \
;         __builtin_amdgcn_global_load_lds((const unsigned*)((const char*)(gbase) + (voff)[_i]), (LAS unsigned*)(lds + (bufoff) + ldsw + _i * 8192), 16, 0, 0); } while (0)
; #define PG8_LDA(dst, b, h) do { _Pragma("unroll") for (int m = 0; m < 4; ++m) _Pragma("unroll") for (int k = 0; k < 2; ++k) dst[m][k] = *(const LAS bf16x8*)(lds + PG8_SA(b, h) + aoff + m * 2048 + k * 1024); } while (0)
; template <class Epi, class Sched, bool I8 = false>
; __device__ __forceinline__ void gemm_phase(LAS unsigned char* lds, const Gemm g, const Sched& S, const Epi& E) {
;     ...
;         const bool has_next = S.next(ui + 1, nxt);
;         const char* nA = has_next ? g.A + (size_t)nxt.seg * g.segA + (size_t)nxt.pm * tstepA + nxt.koff : cA; const char* nB = has_next ? g.Bt + (size_t)nxt.seg * g.segB + (size_t)nxt.pn * tstepB + nxt.koff : cB;
;         const int nt = cur.nt;
;         for (int t = 0; t < nt; t += 2) {
;             const bool last = (t == nt - 2);
;             const char* a1 = cA + (size_t)(t + 1) * kstep;
;             const char* a2 = last ? nA : cA + (size_t)(t + 2) * kstep; const char* b2 = last ? nB : cB + (size_t)(t + 2) * kstep;
;             const char* a3 = a2 + kstep; const char* b3 = b2 + kstep;
;             if (PG8_SP2) {
;             PG8_LDB(B0, 0, 0); PG8_LDB(B1, 0, 1); PG8_SCHED; PG8_LDA(At, 0, 0); PG8_STAGE(PG8_SA(1, 1), a1 + hstepA, voffA);
;             PG8_WAIT_V(8); PG8_WAIT_L(0); PG8_BAR; PG8_MMA(0, 0, At, B0); PG8_MMA(0, 1, At, B1); PG8_BAR; PG8_SCHED;
;             PG8_LDA(At, 0, 1); PG8_STAGE(PG8_SB(0, 0), b2, voffB); PG8_STAGE(PG8_SB(0, 1), b2 + hstepB, voffB); PG8_STAGE(PG8_SA(0, 0), a2, voffA);
;             PG8_WAIT_V(8); PG8_WAIT_L(0); PG8_BAR; PG8_MMA(1, 0, At, B0); PG8_MMA(1, 1, At, B1); PG8_BAR; PG8_SCHED;
.LBB0_768:
	s_add_u32 s40, s0, 0xfffc0080
	s_addc_u32 s41, s1, -1
	s_add_i32 s46, 0, 0x10000
	s_cmp_eq_u32 s45, 12
	s_cselect_b32 s43, s37, s41
	s_cselect_b32 s42, s36, s40
	s_cselect_b32 s41, s9, s44
	s_cselect_b32 s40, s17, s27
	s_add_i32 s49, 0, 0x14000
	v_add_u32_e32 v14, s46, v163
	v_add_u32_e32 v130, s49, v163
	ds_read_b128 v[2:5], v14
	ds_read_b128 v[6:9], v14 offset:1024
	ds_read_b128 v[10:13], v14 offset:2048
	ds_read_b128 v[14:17], v14 offset:3072
	ds_read_b128 v[132:135], v130
	ds_read_b128 v[174:177], v130 offset:1024
	ds_read_b128 v[178:181], v130 offset:2048
	ds_read_b128 v[182:185], v130 offset:3072
	v_lshl_add_u64 v[136:137], s[0:1], 0, v[170:171]
	s_add_i32 m0, s14, 0xc000
	ds_read_b128 v[186:189], v167
	ds_read_b128 v[190:193], v167 offset:1024
	ds_read_b128 v[194:197], v167 offset:2048
	ds_read_b128 v[198:201], v167 offset:3072
	ds_read_b128 v[212:215], v167 offset:4096
	ds_read_b128 v[216:219], v167 offset:5120
	ds_read_b128 v[220:223], v167 offset:6144
	ds_read_b128 v[224:227], v167 offset:7168
	global_load_lds_dwordx4 v[136:137], off
	v_lshl_add_u64 v[136:137], s[0:1], 0, v[172:173]
	s_add_i32 m0, s14, 0xe000
	s_nop 0
	global_load_lds_dwordx4 v[136:137], off
	s_waitcnt vmcnt(8)
	s_waitcnt lgkmcnt(0)
	s_barrier
	s_setprio 1
	v_mfma_f32_16x16x32_bf16 v[150:153], v[2:5], v[186:189], v[150:153]
	v_mfma_f32_16x16x32_bf16 v[146:149], v[10:13], v[186:189], v[146:149]
	v_mfma_f32_16x16x32_bf16 v[142:145], v[2:5], v[194:197], v[142:145]
	v_mfma_f32_16x16x32_bf16 v[136:139], v[10:13], v[194:197], v[138:141]
	v_mfma_f32_16x16x32_bf16 v[126:129], v[2:5], v[212:215], v[126:129]
	v_mfma_f32_16x16x32_bf16 v[122:125], v[10:13], v[212:215], v[122:125]
	v_mfma_f32_16x16x32_bf16 v[118:121], v[2:5], v[220:223], v[118:121]
	v_mfma_f32_16x16x32_bf16 v[114:117], v[10:13], v[220:223], v[114:117]
	v_mfma_f32_16x16x32_bf16 v[150:153], v[6:9], v[190:193], v[150:153]
	v_mfma_f32_16x16x32_bf16 v[146:149], v[14:17], v[190:193], v[146:149]
	v_mfma_f32_16x16x32_bf16 v[142:145], v[6:9], v[198:201], v[142:145]
	v_mfma_f32_16x16x32_bf16 v[136:139], v[14:17], v[198:201], v[136:139]
	v_mfma_f32_16x16x32_bf16 v[126:129], v[6:9], v[216:219], v[126:129]
	v_mfma_f32_16x16x32_bf16 v[122:125], v[14:17], v[216:219], v[122:125]
	v_mfma_f32_16x16x32_bf16 v[118:121], v[6:9], v[224:227], v[118:121]
	v_mfma_f32_16x16x32_bf16 v[114:117], v[14:17], v[224:227], v[114:117]
	s_setprio 0
	s_setprio 1
	v_mfma_f32_16x16x32_bf16 v[110:113], v[132:135], v[186:189], v[110:113]
	v_mfma_f32_16x16x32_bf16 v[106:109], v[178:181], v[186:189], v[106:109]
	v_mfma_f32_16x16x32_bf16 v[102:105], v[132:135], v[194:197], v[102:105]
	v_mfma_f32_16x16x32_bf16 v[98:101], v[178:181], v[194:197], v[98:101]
	v_mfma_f32_16x16x32_bf16 v[94:97], v[132:135], v[212:215], v[94:97]
	v_mfma_f32_16x16x32_bf16 v[90:93], v[178:181], v[212:215], v[90:93]
	v_mfma_f32_16x16x32_bf16 v[86:89], v[132:135], v[220:223], v[86:89]
	v_mfma_f32_16x16x32_bf16 v[82:85], v[178:181], v[220:223], v[82:85]
	v_mfma_f32_16x16x32_bf16 v[110:113], v[174:177], v[190:193], v[110:113]
	v_mfma_f32_16x16x32_bf16 v[106:109], v[182:185], v[190:193], v[106:109]
	v_mfma_f32_16x16x32_bf16 v[102:105], v[174:177], v[198:201], v[102:105]
	v_mfma_f32_16x16x32_bf16 v[98:101], v[182:185], v[198:201], v[98:101]
	v_mfma_f32_16x16x32_bf16 v[94:97], v[174:177], v[216:219], v[94:97]
	v_mfma_f32_16x16x32_bf16 v[90:93], v[182:185], v[216:219], v[90:93]
	v_mfma_f32_16x16x32_bf16 v[86:89], v[174:177], v[224:227], v[86:89]
	v_mfma_f32_16x16x32_bf16 v[82:85], v[182:185], v[224:227], v[82:85]
	s_setprio 0
	s_barrier
	s_add_i32 s46, s46, s21
	v_lshl_add_u64 v[202:203], s[40:41], 0, v[158:159]
	s_mov_b32 m0, s46
	ds_read_b128 v[186:189], v167 offset:16384
	ds_read_b128 v[190:193], v167 offset:17408
	ds_read_b128 v[194:197], v167 offset:18432
	ds_read_b128 v[198:201], v167 offset:19456
	ds_read_b128 v[212:215], v167 offset:20480
	ds_read_b128 v[216:219], v167 offset:21504
	ds_read_b128 v[220:223], v167 offset:22528
	ds_read_b128 v[224:227], v167 offset:23552
	global_load_lds_dwordx4 v[202:203], off
	s_add_i32 m0, s46, 0x2000
	s_add_u32 s46, s40, 0x10000
	v_lshl_add_u64 v[232:233], s[40:41], 0, v[154:155]
	s_addc_u32 s47, s41, 0
	s_add_i32 s49, s49, s21
	global_load_lds_dwordx4 v[232:233], off
	v_lshl_add_u64 v[140:141], s[46:47], 0, v[158:159]
	s_mov_b32 m0, s49
	v_lshl_add_u64 v[234:235], s[42:43], 0, v[160:161]
	global_load_lds_dwordx4 v[140:141], off
	v_lshl_add_u64 v[140:141], s[46:47], 0, v[154:155]
	s_add_i32 m0, s49, 0x2000
	v_lshl_add_u64 v[236:237], s[42:43], 0, v[156:157]
	global_load_lds_dwordx4 v[140:141], off
	s_mov_b32 m0, s14
	s_nop 0
	global_load_lds_dwordx4 v[234:235], off
	s_mov_b32 m0, s22
	s_nop 0
	global_load_lds_dwordx4 v[236:237], off
	s_waitcnt vmcnt(8)
	s_waitcnt lgkmcnt(0)
	s_barrier
; #define PG8_STAGE(bufoff, gbase, voff) do { _Pragma("unroll") for (int _i = 0; _i < 2; ++_i) \
;         __builtin_amdgcn_global_load_lds((const unsigned*)((const char*)(gbase) + (voff)[_i]), (LAS unsigned*)(lds + (bufoff) + ldsw + _i * 8192), 16, 0, 0); } while (0)
; #define PG8_LDA(dst, b, h) do { _Pragma("unroll") for (int m = 0; m < 4; ++m) _Pragma("unroll") for (int k = 0; k < 2; ++k) dst[m][k] = *(const LAS bf16x8*)(lds + PG8_SA(b, h) + aoff + m * 2048 + k * 1024); } while (0)
; #define PG8_LDB(dst, b, h) do { _Pragma("unroll") for (int n = 0; n < 2; ++n) _Pragma("unroll") for (int k = 0; k < 2; ++k) dst[n][k] = *(const LAS bf16x8*)(lds + PG8_SB(b, h) + boff + n * 2048 + k * 1024); } while (0)
; #define PG8_MMA(ai, bj, At, Bt) do { __builtin_amdgcn_s_setprio(1); _Pragma("unroll") for (int m = 0; m < 4; ++m) _Pragma("unroll") for (int n = 0; n < 2; ++n) _Pragma("unroll") for (int k = 0; k < 2; ++k) \
;         acc[ai][bj][m][n] = mma16<I8>(Bt[n][k], At[m][k], acc[ai][bj][m][n]); __builtin_amdgcn_s_setprio(0); } while (0)
; #define PG8_WAIT_V(n) asm volatile("s_waitcnt vmcnt(" #n ")" ::: "memory")
; #define PG8_WAIT_L(n) asm volatile("s_waitcnt lgkmcnt(" #n ")" ::: "memory")
; #define PG8_BAR __builtin_amdgcn_s_barrier()
; #define PG8_SCHED __builtin_amdgcn_sched_barrier(0)
; template <class Epi, class Sched, bool I8 = false>
; __device__ __forceinline__ void gemm_phase(LAS unsigned char* lds, const Gemm g, const Sched& S, const Epi& E) {
;     ...
;             PG8_WAIT_V(8); PG8_WAIT_L(0); PG8_BAR; PG8_MMA(1, 0, At, B0); PG8_MMA(1, 1, At, B1); PG8_BAR; PG8_SCHED;
;             PG8_LDB(B0, 1, 0); PG8_LDB(B1, 1, 1); PG8_SCHED; PG8_LDA(At, 1, 0); PG8_STAGE(PG8_SA(0, 1), a2 + hstepA, voffA);
;             PG8_WAIT_V(8); PG8_WAIT_L(0); PG8_BAR; PG8_MMA(0, 0, At, B0); PG8_MMA(0, 1, At, B1); PG8_BAR; PG8_SCHED;
	s_setprio 1
	v_mfma_f32_16x16x32_bf16 v[78:81], v[2:5], v[186:189], v[78:81]
	v_mfma_f32_16x16x32_bf16 v[74:77], v[10:13], v[186:189], v[74:77]
	v_mfma_f32_16x16x32_bf16 v[70:73], v[2:5], v[194:197], v[70:73]
	v_mfma_f32_16x16x32_bf16 v[66:69], v[10:13], v[194:197], v[66:69]
	v_mfma_f32_16x16x32_bf16 v[62:65], v[2:5], v[212:215], v[62:65]
	v_mfma_f32_16x16x32_bf16 v[58:61], v[10:13], v[212:215], v[58:61]
	v_mfma_f32_16x16x32_bf16 v[2:5], v[2:5], v[220:223], v[54:57]
	v_mfma_f32_16x16x32_bf16 v[78:81], v[6:9], v[190:193], v[78:81]
	v_mfma_f32_16x16x32_bf16 v[74:77], v[14:17], v[190:193], v[74:77]
	v_mfma_f32_16x16x32_bf16 v[70:73], v[6:9], v[198:201], v[70:73]
	v_mfma_f32_16x16x32_bf16 v[66:69], v[14:17], v[198:201], v[66:69]
	v_mfma_f32_16x16x32_bf16 v[62:65], v[6:9], v[216:219], v[62:65]
	v_mfma_f32_16x16x32_bf16 v[58:61], v[14:17], v[216:219], v[58:61]
	v_mfma_f32_16x16x32_bf16 v[2:5], v[6:9], v[224:227], v[2:5]
	v_mfma_f32_16x16x32_bf16 v[6:9], v[10:13], v[220:223], v[50:53]
	v_mfma_f32_16x16x32_bf16 v[6:9], v[14:17], v[224:227], v[6:9]
	s_setprio 0
	s_setprio 1
	v_mfma_f32_16x16x32_bf16 v[38:41], v[132:135], v[194:197], v[38:41]
	v_mfma_f32_16x16x32_bf16 v[34:37], v[178:181], v[194:197], v[34:37]
	v_mfma_f32_16x16x32_bf16 v[30:33], v[132:135], v[212:215], v[30:33]
	v_mfma_f32_16x16x32_bf16 v[26:29], v[178:181], v[212:215], v[26:29]
	v_mfma_f32_16x16x32_bf16 v[22:25], v[132:135], v[220:223], v[22:25]
	v_mfma_f32_16x16x32_bf16 v[18:21], v[178:181], v[220:223], v[18:21]
	v_mfma_f32_16x16x32_bf16 v[10:13], v[132:135], v[186:189], v[46:49]
	v_mfma_f32_16x16x32_bf16 v[14:17], v[178:181], v[186:189], v[42:45]
	v_mfma_f32_16x16x32_bf16 v[38:41], v[174:177], v[198:201], v[38:41]
	v_mfma_f32_16x16x32_bf16 v[34:37], v[182:185], v[198:201], v[34:37]
	v_mfma_f32_16x16x32_bf16 v[30:33], v[174:177], v[216:219], v[30:33]
	v_mfma_f32_16x16x32_bf16 v[26:29], v[182:185], v[216:219], v[26:29]
	v_mfma_f32_16x16x32_bf16 v[22:25], v[174:177], v[224:227], v[22:25]
	v_mfma_f32_16x16x32_bf16 v[18:21], v[182:185], v[224:227], v[18:21]
	v_mfma_f32_16x16x32_bf16 v[10:13], v[174:177], v[190:193], v[10:13]
	v_mfma_f32_16x16x32_bf16 v[14:17], v[182:185], v[190:193], v[14:17]
	s_setprio 0
	s_barrier
	s_add_i32 s46, 0, 0x18000
	v_add_u32_e32 v54, s46, v163
	s_add_i32 s47, 0, 0x1c000
	ds_read_b128 v[42:45], v54
	ds_read_b128 v[46:49], v54 offset:1024
	ds_read_b128 v[50:53], v54 offset:2048
	ds_read_b128 v[132:135], v54 offset:3072
	v_add_u32_e32 v54, s47, v163
	ds_read_b128 v[174:177], v54
	ds_read_b128 v[178:181], v54 offset:1024
	ds_read_b128 v[182:185], v54 offset:2048
	ds_read_b128 v[186:189], v54 offset:3072
	s_add_u32 s42, s42, 0x40000
	s_addc_u32 s43, s43, 0
	s_mov_b32 m0, s23
	v_lshl_add_u64 v[140:141], s[42:43], 0, v[160:161]
	ds_read_b128 v[54:57], v167 offset:32768
	ds_read_b128 v[190:193], v167 offset:33792
	ds_read_b128 v[194:197], v167 offset:34816
	ds_read_b128 v[198:201], v167 offset:35840
	ds_read_b128 v[212:215], v167 offset:36864
	ds_read_b128 v[216:219], v167 offset:37888
	ds_read_b128 v[220:223], v167 offset:38912
	ds_read_b128 v[224:227], v167 offset:39936
	global_load_lds_dwordx4 v[140:141], off
	v_lshl_add_u64 v[140:141], s[42:43], 0, v[156:157]
	s_mov_b32 m0, s24
	s_nop 0
	global_load_lds_dwordx4 v[140:141], off
	s_waitcnt vmcnt(8)
	s_waitcnt lgkmcnt(0)
	s_barrier
	s_setprio 1
	v_mfma_f32_16x16x32_bf16 v[150:153], v[42:45], v[54:57], v[150:153]
	v_mfma_f32_16x16x32_bf16 v[146:149], v[50:53], v[54:57], v[146:149]
	v_mfma_f32_16x16x32_bf16 v[140:143], v[42:45], v[194:197], v[142:145]
	v_mfma_f32_16x16x32_bf16 v[136:139], v[50:53], v[194:197], v[136:139]
	v_mfma_f32_16x16x32_bf16 v[126:129], v[42:45], v[212:215], v[126:129]
	v_mfma_f32_16x16x32_bf16 v[122:125], v[50:53], v[212:215], v[122:125]
	v_mfma_f32_16x16x32_bf16 v[118:121], v[42:45], v[220:223], v[118:121]
	v_mfma_f32_16x16x32_bf16 v[114:117], v[50:53], v[220:223], v[114:117]
	v_mfma_f32_16x16x32_bf16 v[150:153], v[46:49], v[190:193], v[150:153]
	v_mfma_f32_16x16x32_bf16 v[146:149], v[132:135], v[190:193], v[146:149]
	v_mfma_f32_16x16x32_bf16 v[142:145], v[46:49], v[198:201], v[140:143]
	v_mfma_f32_16x16x32_bf16 v[138:141], v[132:135], v[198:201], v[136:139]
	v_mfma_f32_16x16x32_bf16 v[126:129], v[46:49], v[216:219], v[126:129]
	v_mfma_f32_16x16x32_bf16 v[122:125], v[132:135], v[216:219], v[122:125]
	v_mfma_f32_16x16x32_bf16 v[118:121], v[46:49], v[224:227], v[118:121]
	v_mfma_f32_16x16x32_bf16 v[114:117], v[132:135], v[224:227], v[114:117]
	s_setprio 0
	s_setprio 1
	v_mfma_f32_16x16x32_bf16 v[110:113], v[174:177], v[54:57], v[110:113]
	v_mfma_f32_16x16x32_bf16 v[54:57], v[182:185], v[54:57], v[106:109]
	v_mfma_f32_16x16x32_bf16 v[106:109], v[186:189], v[190:193], v[54:57]
	v_mfma_f32_16x16x32_bf16 v[54:57], v[174:177], v[194:197], v[102:105]
	v_mfma_f32_16x16x32_bf16 v[102:105], v[178:181], v[198:201], v[54:57]
	v_mfma_f32_16x16x32_bf16 v[54:57], v[182:185], v[194:197], v[98:101]
	v_mfma_f32_16x16x32_bf16 v[98:101], v[186:189], v[198:201], v[54:57]
	v_mfma_f32_16x16x32_bf16 v[54:57], v[174:177], v[212:215], v[94:97]
	v_mfma_f32_16x16x32_bf16 v[94:97], v[178:181], v[216:219], v[54:57]
	v_mfma_f32_16x16x32_bf16 v[54:57], v[182:185], v[212:215], v[90:93]
	v_mfma_f32_16x16x32_bf16 v[90:93], v[186:189], v[216:219], v[54:57]
	v_mfma_f32_16x16x32_bf16 v[54:57], v[174:177], v[220:223], v[86:89]
	v_mfma_f32_16x16x32_bf16 v[86:89], v[178:181], v[224:227], v[54:57]
	v_mfma_f32_16x16x32_bf16 v[54:57], v[182:185], v[220:223], v[82:85]
	v_mfma_f32_16x16x32_bf16 v[110:113], v[178:181], v[190:193], v[110:113]
	v_mfma_f32_16x16x32_bf16 v[82:85], v[186:189], v[224:227], v[54:57]
	s_setprio 0
	s_barrier
; #define PG8_STAGE(bufoff, gbase, voff) do { _Pragma("unroll") for (int _i = 0; _i < 2; ++_i) \
;         __builtin_amdgcn_global_load_lds((const unsigned*)((const char*)(gbase) + (voff)[_i]), (LAS unsigned*)(lds + (bufoff) + ldsw + _i * 8192), 16, 0, 0); } while (0)
; #define PG8_LDA(dst, b, h) do { _Pragma("unroll") for (int m = 0; m < 4; ++m) _Pragma("unroll") for (int k = 0; k < 2; ++k) dst[m][k] = *(const LAS bf16x8*)(lds + PG8_SA(b, h) + aoff + m * 2048 + k * 1024); } while (0)
; #define PG8_MMA(ai, bj, At, Bt) do { __builtin_amdgcn_s_setprio(1); _Pragma("unroll") for (int m = 0; m < 4; ++m) _Pragma("unroll") for (int n = 0; n < 2; ++n) _Pragma("unroll") for (int k = 0; k < 2; ++k) \
;         acc[ai][bj][m][n] = mma16<I8>(Bt[n][k], At[m][k], acc[ai][bj][m][n]); __builtin_amdgcn_s_setprio(0); } while (0)
; #define PG8_WAIT_V(n) asm volatile("s_waitcnt vmcnt(" #n ")" ::: "memory")
; #define PG8_WAIT_L(n) asm volatile("s_waitcnt lgkmcnt(" #n ")" ::: "memory")
; #define PG8_BAR __builtin_amdgcn_s_barrier()
; #define PG8_SCHED __builtin_amdgcn_sched_barrier(0)
; template <class Epi, class Sched, bool I8 = false>
; __device__ __forceinline__ void gemm_phase(LAS unsigned char* lds, const Gemm g, const Sched& S, const Epi& E) {
;     ...
;         for (int t = 0; t < nt; t += 2) {
;             const bool last = (t == nt - 2);
;     ...
;             PG8_LDA(At, 1, 1); PG8_STAGE(PG8_SB(1, 0), b3, voffB); PG8_STAGE(PG8_SB(1, 1), b3 + hstepB, voffB); PG8_STAGE(PG8_SA(1, 0), a3, voffA);
;             PG8_WAIT_V(8); PG8_WAIT_L(0); PG8_BAR; PG8_MMA(1, 0, At, B0); PG8_MMA(1, 1, At, B1); PG8_BAR; PG8_SCHED;
	s_add_i32 s42, s46, s21
	s_nop 2
	v_lshl_add_u64 v[54:55], v[202:203], 0, s[12:13]
	s_mov_b32 m0, s42
	ds_read_b128 v[190:193], v167 offset:49152
	ds_read_b128 v[194:197], v167 offset:50176
	ds_read_b128 v[198:201], v167 offset:51200
	ds_read_b128 v[212:215], v167 offset:52224
	ds_read_b128 v[216:219], v167 offset:53248
	ds_read_b128 v[220:223], v167 offset:54272
	ds_read_b128 v[224:227], v167 offset:55296
	ds_read_b128 v[228:231], v167 offset:56320
	global_load_lds_dwordx4 v[54:55], off
	s_add_i32 m0, s42, 0x2000
	s_add_u32 s40, s40, 0x10080
	v_lshl_add_u64 v[54:55], v[232:233], 0, s[12:13]
	s_addc_u32 s41, s41, 0
	s_add_i32 s42, s47, s21
	global_load_lds_dwordx4 v[54:55], off
	v_lshl_add_u64 v[54:55], s[40:41], 0, v[158:159]
	s_mov_b32 m0, s42
	s_nop 0
	global_load_lds_dwordx4 v[54:55], off
	v_lshl_add_u64 v[54:55], s[40:41], 0, v[154:155]
	s_add_i32 m0, s42, 0x2000
	s_nop 0
	global_load_lds_dwordx4 v[54:55], off
	v_lshl_add_u64 v[54:55], v[234:235], 0, s[12:13]
	s_mov_b32 m0, s29
	s_nop 0
	global_load_lds_dwordx4 v[54:55], off
	v_lshl_add_u64 v[54:55], v[236:237], 0, s[12:13]
	s_mov_b32 m0, s30
	s_nop 0
	global_load_lds_dwordx4 v[54:55], off
	s_waitcnt vmcnt(8)
	s_waitcnt lgkmcnt(0)
	s_barrier
	s_setprio 1
	v_mfma_f32_16x16x32_bf16 v[54:57], v[42:45], v[190:193], v[78:81]
	v_mfma_f32_16x16x32_bf16 v[78:81], v[46:49], v[194:197], v[54:57]
	v_mfma_f32_16x16x32_bf16 v[54:57], v[50:53], v[190:193], v[74:77]
	v_mfma_f32_16x16x32_bf16 v[74:77], v[132:135], v[194:197], v[54:57]
	v_mfma_f32_16x16x32_bf16 v[54:57], v[42:45], v[198:201], v[70:73]
	v_mfma_f32_16x16x32_bf16 v[70:73], v[46:49], v[212:215], v[54:57]
	v_mfma_f32_16x16x32_bf16 v[54:57], v[50:53], v[198:201], v[66:69]
	v_mfma_f32_16x16x32_bf16 v[66:69], v[132:135], v[212:215], v[54:57]
	v_mfma_f32_16x16x32_bf16 v[54:57], v[42:45], v[216:219], v[62:65]
	v_mfma_f32_16x16x32_bf16 v[62:65], v[46:49], v[220:223], v[54:57]
	v_mfma_f32_16x16x32_bf16 v[54:57], v[50:53], v[216:219], v[58:61]
	v_mfma_f32_16x16x32_bf16 v[2:5], v[42:45], v[224:227], v[2:5]
	v_mfma_f32_16x16x32_bf16 v[58:61], v[132:135], v[220:223], v[54:57]
	v_mfma_f32_16x16x32_bf16 v[54:57], v[46:49], v[228:231], v[2:5]
	v_mfma_f32_16x16x32_bf16 v[2:5], v[50:53], v[224:227], v[6:9]
	v_mfma_f32_16x16x32_bf16 v[50:53], v[132:135], v[228:231], v[2:5]
	s_setprio 0
	s_setprio 1
	v_mfma_f32_16x16x32_bf16 v[2:5], v[174:177], v[190:193], v[10:13]
	v_mfma_f32_16x16x32_bf16 v[46:49], v[178:181], v[194:197], v[2:5]
	v_mfma_f32_16x16x32_bf16 v[2:5], v[182:185], v[190:193], v[14:17]
	v_mfma_f32_16x16x32_bf16 v[42:45], v[186:189], v[194:197], v[2:5]
	v_mfma_f32_16x16x32_bf16 v[2:5], v[174:177], v[198:201], v[38:41]
	v_mfma_f32_16x16x32_bf16 v[38:41], v[178:181], v[212:215], v[2:5]
	v_mfma_f32_16x16x32_bf16 v[2:5], v[182:185], v[198:201], v[34:37]
	v_mfma_f32_16x16x32_bf16 v[34:37], v[186:189], v[212:215], v[2:5]
	v_mfma_f32_16x16x32_bf16 v[2:5], v[174:177], v[216:219], v[30:33]
	v_mfma_f32_16x16x32_bf16 v[30:33], v[178:181], v[220:223], v[2:5]
	v_mfma_f32_16x16x32_bf16 v[2:5], v[182:185], v[216:219], v[26:29]
	v_mfma_f32_16x16x32_bf16 v[26:29], v[186:189], v[220:223], v[2:5]
	v_mfma_f32_16x16x32_bf16 v[2:5], v[174:177], v[224:227], v[22:25]
	v_mfma_f32_16x16x32_bf16 v[22:25], v[178:181], v[228:231], v[2:5]
	v_mfma_f32_16x16x32_bf16 v[2:5], v[182:185], v[224:227], v[18:21]
	v_mfma_f32_16x16x32_bf16 v[18:21], v[186:189], v[228:231], v[2:5]
	s_setprio 0
	s_barrier
	s_add_i32 s45, s45, 2
	s_add_u32 s0, s0, 0x100
	s_addc_u32 s1, s1, 0
	s_add_u32 s27, s27, 0x100
	s_addc_u32 s44, s44, 0
	s_cmp_gt_u32 s45, 13
	s_cbranch_scc0 .LBB0_768
	s_and_b64 vcc, exec, s[6:7]
	s_cbranch_vccz .LBB0_771
	s_barrier

;     __device__ __forceinline__ bool next(int i, Unit& u) const { u.seg = 0; u.ks = -1; u.nt = ntk; u.koff = 0; return unit(i, u); }
;     __device__ __forceinline__ bool next(int i, Unit& u) const { const int t = i / 3; u.seg = i - 3 * t; u.ks = -1; u.nt = ntk; u.koff = 0; return unit(t, u); }
;     __device__ __forceinline__ bool next(int i, Unit& u) const { if (i > 0 || c < 80 || c >= 144) return false; const int k = c - 80; u.pm = k & 1; u.pn = k >> 1; u.seg = 0; u.ks = -1; u.nt = DM / BK; u.koff = 0; return true; }
; #define PG8_STAGE(bufoff, gbase, voff) do { _Pragma("unroll") for (int _i = 0; _i < 2; ++_i) \
;         __builtin_amdgcn_global_load_lds((const unsigned*)((const char*)(gbase) + (voff)[_i]), (LAS unsigned*)(lds + (bufoff) + ldsw + _i * 8192), 16, 0, 0); } while (0)
; #define PG8_LDA(dst, b, h) do { _Pragma("unroll") for (int m = 0; m < 4; ++m) _Pragma("unroll") for (int k = 0; k < 2; ++k) dst[m][k] = *(const LAS bf16x8*)(lds + PG8_SA(b, h) + aoff + m * 2048 + k * 1024); } while (0)
; template <class Epi, class Sched, bool I8 = false>
; __device__ __forceinline__ void gemm_phase(LAS unsigned char* lds, const Gemm g, const Sched& S, const Epi& E) {
;     ...
;         const bool has_next = S.next(ui + 1, nxt);
;         const char* nA = has_next ? g.A + (size_t)nxt.seg * g.segA + (size_t)nxt.pm * tstepA + nxt.koff : cA; const char* nB = has_next ? g.Bt + (size_t)nxt.seg * g.segB + (size_t)nxt.pn * tstepB + nxt.koff : cB;
;         const int nt = cur.nt;
;         for (int t = 0; t < nt; t += 2) {
;             const bool last = (t == nt - 2);
;             const char* a1 = cA + (size_t)(t + 1) * kstep;
;             const char* a2 = last ? nA : cA + (size_t)(t + 2) * kstep; const char* b2 = last ? nB : cB + (size_t)(t + 2) * kstep;
;             const char* a3 = a2 + kstep; const char* b3 = b2 + kstep;
;             if (PG8_SP2) {
;             PG8_LDB(B0, 0, 0); PG8_LDB(B1, 0, 1); PG8_SCHED; PG8_LDA(At, 0, 0); PG8_STAGE(PG8_SA(1, 1), a1 + hstepA, voffA);
;             PG8_WAIT_V(8); PG8_WAIT_L(0); PG8_BAR; PG8_MMA(0, 0, At, B0); PG8_MMA(0, 1, At, B1); PG8_BAR; PG8_SCHED;
;             PG8_LDA(At, 0, 1); PG8_STAGE(PG8_SB(0, 0), b2, voffB); PG8_STAGE(PG8_SB(0, 1), b2 + hstepB, voffB); PG8_STAGE(PG8_SA(0, 0), a2, voffA);
;             PG8_WAIT_V(8); PG8_WAIT_L(0); PG8_BAR; PG8_MMA(1, 0, At, B0); PG8_MMA(1, 1, At, B1); PG8_BAR; PG8_SCHED;
.LBB0_901:
	s_add_u32 s6, s4, 0x100
	s_addc_u32 s7, s5, 0
	s_cmp_lg_u32 s29, 12
	s_cselect_b32 s8, s6, 0
	s_add_u32 s16, s40, s8
	s_addc_u32 s17, s41, 0
	s_add_i32 s30, 0, 0x10000
	s_add_u32 s8, s0, s8
	s_addc_u32 s9, s1, 0
	s_add_i32 s31, 0, 0x14000
	v_add_u32_e32 v158, s30, v144
	v_add_u32_e32 v174, s31, v144
	ds_read_b128 v[146:149], v158
	ds_read_b128 v[150:153], v158 offset:1024
	ds_read_b128 v[154:157], v158 offset:2048
	ds_read_b128 v[158:161], v158 offset:3072
	ds_read_b128 v[162:165], v174
	ds_read_b128 v[166:169], v174 offset:1024
	ds_read_b128 v[170:173], v174 offset:2048
	ds_read_b128 v[174:177], v174 offset:3072
	v_lshl_add_u64 v[202:203], v[138:139], 0, s[4:5]
	s_add_i32 m0, s2, 0xc000
	ds_read_b128 v[178:181], v145
	ds_read_b128 v[182:185], v145 offset:1024
	ds_read_b128 v[186:189], v145 offset:2048
	ds_read_b128 v[190:193], v145 offset:3072
	ds_read_b128 v[194:197], v145 offset:4096
	ds_read_b128 v[198:201], v145 offset:5120
	ds_read_b128 v[212:215], v145 offset:6144
	ds_read_b128 v[216:219], v145 offset:7168
	global_load_lds_dwordx4 v[202:203], off
	v_lshl_add_u64 v[202:203], v[140:141], 0, s[4:5]
	s_add_i32 m0, s2, 0xe000
	s_nop 0
	global_load_lds_dwordx4 v[202:203], off
	s_waitcnt vmcnt(8)
	s_waitcnt lgkmcnt(0)
	s_barrier
	s_setprio 1
	v_mfma_f32_16x16x32_bf16 v[126:129], v[146:149], v[178:181], v[126:129]
	v_mfma_f32_16x16x32_bf16 v[122:125], v[154:157], v[178:181], v[122:125]
	v_mfma_f32_16x16x32_bf16 v[118:121], v[146:149], v[186:189], v[118:121]
	v_mfma_f32_16x16x32_bf16 v[114:117], v[154:157], v[186:189], v[114:117]
	v_mfma_f32_16x16x32_bf16 v[110:113], v[146:149], v[194:197], v[110:113]
	v_mfma_f32_16x16x32_bf16 v[102:105], v[154:157], v[194:197], v[102:105]
	v_mfma_f32_16x16x32_bf16 v[94:97], v[146:149], v[212:215], v[94:97]
	v_mfma_f32_16x16x32_bf16 v[86:89], v[154:157], v[212:215], v[86:89]
	v_mfma_f32_16x16x32_bf16 v[126:129], v[150:153], v[182:185], v[126:129]
	v_mfma_f32_16x16x32_bf16 v[122:125], v[158:161], v[182:185], v[122:125]
	v_mfma_f32_16x16x32_bf16 v[118:121], v[150:153], v[190:193], v[118:121]
	v_mfma_f32_16x16x32_bf16 v[114:117], v[158:161], v[190:193], v[114:117]
	v_mfma_f32_16x16x32_bf16 v[110:113], v[150:153], v[198:201], v[110:113]
	v_mfma_f32_16x16x32_bf16 v[102:105], v[158:161], v[198:201], v[102:105]
	v_mfma_f32_16x16x32_bf16 v[94:97], v[150:153], v[216:219], v[94:97]
	v_mfma_f32_16x16x32_bf16 v[86:89], v[158:161], v[216:219], v[86:89]
	s_setprio 0
	s_setprio 1
	v_mfma_f32_16x16x32_bf16 v[106:109], v[162:165], v[178:181], v[106:109]
	v_mfma_f32_16x16x32_bf16 v[98:101], v[170:173], v[178:181], v[98:101]
	v_mfma_f32_16x16x32_bf16 v[90:93], v[162:165], v[186:189], v[90:93]
	v_mfma_f32_16x16x32_bf16 v[82:85], v[170:173], v[186:189], v[82:85]
	v_mfma_f32_16x16x32_bf16 v[78:81], v[162:165], v[194:197], v[78:81]
	v_mfma_f32_16x16x32_bf16 v[74:77], v[170:173], v[194:197], v[74:77]
	v_mfma_f32_16x16x32_bf16 v[70:73], v[162:165], v[212:215], v[70:73]
	v_mfma_f32_16x16x32_bf16 v[66:69], v[170:173], v[212:215], v[66:69]
	v_mfma_f32_16x16x32_bf16 v[106:109], v[166:169], v[182:185], v[106:109]
	v_mfma_f32_16x16x32_bf16 v[98:101], v[174:177], v[182:185], v[98:101]
	v_mfma_f32_16x16x32_bf16 v[90:93], v[166:169], v[190:193], v[90:93]
	v_mfma_f32_16x16x32_bf16 v[82:85], v[174:177], v[190:193], v[82:85]
	v_mfma_f32_16x16x32_bf16 v[78:81], v[166:169], v[198:201], v[78:81]
	v_mfma_f32_16x16x32_bf16 v[74:77], v[174:177], v[198:201], v[74:77]
	v_mfma_f32_16x16x32_bf16 v[70:73], v[166:169], v[216:219], v[70:73]
	v_mfma_f32_16x16x32_bf16 v[66:69], v[174:177], v[216:219], v[66:69]
	s_setprio 0
	s_barrier
	s_add_i32 s4, s30, s21
	v_lshl_add_u64 v[202:203], s[8:9], 0, v[130:131]
	s_mov_b32 m0, s4
	ds_read_b128 v[178:181], v145 offset:16384
	ds_read_b128 v[182:185], v145 offset:17408
	ds_read_b128 v[186:189], v145 offset:18432
	ds_read_b128 v[190:193], v145 offset:19456
	ds_read_b128 v[194:197], v145 offset:20480
	ds_read_b128 v[198:201], v145 offset:21504
	ds_read_b128 v[212:215], v145 offset:22528
	ds_read_b128 v[216:219], v145 offset:23552
	global_load_lds_dwordx4 v[202:203], off
	s_add_i32 m0, s4, 0x2000
	s_add_u32 s4, s8, 0x10000
	v_lshl_add_u64 v[220:221], s[8:9], 0, v[132:133]
	s_addc_u32 s5, s9, 0
	s_add_i32 s30, s31, s21
	global_load_lds_dwordx4 v[220:221], off
	v_lshl_add_u64 v[222:223], s[4:5], 0, v[130:131]
	s_mov_b32 m0, s30
	v_lshl_add_u64 v[224:225], s[16:17], 0, v[134:135]
	global_load_lds_dwordx4 v[222:223], off
	v_lshl_add_u64 v[222:223], s[4:5], 0, v[132:133]
	s_add_i32 m0, s30, 0x2000
	s_nop 0
	global_load_lds_dwordx4 v[222:223], off
	v_lshl_add_u64 v[222:223], s[16:17], 0, v[136:137]
	s_mov_b32 m0, s2
	s_nop 0
	global_load_lds_dwordx4 v[222:223], off
	s_mov_b32 m0, s3
	s_nop 0
	global_load_lds_dwordx4 v[224:225], off
	s_waitcnt vmcnt(8)
	s_waitcnt lgkmcnt(0)
	s_barrier
; #define PG8_STAGE(bufoff, gbase, voff) do { _Pragma("unroll") for (int _i = 0; _i < 2; ++_i) \
;         __builtin_amdgcn_global_load_lds((const unsigned*)((const char*)(gbase) + (voff)[_i]), (LAS unsigned*)(lds + (bufoff) + ldsw + _i * 8192), 16, 0, 0); } while (0)
; #define PG8_LDA(dst, b, h) do { _Pragma("unroll") for (int m = 0; m < 4; ++m) _Pragma("unroll") for (int k = 0; k < 2; ++k) dst[m][k] = *(const LAS bf16x8*)(lds + PG8_SA(b, h) + aoff + m * 2048 + k * 1024); } while (0)
; #define PG8_LDB(dst, b, h) do { _Pragma("unroll") for (int n = 0; n < 2; ++n) _Pragma("unroll") for (int k = 0; k < 2; ++k) dst[n][k] = *(const LAS bf16x8*)(lds + PG8_SB(b, h) + boff + n * 2048 + k * 1024); } while (0)
; #define PG8_MMA(ai, bj, At, Bt) do { __builtin_amdgcn_s_setprio(1); _Pragma("unroll") for (int m = 0; m < 4; ++m) _Pragma("unroll") for (int n = 0; n < 2; ++n) _Pragma("unroll") for (int k = 0; k < 2; ++k) \
;         acc[ai][bj][m][n] = mma16<I8>(Bt[n][k], At[m][k], acc[ai][bj][m][n]); __builtin_amdgcn_s_setprio(0); } while (0)
; #define PG8_WAIT_V(n) asm volatile("s_waitcnt vmcnt(" #n ")" ::: "memory")
; #define PG8_WAIT_L(n) asm volatile("s_waitcnt lgkmcnt(" #n ")" ::: "memory")
; #define PG8_BAR __builtin_amdgcn_s_barrier()
; #define PG8_SCHED __builtin_amdgcn_sched_barrier(0)
; template <class Epi, class Sched, bool I8 = false>
; __device__ __forceinline__ void gemm_phase(LAS unsigned char* lds, const Gemm g, const Sched& S, const Epi& E) {
;     ...
;             PG8_WAIT_V(8); PG8_WAIT_L(0); PG8_BAR; PG8_MMA(1, 0, At, B0); PG8_MMA(1, 1, At, B1); PG8_BAR; PG8_SCHED;
;             PG8_LDB(B0, 1, 0); PG8_LDB(B1, 1, 1); PG8_SCHED; PG8_LDA(At, 1, 0); PG8_STAGE(PG8_SA(0, 1), a2 + hstepA, voffA);
;             PG8_WAIT_V(8); PG8_WAIT_L(0); PG8_BAR; PG8_MMA(0, 0, At, B0); PG8_MMA(0, 1, At, B1); PG8_BAR; PG8_SCHED;
	s_setprio 1
	v_mfma_f32_16x16x32_bf16 v[62:65], v[146:149], v[178:181], v[62:65]
	v_mfma_f32_16x16x32_bf16 v[58:61], v[154:157], v[178:181], v[58:61]
	v_mfma_f32_16x16x32_bf16 v[54:57], v[146:149], v[186:189], v[54:57]
	v_mfma_f32_16x16x32_bf16 v[50:53], v[154:157], v[186:189], v[50:53]
	v_mfma_f32_16x16x32_bf16 v[42:45], v[146:149], v[194:197], v[42:45]
	v_mfma_f32_16x16x32_bf16 v[34:37], v[154:157], v[194:197], v[34:37]
	v_mfma_f32_16x16x32_bf16 v[26:29], v[146:149], v[212:215], v[26:29]
	v_mfma_f32_16x16x32_bf16 v[18:21], v[154:157], v[212:215], v[18:21]
	v_mfma_f32_16x16x32_bf16 v[62:65], v[150:153], v[182:185], v[62:65]
	v_mfma_f32_16x16x32_bf16 v[58:61], v[158:161], v[182:185], v[58:61]
	v_mfma_f32_16x16x32_bf16 v[54:57], v[150:153], v[190:193], v[54:57]
	v_mfma_f32_16x16x32_bf16 v[50:53], v[158:161], v[190:193], v[50:53]
	v_mfma_f32_16x16x32_bf16 v[42:45], v[150:153], v[198:201], v[42:45]
	v_mfma_f32_16x16x32_bf16 v[34:37], v[158:161], v[198:201], v[34:37]
	v_mfma_f32_16x16x32_bf16 v[26:29], v[150:153], v[216:219], v[26:29]
	v_mfma_f32_16x16x32_bf16 v[18:21], v[158:161], v[216:219], v[18:21]
	s_setprio 0
	s_setprio 1
	v_mfma_f32_16x16x32_bf16 v[46:49], v[162:165], v[178:181], v[46:49]
	v_mfma_f32_16x16x32_bf16 v[38:41], v[170:173], v[178:181], v[38:41]
	v_mfma_f32_16x16x32_bf16 v[30:33], v[162:165], v[186:189], v[30:33]
	v_mfma_f32_16x16x32_bf16 v[22:25], v[170:173], v[186:189], v[22:25]
	v_mfma_f32_16x16x32_bf16 v[14:17], v[162:165], v[194:197], v[14:17]
	v_mfma_f32_16x16x32_bf16 v[10:13], v[170:173], v[194:197], v[10:13]
	v_mfma_f32_16x16x32_bf16 v[6:9], v[162:165], v[212:215], v[6:9]
	v_mfma_f32_16x16x32_bf16 v[2:5], v[170:173], v[212:215], v[2:5]
	v_mfma_f32_16x16x32_bf16 v[46:49], v[166:169], v[182:185], v[46:49]
	v_mfma_f32_16x16x32_bf16 v[38:41], v[174:177], v[182:185], v[38:41]
	v_mfma_f32_16x16x32_bf16 v[30:33], v[166:169], v[190:193], v[30:33]
	v_mfma_f32_16x16x32_bf16 v[22:25], v[174:177], v[190:193], v[22:25]
	v_mfma_f32_16x16x32_bf16 v[14:17], v[166:169], v[198:201], v[14:17]
	v_mfma_f32_16x16x32_bf16 v[10:13], v[174:177], v[198:201], v[10:13]
	v_mfma_f32_16x16x32_bf16 v[6:9], v[166:169], v[216:219], v[6:9]
	v_mfma_f32_16x16x32_bf16 v[2:5], v[174:177], v[216:219], v[2:5]
	s_setprio 0
	s_barrier
	s_add_i32 s30, 0, 0x18000
	s_add_i32 s31, 0, 0x1c000
	v_add_u32_e32 v158, s30, v144
	v_add_u32_e32 v174, s31, v144
	ds_read_b128 v[146:149], v158
	ds_read_b128 v[150:153], v158 offset:1024
	ds_read_b128 v[154:157], v158 offset:2048
	ds_read_b128 v[158:161], v158 offset:3072
	ds_read_b128 v[162:165], v174
	ds_read_b128 v[166:169], v174 offset:1024
	ds_read_b128 v[170:173], v174 offset:2048
	ds_read_b128 v[174:177], v174 offset:3072
	s_add_u32 s4, s16, 0x40000
	s_addc_u32 s5, s17, 0
	s_mov_b32 m0, s22
	v_lshl_add_u64 v[226:227], s[4:5], 0, v[136:137]
	ds_read_b128 v[178:181], v145 offset:32768
	ds_read_b128 v[182:185], v145 offset:33792
	ds_read_b128 v[186:189], v145 offset:34816
	ds_read_b128 v[190:193], v145 offset:35840
	ds_read_b128 v[194:197], v145 offset:36864
	ds_read_b128 v[198:201], v145 offset:37888
	ds_read_b128 v[212:215], v145 offset:38912
	ds_read_b128 v[216:219], v145 offset:39936
	global_load_lds_dwordx4 v[226:227], off
	v_lshl_add_u64 v[226:227], s[4:5], 0, v[134:135]
	s_mov_b32 m0, s23
	s_nop 0
	global_load_lds_dwordx4 v[226:227], off
	s_waitcnt vmcnt(8)
	s_waitcnt lgkmcnt(0)
	s_barrier
	s_setprio 1
	v_mfma_f32_16x16x32_bf16 v[126:129], v[146:149], v[178:181], v[126:129]
	v_mfma_f32_16x16x32_bf16 v[122:125], v[154:157], v[178:181], v[122:125]
	v_mfma_f32_16x16x32_bf16 v[118:121], v[146:149], v[186:189], v[118:121]
	v_mfma_f32_16x16x32_bf16 v[114:117], v[154:157], v[186:189], v[114:117]
	v_mfma_f32_16x16x32_bf16 v[110:113], v[146:149], v[194:197], v[110:113]
	v_mfma_f32_16x16x32_bf16 v[102:105], v[154:157], v[194:197], v[102:105]
	v_mfma_f32_16x16x32_bf16 v[94:97], v[146:149], v[212:215], v[94:97]
	v_mfma_f32_16x16x32_bf16 v[86:89], v[154:157], v[212:215], v[86:89]
	v_mfma_f32_16x16x32_bf16 v[126:129], v[150:153], v[182:185], v[126:129]
	v_mfma_f32_16x16x32_bf16 v[122:125], v[158:161], v[182:185], v[122:125]
	v_mfma_f32_16x16x32_bf16 v[118:121], v[150:153], v[190:193], v[118:121]
	v_mfma_f32_16x16x32_bf16 v[114:117], v[158:161], v[190:193], v[114:117]
	v_mfma_f32_16x16x32_bf16 v[110:113], v[150:153], v[198:201], v[110:113]
	v_mfma_f32_16x16x32_bf16 v[102:105], v[158:161], v[198:201], v[102:105]
	v_mfma_f32_16x16x32_bf16 v[94:97], v[150:153], v[216:219], v[94:97]
	v_mfma_f32_16x16x32_bf16 v[86:89], v[158:161], v[216:219], v[86:89]
	s_setprio 0
	s_setprio 1
	v_mfma_f32_16x16x32_bf16 v[106:109], v[162:165], v[178:181], v[106:109]
	v_mfma_f32_16x16x32_bf16 v[98:101], v[170:173], v[178:181], v[98:101]
	v_mfma_f32_16x16x32_bf16 v[90:93], v[162:165], v[186:189], v[90:93]
	v_mfma_f32_16x16x32_bf16 v[82:85], v[170:173], v[186:189], v[82:85]
	v_mfma_f32_16x16x32_bf16 v[78:81], v[162:165], v[194:197], v[78:81]
	v_mfma_f32_16x16x32_bf16 v[74:77], v[170:173], v[194:197], v[74:77]
	v_mfma_f32_16x16x32_bf16 v[70:73], v[162:165], v[212:215], v[70:73]
	v_mfma_f32_16x16x32_bf16 v[66:69], v[170:173], v[212:215], v[66:69]
	v_mfma_f32_16x16x32_bf16 v[106:109], v[166:169], v[182:185], v[106:109]
	v_mfma_f32_16x16x32_bf16 v[98:101], v[174:177], v[182:185], v[98:101]
	v_mfma_f32_16x16x32_bf16 v[90:93], v[166:169], v[190:193], v[90:93]
	v_mfma_f32_16x16x32_bf16 v[82:85], v[174:177], v[190:193], v[82:85]
	v_mfma_f32_16x16x32_bf16 v[78:81], v[166:169], v[198:201], v[78:81]
	v_mfma_f32_16x16x32_bf16 v[74:77], v[174:177], v[198:201], v[74:77]
	v_mfma_f32_16x16x32_bf16 v[70:73], v[166:169], v[216:219], v[70:73]
	v_mfma_f32_16x16x32_bf16 v[66:69], v[174:177], v[216:219], v[66:69]
	s_setprio 0
	s_barrier
; #define PG8_STAGE(bufoff, gbase, voff) do { _Pragma("unroll") for (int _i = 0; _i < 2; ++_i) \
;         __builtin_amdgcn_global_load_lds((const unsigned*)((const char*)(gbase) + (voff)[_i]), (LAS unsigned*)(lds + (bufoff) + ldsw + _i * 8192), 16, 0, 0); } while (0)
; #define PG8_LDA(dst, b, h) do { _Pragma("unroll") for (int m = 0; m < 4; ++m) _Pragma("unroll") for (int k = 0; k < 2; ++k) dst[m][k] = *(const LAS bf16x8*)(lds + PG8_SA(b, h) + aoff + m * 2048 + k * 1024); } while (0)
; #define PG8_MMA(ai, bj, At, Bt) do { __builtin_amdgcn_s_setprio(1); _Pragma("unroll") for (int m = 0; m < 4; ++m) _Pragma("unroll") for (int n = 0; n < 2; ++n) _Pragma("unroll") for (int k = 0; k < 2; ++k) \
;         acc[ai][bj][m][n] = mma16<I8>(Bt[n][k], At[m][k], acc[ai][bj][m][n]); __builtin_amdgcn_s_setprio(0); } while (0)
; #define PG8_WAIT_V(n) asm volatile("s_waitcnt vmcnt(" #n ")" ::: "memory")
; #define PG8_WAIT_L(n) asm volatile("s_waitcnt lgkmcnt(" #n ")" ::: "memory")
; #define PG8_BAR __builtin_amdgcn_s_barrier()
; #define PG8_SCHED __builtin_amdgcn_sched_barrier(0)
; template <class Epi, class Sched, bool I8 = false>
; __device__ __forceinline__ void gemm_phase(LAS unsigned char* lds, const Gemm g, const Sched& S, const Epi& E) {
;     ...
;         for (int t = 0; t < nt; t += 2) {
;             const bool last = (t == nt - 2);
;     ...
;             PG8_LDA(At, 1, 1); PG8_STAGE(PG8_SB(1, 0), b3, voffB); PG8_STAGE(PG8_SB(1, 1), b3 + hstepB, voffB); PG8_STAGE(PG8_SA(1, 0), a3, voffA);
;             PG8_WAIT_V(8); PG8_WAIT_L(0); PG8_BAR; PG8_MMA(1, 0, At, B0); PG8_MMA(1, 1, At, B1); PG8_BAR; PG8_SCHED;
	s_add_i32 s4, s30, s21
	v_lshl_add_u64 v[202:203], v[202:203], 0, s[12:13]
	s_mov_b32 m0, s4
	ds_read_b128 v[178:181], v145 offset:49152
	ds_read_b128 v[182:185], v145 offset:50176
	ds_read_b128 v[186:189], v145 offset:51200
	ds_read_b128 v[190:193], v145 offset:52224
	ds_read_b128 v[194:197], v145 offset:53248
	ds_read_b128 v[198:201], v145 offset:54272
	ds_read_b128 v[212:215], v145 offset:55296
	ds_read_b128 v[216:219], v145 offset:56320
	global_load_lds_dwordx4 v[202:203], off
	s_add_i32 m0, s4, 0x2000
	s_add_u32 s4, s8, 0x10080
	v_lshl_add_u64 v[202:203], v[220:221], 0, s[12:13]
	s_addc_u32 s5, s9, 0
	s_add_i32 s8, s31, s21
	global_load_lds_dwordx4 v[202:203], off
	v_lshl_add_u64 v[202:203], s[4:5], 0, v[130:131]
	s_mov_b32 m0, s8
	s_nop 0
	global_load_lds_dwordx4 v[202:203], off
	v_lshl_add_u64 v[202:203], s[4:5], 0, v[132:133]
	s_add_i32 m0, s8, 0x2000
	s_nop 0
	global_load_lds_dwordx4 v[202:203], off
	v_lshl_add_u64 v[202:203], v[222:223], 0, s[12:13]
	s_mov_b32 m0, s26
	s_nop 0
	global_load_lds_dwordx4 v[202:203], off
	v_lshl_add_u64 v[202:203], v[224:225], 0, s[12:13]
	s_mov_b32 m0, s27
	s_nop 0
	global_load_lds_dwordx4 v[202:203], off
	s_waitcnt vmcnt(8)
	s_waitcnt lgkmcnt(0)
	s_barrier
	s_setprio 1
	v_mfma_f32_16x16x32_bf16 v[62:65], v[146:149], v[178:181], v[62:65]
	v_mfma_f32_16x16x32_bf16 v[58:61], v[154:157], v[178:181], v[58:61]
	v_mfma_f32_16x16x32_bf16 v[54:57], v[146:149], v[186:189], v[54:57]
	v_mfma_f32_16x16x32_bf16 v[50:53], v[154:157], v[186:189], v[50:53]
	v_mfma_f32_16x16x32_bf16 v[42:45], v[146:149], v[194:197], v[42:45]
	v_mfma_f32_16x16x32_bf16 v[34:37], v[154:157], v[194:197], v[34:37]
	v_mfma_f32_16x16x32_bf16 v[26:29], v[146:149], v[212:215], v[26:29]
	v_mfma_f32_16x16x32_bf16 v[18:21], v[154:157], v[212:215], v[18:21]
	v_mfma_f32_16x16x32_bf16 v[62:65], v[150:153], v[182:185], v[62:65]
	v_mfma_f32_16x16x32_bf16 v[58:61], v[158:161], v[182:185], v[58:61]
	v_mfma_f32_16x16x32_bf16 v[54:57], v[150:153], v[190:193], v[54:57]
	v_mfma_f32_16x16x32_bf16 v[50:53], v[158:161], v[190:193], v[50:53]
	v_mfma_f32_16x16x32_bf16 v[42:45], v[150:153], v[198:201], v[42:45]
	v_mfma_f32_16x16x32_bf16 v[34:37], v[158:161], v[198:201], v[34:37]
	v_mfma_f32_16x16x32_bf16 v[26:29], v[150:153], v[216:219], v[26:29]
	v_mfma_f32_16x16x32_bf16 v[18:21], v[158:161], v[216:219], v[18:21]
	s_setprio 0
	s_setprio 1
	v_mfma_f32_16x16x32_bf16 v[46:49], v[162:165], v[178:181], v[46:49]
	v_mfma_f32_16x16x32_bf16 v[38:41], v[170:173], v[178:181], v[38:41]
	v_mfma_f32_16x16x32_bf16 v[30:33], v[162:165], v[186:189], v[30:33]
	v_mfma_f32_16x16x32_bf16 v[22:25], v[170:173], v[186:189], v[22:25]
	v_mfma_f32_16x16x32_bf16 v[14:17], v[162:165], v[194:197], v[14:17]
	v_mfma_f32_16x16x32_bf16 v[10:13], v[170:173], v[194:197], v[10:13]
	v_mfma_f32_16x16x32_bf16 v[6:9], v[162:165], v[212:215], v[6:9]
	v_mfma_f32_16x16x32_bf16 v[2:5], v[170:173], v[212:215], v[2:5]
	v_mfma_f32_16x16x32_bf16 v[46:49], v[166:169], v[182:185], v[46:49]
	v_mfma_f32_16x16x32_bf16 v[38:41], v[174:177], v[182:185], v[38:41]
	v_mfma_f32_16x16x32_bf16 v[30:33], v[166:169], v[190:193], v[30:33]
	v_mfma_f32_16x16x32_bf16 v[22:25], v[174:177], v[190:193], v[22:25]
	v_mfma_f32_16x16x32_bf16 v[14:17], v[166:169], v[198:201], v[14:17]
	v_mfma_f32_16x16x32_bf16 v[10:13], v[174:177], v[198:201], v[10:13]
	v_mfma_f32_16x16x32_bf16 v[6:9], v[166:169], v[216:219], v[6:9]
	v_mfma_f32_16x16x32_bf16 v[2:5], v[174:177], v[216:219], v[2:5]
	s_setprio 0
	s_barrier
	s_add_i32 s29, s29, 2
	s_cmp_gt_u32 s29, 13
	s_mov_b64 s[4:5], s[6:7]
	s_cbranch_scc0 .LBB0_901
	s_cmpk_lt_u32 s14, 0x100
	s_cbranch_scc0 .LBB0_904
	s_barrier

;     __device__ __forceinline__ bool next(int i, Unit& u) const { u.seg = 0; u.ks = -1; u.nt = ntk; u.koff = 0; return unit(i, u); }
;     __device__ __forceinline__ bool next(int i, Unit& u) const { const int t = i / 3; u.seg = i - 3 * t; u.ks = -1; u.nt = ntk; u.koff = 0; return unit(t, u); }
;     __device__ __forceinline__ bool next(int i, Unit& u) const { if (i > 0 || c < 80 || c >= 144) return false; const int k = c - 80; u.pm = k & 1; u.pn = k >> 1; u.seg = 0; u.ks = -1; u.nt = DM / BK; u.koff = 0; return true; }
; #define PG8_STAGE(bufoff, gbase, voff) do { _Pragma("unroll") for (int _i = 0; _i < 2; ++_i) \
;         __builtin_amdgcn_global_load_lds((const unsigned*)((const char*)(gbase) + (voff)[_i]), (LAS unsigned*)(lds + (bufoff) + ldsw + _i * 8192), 16, 0, 0); } while (0)
; #define PG8_LDA(dst, b, h) do { _Pragma("unroll") for (int m = 0; m < 4; ++m) _Pragma("unroll") for (int k = 0; k < 2; ++k) dst[m][k] = *(const LAS bf16x8*)(lds + PG8_SA(b, h) + aoff + m * 2048 + k * 1024); } while (0)
; template <class Epi, class Sched, bool I8 = false>
; __device__ __forceinline__ void gemm_phase(LAS unsigned char* lds, const Gemm g, const Sched& S, const Epi& E) {
;     ...
;         const bool has_next = S.next(ui + 1, nxt);
;         const char* nA = has_next ? g.A + (size_t)nxt.seg * g.segA + (size_t)nxt.pm * tstepA + nxt.koff : cA; const char* nB = has_next ? g.Bt + (size_t)nxt.seg * g.segB + (size_t)nxt.pn * tstepB + nxt.koff : cB;
;         const int nt = cur.nt;
;         for (int t = 0; t < nt; t += 2) {
;             const bool last = (t == nt - 2);
;             const char* a1 = cA + (size_t)(t + 1) * kstep;
;             const char* a2 = last ? nA : cA + (size_t)(t + 2) * kstep; const char* b2 = last ? nB : cB + (size_t)(t + 2) * kstep;
;             const char* a3 = a2 + kstep; const char* b3 = b2 + kstep;
;             if (PG8_SP2) {
;             PG8_LDB(B0, 0, 0); PG8_LDB(B1, 0, 1); PG8_SCHED; PG8_LDA(At, 0, 0); PG8_STAGE(PG8_SA(1, 1), a1 + hstepA, voffA);
;             PG8_WAIT_V(8); PG8_WAIT_L(0); PG8_BAR; PG8_MMA(0, 0, At, B0); PG8_MMA(0, 1, At, B1); PG8_BAR; PG8_SCHED;
;             PG8_LDA(At, 0, 1); PG8_STAGE(PG8_SB(0, 0), b2, voffB); PG8_STAGE(PG8_SB(0, 1), b2 + hstepB, voffB); PG8_STAGE(PG8_SA(0, 0), a2, voffA);
;             PG8_WAIT_V(8); PG8_WAIT_L(0); PG8_BAR; PG8_MMA(1, 0, At, B0); PG8_MMA(1, 1, At, B1); PG8_BAR; PG8_SCHED;
.LBB0_1153:
	s_add_i32 s63, s58, 2
	s_add_u32 s42, s40, 0xfff80080
	s_addc_u32 s43, s41, -1
	s_add_i32 s82, 0, 0x10000
	s_cmp_eq_u32 s47, s58
	s_cselect_b32 s59, s9, s43
	s_cselect_b32 s58, s45, s42
	v_add_u32_e32 v130, s82, v143
	s_cselect_b32 s43, s17, s62
	s_cselect_b32 s42, s46, s49
	s_add_i32 s84, 0, 0x14000
	ds_read_b128 v[150:153], v130
	ds_read_b128 v[154:157], v130 offset:1024
	ds_read_b128 v[158:161], v130 offset:2048
	ds_read_b128 v[162:165], v130 offset:3072
	v_add_u32_e32 v130, s84, v143
	ds_read_b128 v[166:169], v130
	ds_read_b128 v[170:173], v130 offset:1024
	ds_read_b128 v[174:177], v130 offset:2048
	ds_read_b128 v[178:181], v130 offset:3072
	v_lshl_add_u64 v[202:203], s[40:41], 0, v[146:147]
	s_add_i32 m0, s21, 0xc000
	ds_read_b128 v[182:185], v145
	ds_read_b128 v[186:189], v145 offset:1024
	ds_read_b128 v[190:193], v145 offset:2048
	ds_read_b128 v[194:197], v145 offset:3072
	ds_read_b128 v[198:201], v145 offset:4096
	ds_read_b128 v[212:215], v145 offset:5120
	ds_read_b128 v[216:219], v145 offset:6144
	ds_read_b128 v[220:223], v145 offset:7168
	global_load_lds_dwordx4 v[202:203], off
	v_lshl_add_u64 v[202:203], s[40:41], 0, v[148:149]
	s_add_i32 m0, s21, 0xe000
	s_nop 0
	global_load_lds_dwordx4 v[202:203], off
	s_waitcnt vmcnt(8)
	s_waitcnt lgkmcnt(0)
	s_barrier
	s_setprio 1
	v_mfma_f32_16x16x32_bf16 v[126:129], v[150:153], v[182:185], v[126:129]
	v_mfma_f32_16x16x32_bf16 v[122:125], v[158:161], v[182:185], v[122:125]
	v_mfma_f32_16x16x32_bf16 v[110:113], v[150:153], v[190:193], v[110:113]
	v_mfma_f32_16x16x32_bf16 v[106:109], v[158:161], v[190:193], v[106:109]
	v_mfma_f32_16x16x32_bf16 v[94:97], v[150:153], v[198:201], v[94:97]
	v_mfma_f32_16x16x32_bf16 v[90:93], v[158:161], v[198:201], v[90:93]
	v_mfma_f32_16x16x32_bf16 v[78:81], v[150:153], v[216:219], v[78:81]
	v_mfma_f32_16x16x32_bf16 v[74:77], v[158:161], v[216:219], v[74:77]
	v_mfma_f32_16x16x32_bf16 v[126:129], v[154:157], v[186:189], v[126:129]
	v_mfma_f32_16x16x32_bf16 v[122:125], v[162:165], v[186:189], v[122:125]
	v_mfma_f32_16x16x32_bf16 v[110:113], v[154:157], v[194:197], v[110:113]
	v_mfma_f32_16x16x32_bf16 v[106:109], v[162:165], v[194:197], v[106:109]
	v_mfma_f32_16x16x32_bf16 v[94:97], v[154:157], v[212:215], v[94:97]
	v_mfma_f32_16x16x32_bf16 v[90:93], v[162:165], v[212:215], v[90:93]
	v_mfma_f32_16x16x32_bf16 v[78:81], v[154:157], v[220:223], v[78:81]
	v_mfma_f32_16x16x32_bf16 v[74:77], v[162:165], v[220:223], v[74:77]
	s_setprio 0
	s_setprio 1
	v_mfma_f32_16x16x32_bf16 v[118:121], v[166:169], v[182:185], v[118:121]
	v_mfma_f32_16x16x32_bf16 v[114:117], v[174:177], v[182:185], v[114:117]
	v_mfma_f32_16x16x32_bf16 v[102:105], v[166:169], v[190:193], v[102:105]
	v_mfma_f32_16x16x32_bf16 v[98:101], v[174:177], v[190:193], v[98:101]
	v_mfma_f32_16x16x32_bf16 v[86:89], v[166:169], v[198:201], v[86:89]
	v_mfma_f32_16x16x32_bf16 v[82:85], v[174:177], v[198:201], v[82:85]
	v_mfma_f32_16x16x32_bf16 v[70:73], v[166:169], v[216:219], v[70:73]
	v_mfma_f32_16x16x32_bf16 v[66:69], v[174:177], v[216:219], v[66:69]
	v_mfma_f32_16x16x32_bf16 v[118:121], v[170:173], v[186:189], v[118:121]
	v_mfma_f32_16x16x32_bf16 v[114:117], v[178:181], v[186:189], v[114:117]
	v_mfma_f32_16x16x32_bf16 v[102:105], v[170:173], v[194:197], v[102:105]
	v_mfma_f32_16x16x32_bf16 v[98:101], v[178:181], v[194:197], v[98:101]
	v_mfma_f32_16x16x32_bf16 v[86:89], v[170:173], v[212:215], v[86:89]
	v_mfma_f32_16x16x32_bf16 v[82:85], v[178:181], v[212:215], v[82:85]
	v_mfma_f32_16x16x32_bf16 v[70:73], v[170:173], v[220:223], v[70:73]
	v_mfma_f32_16x16x32_bf16 v[66:69], v[178:181], v[220:223], v[66:69]
	s_setprio 0
	s_barrier
	s_add_i32 s82, s82, s14
	v_lshl_add_u64 v[202:203], s[42:43], 0, v[136:137]
	s_mov_b32 m0, s82
	ds_read_b128 v[182:185], v145 offset:16384
	ds_read_b128 v[186:189], v145 offset:17408
	ds_read_b128 v[190:193], v145 offset:18432
	ds_read_b128 v[194:197], v145 offset:19456
	ds_read_b128 v[198:201], v145 offset:20480
	ds_read_b128 v[212:215], v145 offset:21504
	ds_read_b128 v[216:219], v145 offset:22528
	ds_read_b128 v[220:223], v145 offset:23552
	global_load_lds_dwordx4 v[202:203], off
	s_add_i32 m0, s82, 0x2000
	s_add_u32 s82, s42, 0x20000
	v_lshl_add_u64 v[224:225], s[42:43], 0, v[132:133]
	s_addc_u32 s83, s43, 0
	s_add_i32 s84, s84, s14
	global_load_lds_dwordx4 v[224:225], off
	v_lshl_add_u64 v[226:227], s[82:83], 0, v[136:137]
	s_mov_b32 m0, s84
	v_lshl_add_u64 v[228:229], s[58:59], 0, v[134:135]
	global_load_lds_dwordx4 v[226:227], off
	v_lshl_add_u64 v[226:227], s[82:83], 0, v[132:133]
	s_add_i32 m0, s84, 0x2000
	s_nop 0
	global_load_lds_dwordx4 v[226:227], off
	v_lshl_add_u64 v[226:227], s[58:59], 0, v[138:139]
	s_mov_b32 m0, s21
	s_nop 0
	global_load_lds_dwordx4 v[226:227], off
	s_mov_b32 m0, s22
	s_nop 0
	global_load_lds_dwordx4 v[228:229], off
	s_waitcnt vmcnt(8)
	s_waitcnt lgkmcnt(0)
	s_barrier
; #define PG8_STAGE(bufoff, gbase, voff) do { _Pragma("unroll") for (int _i = 0; _i < 2; ++_i) \
;         __builtin_amdgcn_global_load_lds((const unsigned*)((const char*)(gbase) + (voff)[_i]), (LAS unsigned*)(lds + (bufoff) + ldsw + _i * 8192), 16, 0, 0); } while (0)
; #define PG8_LDA(dst, b, h) do { _Pragma("unroll") for (int m = 0; m < 4; ++m) _Pragma("unroll") for (int k = 0; k < 2; ++k) dst[m][k] = *(const LAS bf16x8*)(lds + PG8_SA(b, h) + aoff + m * 2048 + k * 1024); } while (0)
; #define PG8_LDB(dst, b, h) do { _Pragma("unroll") for (int n = 0; n < 2; ++n) _Pragma("unroll") for (int k = 0; k < 2; ++k) dst[n][k] = *(const LAS bf16x8*)(lds + PG8_SB(b, h) + boff + n * 2048 + k * 1024); } while (0)
; #define PG8_MMA(ai, bj, At, Bt) do { __builtin_amdgcn_s_setprio(1); _Pragma("unroll") for (int m = 0; m < 4; ++m) _Pragma("unroll") for (int n = 0; n < 2; ++n) _Pragma("unroll") for (int k = 0; k < 2; ++k) \
;         acc[ai][bj][m][n] = mma16<I8>(Bt[n][k], At[m][k], acc[ai][bj][m][n]); __builtin_amdgcn_s_setprio(0); } while (0)
; #define PG8_WAIT_V(n) asm volatile("s_waitcnt vmcnt(" #n ")" ::: "memory")
; #define PG8_WAIT_L(n) asm volatile("s_waitcnt lgkmcnt(" #n ")" ::: "memory")
; #define PG8_BAR __builtin_amdgcn_s_barrier()
; #define PG8_SCHED __builtin_amdgcn_sched_barrier(0)
; template <class Epi, class Sched, bool I8 = false>
; __device__ __forceinline__ void gemm_phase(LAS unsigned char* lds, const Gemm g, const Sched& S, const Epi& E) {
;     ...
;             PG8_WAIT_V(8); PG8_WAIT_L(0); PG8_BAR; PG8_MMA(1, 0, At, B0); PG8_MMA(1, 1, At, B1); PG8_BAR; PG8_SCHED;
;             PG8_LDB(B0, 1, 0); PG8_LDB(B1, 1, 1); PG8_SCHED; PG8_LDA(At, 1, 0); PG8_STAGE(PG8_SA(0, 1), a2 + hstepA, voffA);
;             PG8_WAIT_V(8); PG8_WAIT_L(0); PG8_BAR; PG8_MMA(0, 0, At, B0); PG8_MMA(0, 1, At, B1); PG8_BAR; PG8_SCHED;
	s_setprio 1
	v_mfma_f32_16x16x32_bf16 v[62:65], v[150:153], v[182:185], v[62:65]
	v_mfma_f32_16x16x32_bf16 v[58:61], v[158:161], v[182:185], v[58:61]
	v_mfma_f32_16x16x32_bf16 v[46:49], v[150:153], v[190:193], v[46:49]
	v_mfma_f32_16x16x32_bf16 v[42:45], v[158:161], v[190:193], v[42:45]
	v_mfma_f32_16x16x32_bf16 v[30:33], v[150:153], v[198:201], v[30:33]
	v_mfma_f32_16x16x32_bf16 v[26:29], v[158:161], v[198:201], v[26:29]
	v_mfma_f32_16x16x32_bf16 v[14:17], v[150:153], v[216:219], v[14:17]
	v_mfma_f32_16x16x32_bf16 v[10:13], v[158:161], v[216:219], v[10:13]
	v_mfma_f32_16x16x32_bf16 v[62:65], v[154:157], v[186:189], v[62:65]
	v_mfma_f32_16x16x32_bf16 v[58:61], v[162:165], v[186:189], v[58:61]
	v_mfma_f32_16x16x32_bf16 v[46:49], v[154:157], v[194:197], v[46:49]
	v_mfma_f32_16x16x32_bf16 v[42:45], v[162:165], v[194:197], v[42:45]
	v_mfma_f32_16x16x32_bf16 v[30:33], v[154:157], v[212:215], v[30:33]
	v_mfma_f32_16x16x32_bf16 v[26:29], v[162:165], v[212:215], v[26:29]
	v_mfma_f32_16x16x32_bf16 v[14:17], v[154:157], v[220:223], v[14:17]
	v_mfma_f32_16x16x32_bf16 v[10:13], v[162:165], v[220:223], v[10:13]
	s_setprio 0
	s_setprio 1
	v_mfma_f32_16x16x32_bf16 v[54:57], v[166:169], v[182:185], v[54:57]
	v_mfma_f32_16x16x32_bf16 v[50:53], v[174:177], v[182:185], v[50:53]
	v_mfma_f32_16x16x32_bf16 v[38:41], v[166:169], v[190:193], v[38:41]
	v_mfma_f32_16x16x32_bf16 v[34:37], v[174:177], v[190:193], v[34:37]
	v_mfma_f32_16x16x32_bf16 v[22:25], v[166:169], v[198:201], v[22:25]
	v_mfma_f32_16x16x32_bf16 v[18:21], v[174:177], v[198:201], v[18:21]
	v_mfma_f32_16x16x32_bf16 v[6:9], v[166:169], v[216:219], v[6:9]
	v_mfma_f32_16x16x32_bf16 v[2:5], v[174:177], v[216:219], v[2:5]
	v_mfma_f32_16x16x32_bf16 v[54:57], v[170:173], v[186:189], v[54:57]
	v_mfma_f32_16x16x32_bf16 v[50:53], v[178:181], v[186:189], v[50:53]
	v_mfma_f32_16x16x32_bf16 v[38:41], v[170:173], v[194:197], v[38:41]
	v_mfma_f32_16x16x32_bf16 v[34:37], v[178:181], v[194:197], v[34:37]
	v_mfma_f32_16x16x32_bf16 v[22:25], v[170:173], v[212:215], v[22:25]
	v_mfma_f32_16x16x32_bf16 v[18:21], v[178:181], v[212:215], v[18:21]
	v_mfma_f32_16x16x32_bf16 v[6:9], v[170:173], v[220:223], v[6:9]
	v_mfma_f32_16x16x32_bf16 v[2:5], v[178:181], v[220:223], v[2:5]
	s_setprio 0
	s_barrier
	s_add_i32 s82, 0, 0x18000
	v_add_u32_e32 v130, s82, v143
	s_add_i32 s83, 0, 0x1c000
	ds_read_b128 v[150:153], v130
	ds_read_b128 v[154:157], v130 offset:1024
	ds_read_b128 v[158:161], v130 offset:2048
	ds_read_b128 v[162:165], v130 offset:3072
	v_add_u32_e32 v130, s83, v143
	ds_read_b128 v[166:169], v130
	ds_read_b128 v[170:173], v130 offset:1024
	ds_read_b128 v[174:177], v130 offset:2048
	ds_read_b128 v[178:181], v130 offset:3072
	s_add_u32 s58, s58, 0x80000
	s_addc_u32 s59, s59, 0
	s_mov_b32 m0, s23
	v_lshl_add_u64 v[230:231], s[58:59], 0, v[138:139]
	ds_read_b128 v[182:185], v145 offset:32768
	ds_read_b128 v[186:189], v145 offset:33792
	ds_read_b128 v[190:193], v145 offset:34816
	ds_read_b128 v[194:197], v145 offset:35840
	ds_read_b128 v[198:201], v145 offset:36864
	ds_read_b128 v[212:215], v145 offset:37888
	ds_read_b128 v[216:219], v145 offset:38912
	ds_read_b128 v[220:223], v145 offset:39936
	global_load_lds_dwordx4 v[230:231], off
	v_lshl_add_u64 v[230:231], s[58:59], 0, v[134:135]
	s_mov_b32 m0, s24
	s_nop 0
	global_load_lds_dwordx4 v[230:231], off
	s_waitcnt vmcnt(8)
	s_waitcnt lgkmcnt(0)
	s_barrier
	s_setprio 1
	v_mfma_f32_16x16x32_bf16 v[126:129], v[150:153], v[182:185], v[126:129]
	v_mfma_f32_16x16x32_bf16 v[122:125], v[158:161], v[182:185], v[122:125]
	v_mfma_f32_16x16x32_bf16 v[110:113], v[150:153], v[190:193], v[110:113]
	v_mfma_f32_16x16x32_bf16 v[106:109], v[158:161], v[190:193], v[106:109]
	v_mfma_f32_16x16x32_bf16 v[94:97], v[150:153], v[198:201], v[94:97]
	v_mfma_f32_16x16x32_bf16 v[90:93], v[158:161], v[198:201], v[90:93]
	v_mfma_f32_16x16x32_bf16 v[78:81], v[150:153], v[216:219], v[78:81]
	v_mfma_f32_16x16x32_bf16 v[74:77], v[158:161], v[216:219], v[74:77]
	v_mfma_f32_16x16x32_bf16 v[126:129], v[154:157], v[186:189], v[126:129]
	v_mfma_f32_16x16x32_bf16 v[122:125], v[162:165], v[186:189], v[122:125]
	v_mfma_f32_16x16x32_bf16 v[110:113], v[154:157], v[194:197], v[110:113]
	v_mfma_f32_16x16x32_bf16 v[106:109], v[162:165], v[194:197], v[106:109]
	v_mfma_f32_16x16x32_bf16 v[94:97], v[154:157], v[212:215], v[94:97]
	v_mfma_f32_16x16x32_bf16 v[90:93], v[162:165], v[212:215], v[90:93]
	v_mfma_f32_16x16x32_bf16 v[78:81], v[154:157], v[220:223], v[78:81]
	v_mfma_f32_16x16x32_bf16 v[74:77], v[162:165], v[220:223], v[74:77]
	s_setprio 0
	s_setprio 1
	v_mfma_f32_16x16x32_bf16 v[118:121], v[166:169], v[182:185], v[118:121]
	v_mfma_f32_16x16x32_bf16 v[114:117], v[174:177], v[182:185], v[114:117]
	v_mfma_f32_16x16x32_bf16 v[102:105], v[166:169], v[190:193], v[102:105]
	v_mfma_f32_16x16x32_bf16 v[98:101], v[174:177], v[190:193], v[98:101]
	v_mfma_f32_16x16x32_bf16 v[86:89], v[166:169], v[198:201], v[86:89]
	v_mfma_f32_16x16x32_bf16 v[82:85], v[174:177], v[198:201], v[82:85]
	v_mfma_f32_16x16x32_bf16 v[70:73], v[166:169], v[216:219], v[70:73]
	v_mfma_f32_16x16x32_bf16 v[66:69], v[174:177], v[216:219], v[66:69]
	v_mfma_f32_16x16x32_bf16 v[118:121], v[170:173], v[186:189], v[118:121]
	v_mfma_f32_16x16x32_bf16 v[114:117], v[178:181], v[186:189], v[114:117]
	v_mfma_f32_16x16x32_bf16 v[102:105], v[170:173], v[194:197], v[102:105]
	v_mfma_f32_16x16x32_bf16 v[98:101], v[178:181], v[194:197], v[98:101]
	v_mfma_f32_16x16x32_bf16 v[86:89], v[170:173], v[212:215], v[86:89]
	v_mfma_f32_16x16x32_bf16 v[82:85], v[178:181], v[212:215], v[82:85]
	v_mfma_f32_16x16x32_bf16 v[70:73], v[170:173], v[220:223], v[70:73]
	v_mfma_f32_16x16x32_bf16 v[66:69], v[178:181], v[220:223], v[66:69]
	s_setprio 0
	s_barrier
; #define PG8_STAGE(bufoff, gbase, voff) do { _Pragma("unroll") for (int _i = 0; _i < 2; ++_i) \
;         __builtin_amdgcn_global_load_lds((const unsigned*)((const char*)(gbase) + (voff)[_i]), (LAS unsigned*)(lds + (bufoff) + ldsw + _i * 8192), 16, 0, 0); } while (0)
; #define PG8_LDA(dst, b, h) do { _Pragma("unroll") for (int m = 0; m < 4; ++m) _Pragma("unroll") for (int k = 0; k < 2; ++k) dst[m][k] = *(const LAS bf16x8*)(lds + PG8_SA(b, h) + aoff + m * 2048 + k * 1024); } while (0)
; #define PG8_MMA(ai, bj, At, Bt) do { __builtin_amdgcn_s_setprio(1); _Pragma("unroll") for (int m = 0; m < 4; ++m) _Pragma("unroll") for (int n = 0; n < 2; ++n) _Pragma("unroll") for (int k = 0; k < 2; ++k) \
;         acc[ai][bj][m][n] = mma16<I8>(Bt[n][k], At[m][k], acc[ai][bj][m][n]); __builtin_amdgcn_s_setprio(0); } while (0)
; #define PG8_WAIT_V(n) asm volatile("s_waitcnt vmcnt(" #n ")" ::: "memory")
; #define PG8_WAIT_L(n) asm volatile("s_waitcnt lgkmcnt(" #n ")" ::: "memory")
; #define PG8_BAR __builtin_amdgcn_s_barrier()
; #define PG8_SCHED __builtin_amdgcn_sched_barrier(0)
; template <class Epi, class Sched, bool I8 = false>
; __device__ __forceinline__ void gemm_phase(LAS unsigned char* lds, const Gemm g, const Sched& S, const Epi& E) {
;     ...
;             PG8_LDA(At, 1, 1); PG8_STAGE(PG8_SB(1, 0), b3, voffB); PG8_STAGE(PG8_SB(1, 1), b3 + hstepB, voffB); PG8_STAGE(PG8_SA(1, 0), a3, voffA);
;             PG8_WAIT_V(8); PG8_WAIT_L(0); PG8_BAR; PG8_MMA(1, 0, At, B0); PG8_MMA(1, 1, At, B1); PG8_BAR; PG8_SCHED;
;     ...
;         if (PG8_ALIGN) { if (wr == 0) PG8_BAR; }
	s_add_i32 s58, s82, s14
	v_lshl_add_u64 v[202:203], v[202:203], 0, s[12:13]
	s_mov_b32 m0, s58
	ds_read_b128 v[182:185], v145 offset:49152
	ds_read_b128 v[186:189], v145 offset:50176
	ds_read_b128 v[190:193], v145 offset:51200
	ds_read_b128 v[194:197], v145 offset:52224
	ds_read_b128 v[198:201], v145 offset:53248
	ds_read_b128 v[212:215], v145 offset:54272
	ds_read_b128 v[216:219], v145 offset:55296
	ds_read_b128 v[220:223], v145 offset:56320
	global_load_lds_dwordx4 v[202:203], off
	s_add_i32 m0, s58, 0x2000
	s_add_u32 s42, s42, 0x20080
	v_lshl_add_u64 v[202:203], v[224:225], 0, s[12:13]
	s_addc_u32 s43, s43, 0
	s_add_i32 s58, s83, s14
	global_load_lds_dwordx4 v[202:203], off
	v_lshl_add_u64 v[202:203], s[42:43], 0, v[136:137]
	s_mov_b32 m0, s58
	s_nop 0
	global_load_lds_dwordx4 v[202:203], off
	v_lshl_add_u64 v[202:203], s[42:43], 0, v[132:133]
	s_add_i32 m0, s58, 0x2000
	s_nop 0
	global_load_lds_dwordx4 v[202:203], off
	v_lshl_add_u64 v[202:203], v[226:227], 0, s[12:13]
	s_mov_b32 m0, s30
	s_nop 0
	global_load_lds_dwordx4 v[202:203], off
	v_lshl_add_u64 v[202:203], v[228:229], 0, s[12:13]
	s_mov_b32 m0, s31
	s_nop 0
	global_load_lds_dwordx4 v[202:203], off
	s_waitcnt vmcnt(8)
	s_waitcnt lgkmcnt(0)
	s_barrier
	s_setprio 1
	v_mfma_f32_16x16x32_bf16 v[62:65], v[150:153], v[182:185], v[62:65]
	v_mfma_f32_16x16x32_bf16 v[58:61], v[158:161], v[182:185], v[58:61]
	v_mfma_f32_16x16x32_bf16 v[46:49], v[150:153], v[190:193], v[46:49]
	v_mfma_f32_16x16x32_bf16 v[42:45], v[158:161], v[190:193], v[42:45]
	v_mfma_f32_16x16x32_bf16 v[30:33], v[150:153], v[198:201], v[30:33]
	v_mfma_f32_16x16x32_bf16 v[26:29], v[158:161], v[198:201], v[26:29]
	v_mfma_f32_16x16x32_bf16 v[14:17], v[150:153], v[216:219], v[14:17]
	v_mfma_f32_16x16x32_bf16 v[10:13], v[158:161], v[216:219], v[10:13]
	v_mfma_f32_16x16x32_bf16 v[62:65], v[154:157], v[186:189], v[62:65]
	v_mfma_f32_16x16x32_bf16 v[58:61], v[162:165], v[186:189], v[58:61]
	v_mfma_f32_16x16x32_bf16 v[46:49], v[154:157], v[194:197], v[46:49]
	v_mfma_f32_16x16x32_bf16 v[42:45], v[162:165], v[194:197], v[42:45]
	v_mfma_f32_16x16x32_bf16 v[30:33], v[154:157], v[212:215], v[30:33]
	v_mfma_f32_16x16x32_bf16 v[26:29], v[162:165], v[212:215], v[26:29]
	v_mfma_f32_16x16x32_bf16 v[14:17], v[154:157], v[220:223], v[14:17]
	v_mfma_f32_16x16x32_bf16 v[10:13], v[162:165], v[220:223], v[10:13]
	s_setprio 0
	s_setprio 1
	v_mfma_f32_16x16x32_bf16 v[54:57], v[166:169], v[182:185], v[54:57]
	v_mfma_f32_16x16x32_bf16 v[50:53], v[174:177], v[182:185], v[50:53]
	v_mfma_f32_16x16x32_bf16 v[38:41], v[166:169], v[190:193], v[38:41]
	v_mfma_f32_16x16x32_bf16 v[34:37], v[174:177], v[190:193], v[34:37]
	v_mfma_f32_16x16x32_bf16 v[22:25], v[166:169], v[198:201], v[22:25]
	v_mfma_f32_16x16x32_bf16 v[18:21], v[174:177], v[198:201], v[18:21]
	v_mfma_f32_16x16x32_bf16 v[6:9], v[166:169], v[216:219], v[6:9]
	v_mfma_f32_16x16x32_bf16 v[2:5], v[174:177], v[216:219], v[2:5]
	v_mfma_f32_16x16x32_bf16 v[54:57], v[170:173], v[186:189], v[54:57]
	v_mfma_f32_16x16x32_bf16 v[50:53], v[178:181], v[186:189], v[50:53]
	v_mfma_f32_16x16x32_bf16 v[38:41], v[170:173], v[194:197], v[38:41]
	v_mfma_f32_16x16x32_bf16 v[34:37], v[178:181], v[194:197], v[34:37]
	v_mfma_f32_16x16x32_bf16 v[22:25], v[170:173], v[212:215], v[22:25]
	v_mfma_f32_16x16x32_bf16 v[18:21], v[178:181], v[212:215], v[18:21]
	v_mfma_f32_16x16x32_bf16 v[6:9], v[170:173], v[220:223], v[6:9]
	v_mfma_f32_16x16x32_bf16 v[2:5], v[178:181], v[220:223], v[2:5]
	s_setprio 0
	s_barrier
	s_add_u32 s40, s40, 0x100
	s_addc_u32 s41, s41, 0
	s_add_u32 s49, s49, 0x100
	s_addc_u32 s62, s62, 0
	s_cmp_ge_u32 s63, s39
	s_mov_b32 s58, s63
	s_cbranch_scc0 .LBB0_1153
	s_and_b64 vcc, exec, s[4:5]
	s_cbranch_vccz .LBB0_1156
	s_barrier

; #define PG8_STAGE(bufoff, gbase, voff) do { _Pragma("unroll") for (int _i = 0; _i < 2; ++_i) \
;         __builtin_amdgcn_global_load_lds((const unsigned*)((const char*)(gbase) + (voff)[_i]), (LAS unsigned*)(lds + (bufoff) + ldsw + _i * 8192), 16, 0, 0); } while (0)
; #define PG8_LDA(dst, b, h) do { _Pragma("unroll") for (int m = 0; m < 4; ++m) _Pragma("unroll") for (int k = 0; k < 2; ++k) dst[m][k] = *(const LAS bf16x8*)(lds + PG8_SA(b, h) + aoff + m * 2048 + k * 1024); } while (0)
; #define PG8_LDB(dst, b, h) do { _Pragma("unroll") for (int n = 0; n < 2; ++n) _Pragma("unroll") for (int k = 0; k < 2; ++k) dst[n][k] = *(const LAS bf16x8*)(lds + PG8_SB(b, h) + boff + n * 2048 + k * 1024); } while (0)
; #define PG8_MMA(ai, bj, At, Bt) do { __builtin_amdgcn_s_setprio(1); _Pragma("unroll") for (int m = 0; m < 4; ++m) _Pragma("unroll") for (int n = 0; n < 2; ++n) _Pragma("unroll") for (int k = 0; k < 2; ++k) \
;         acc[ai][bj][m][n] = mma16<I8>(Bt[n][k], At[m][k], acc[ai][bj][m][n]); __builtin_amdgcn_s_setprio(0); } while (0)
; template <class Epi, class Sched, bool I8 = false>
; __device__ __forceinline__ void gemm_phase(LAS unsigned char* lds, const Gemm g, const Sched& S, const Epi& E) {
;     ...
;         const char* nA = has_next ? g.A + (size_t)nxt.seg * g.segA + (size_t)nxt.pm * tstepA + nxt.koff : cA; const char* nB = has_next ? g.Bt + (size_t)nxt.seg * g.segB + (size_t)nxt.pn * tstepB + nxt.koff : cB;
;         const int nt = cur.nt;
;         for (int t = 0; t < nt; t += 2) {
;             const bool last = (t == nt - 2);
;             const char* a1 = cA + (size_t)(t + 1) * kstep;
;             const char* a2 = last ? nA : cA + (size_t)(t + 2) * kstep; const char* b2 = last ? nB : cB + (size_t)(t + 2) * kstep;
;             const char* a3 = a2 + kstep; const char* b3 = b2 + kstep;
;             if (PG8_SP2) {
;             PG8_LDB(B0, 0, 0); PG8_LDB(B1, 0, 1); PG8_SCHED; PG8_LDA(At, 0, 0); PG8_STAGE(PG8_SA(1, 1), a1 + hstepA, voffA);
;             PG8_WAIT_V(8); PG8_WAIT_L(0); PG8_BAR; PG8_MMA(0, 0, At, B0); PG8_MMA(0, 1, At, B1); PG8_BAR; PG8_SCHED;
;             PG8_LDA(At, 0, 1); PG8_STAGE(PG8_SB(0, 0), b2, voffB); PG8_STAGE(PG8_SB(0, 1), b2 + hstepB, voffB); PG8_STAGE(PG8_SA(0, 0), a2, voffA);
;             PG8_WAIT_V(8); PG8_WAIT_L(0); PG8_BAR; PG8_MMA(1, 0, At, B0); PG8_MMA(1, 1, At, B1); PG8_BAR; PG8_SCHED;
.LBB0_1336:
	s_add_u32 s40, s0, 0xfffc0080
	s_addc_u32 s41, s1, -1
	s_add_i32 s91, 0, 0x10000
	s_cmp_eq_u32 s90, 12
	s_cselect_b32 s43, s44, s41
	s_cselect_b32 s42, s45, s40
	v_add_u32_e32 v130, s91, v164
	s_cselect_b32 s41, s55, s83
	s_cselect_b32 s40, s57, s82
	s_add_i32 s96, 0, 0x14000
	ds_read_b128 v[114:117], v130
	ds_read_b128 v[118:121], v130 offset:1024
	ds_read_b128 v[126:129], v130 offset:2048
	ds_read_b128 v[136:139], v130 offset:3072
	v_add_u32_e32 v130, s96, v164
	ds_read_b128 v[166:169], v130
	ds_read_b128 v[170:173], v130 offset:1024
	ds_read_b128 v[174:177], v130 offset:2048
	ds_read_b128 v[178:181], v130 offset:3072
	v_lshl_add_u64 v[160:161], s[0:1], 0, v[156:157]
	s_add_i32 m0, s24, 0xc000
	ds_read_b128 v[182:185], v165
	ds_read_b128 v[186:189], v165 offset:1024
	ds_read_b128 v[190:193], v165 offset:2048
	ds_read_b128 v[194:197], v165 offset:3072
	ds_read_b128 v[198:201], v165 offset:4096
	ds_read_b128 v[212:215], v165 offset:5120
	ds_read_b128 v[216:219], v165 offset:6144
	ds_read_b128 v[220:223], v165 offset:7168
	global_load_lds_dwordx4 v[160:161], off
	v_lshl_add_u64 v[160:161], s[0:1], 0, v[158:159]
	s_add_i32 m0, s24, 0xe000
	s_nop 0
	global_load_lds_dwordx4 v[160:161], off
	s_waitcnt vmcnt(8)
	s_waitcnt lgkmcnt(0)
	s_barrier
	s_setprio 1
	v_mfma_i32_16x16x64_i8 v[144:147], v[114:117], v[182:185], v[144:147]
	v_mfma_i32_16x16x64_i8 v[140:143], v[126:129], v[182:185], v[140:143]
	v_mfma_i32_16x16x64_i8 v[110:113], v[114:117], v[190:193], v[110:113]
	v_mfma_i32_16x16x64_i8 v[106:109], v[126:129], v[190:193], v[106:109]
	v_mfma_i32_16x16x64_i8 v[94:97], v[114:117], v[198:201], v[94:97]
	v_mfma_i32_16x16x64_i8 v[90:93], v[126:129], v[198:201], v[90:93]
	v_mfma_i32_16x16x64_i8 v[78:81], v[114:117], v[216:219], v[78:81]
	v_mfma_i32_16x16x64_i8 v[74:77], v[126:129], v[216:219], v[74:77]
	v_mfma_i32_16x16x64_i8 v[144:147], v[118:121], v[186:189], v[144:147]
	v_mfma_i32_16x16x64_i8 v[140:143], v[136:139], v[186:189], v[140:143]
	v_mfma_i32_16x16x64_i8 v[110:113], v[118:121], v[194:197], v[110:113]
	v_mfma_i32_16x16x64_i8 v[106:109], v[136:139], v[194:197], v[106:109]
	v_mfma_i32_16x16x64_i8 v[94:97], v[118:121], v[212:215], v[94:97]
	v_mfma_i32_16x16x64_i8 v[90:93], v[136:139], v[212:215], v[90:93]
	v_mfma_i32_16x16x64_i8 v[78:81], v[118:121], v[220:223], v[78:81]
	v_mfma_i32_16x16x64_i8 v[74:77], v[136:139], v[220:223], v[74:77]
	s_setprio 0
	s_setprio 1
	v_mfma_i32_16x16x64_i8 v[132:135], v[166:169], v[182:185], v[132:135]
	v_mfma_i32_16x16x64_i8 v[122:125], v[174:177], v[182:185], v[122:125]
	v_mfma_i32_16x16x64_i8 v[102:105], v[166:169], v[190:193], v[102:105]
	v_mfma_i32_16x16x64_i8 v[98:101], v[174:177], v[190:193], v[98:101]
	v_mfma_i32_16x16x64_i8 v[86:89], v[166:169], v[198:201], v[86:89]
	v_mfma_i32_16x16x64_i8 v[82:85], v[174:177], v[198:201], v[82:85]
	v_mfma_i32_16x16x64_i8 v[70:73], v[166:169], v[216:219], v[70:73]
	v_mfma_i32_16x16x64_i8 v[66:69], v[174:177], v[216:219], v[66:69]
	v_mfma_i32_16x16x64_i8 v[132:135], v[170:173], v[186:189], v[132:135]
	v_mfma_i32_16x16x64_i8 v[122:125], v[178:181], v[186:189], v[122:125]
	v_mfma_i32_16x16x64_i8 v[102:105], v[170:173], v[194:197], v[102:105]
	v_mfma_i32_16x16x64_i8 v[98:101], v[178:181], v[194:197], v[98:101]
	v_mfma_i32_16x16x64_i8 v[86:89], v[170:173], v[212:215], v[86:89]
	v_mfma_i32_16x16x64_i8 v[82:85], v[178:181], v[212:215], v[82:85]
	v_mfma_i32_16x16x64_i8 v[70:73], v[170:173], v[220:223], v[70:73]
	v_mfma_i32_16x16x64_i8 v[66:69], v[178:181], v[220:223], v[66:69]
	s_setprio 0
	s_barrier
	s_add_i32 s91, s91, s21
	v_lshl_add_u64 v[160:161], s[40:41], 0, v[152:153]
	s_mov_b32 m0, s91
	ds_read_b128 v[182:185], v165 offset:16384
	ds_read_b128 v[186:189], v165 offset:17408
	ds_read_b128 v[190:193], v165 offset:18432
	ds_read_b128 v[194:197], v165 offset:19456
	ds_read_b128 v[198:201], v165 offset:20480
	ds_read_b128 v[212:215], v165 offset:21504
	ds_read_b128 v[216:219], v165 offset:22528
	ds_read_b128 v[220:223], v165 offset:23552
	global_load_lds_dwordx4 v[160:161], off
	s_add_i32 m0, s91, 0x2000
	s_add_u32 s94, s40, 0x10000
	v_lshl_add_u64 v[202:203], s[40:41], 0, v[148:149]
	s_addc_u32 s95, s41, 0
	s_add_i32 s91, s96, s21
	global_load_lds_dwordx4 v[202:203], off
	v_lshl_add_u64 v[224:225], s[94:95], 0, v[152:153]
	s_mov_b32 m0, s91
	v_lshl_add_u64 v[226:227], s[42:43], 0, v[150:151]
	global_load_lds_dwordx4 v[224:225], off
	v_lshl_add_u64 v[224:225], s[94:95], 0, v[148:149]
	s_add_i32 m0, s91, 0x2000
	s_nop 0
	global_load_lds_dwordx4 v[224:225], off
	v_lshl_add_u64 v[224:225], s[42:43], 0, v[154:155]
	s_mov_b32 m0, s24
	s_nop 0
	global_load_lds_dwordx4 v[224:225], off
	s_mov_b32 m0, s25
	s_nop 0
	global_load_lds_dwordx4 v[226:227], off
	s_waitcnt vmcnt(8)
	s_waitcnt lgkmcnt(0)
	s_barrier
; #define PG8_STAGE(bufoff, gbase, voff) do { _Pragma("unroll") for (int _i = 0; _i < 2; ++_i) \
;         __builtin_amdgcn_global_load_lds((const unsigned*)((const char*)(gbase) + (voff)[_i]), (LAS unsigned*)(lds + (bufoff) + ldsw + _i * 8192), 16, 0, 0); } while (0)
; #define PG8_LDA(dst, b, h) do { _Pragma("unroll") for (int m = 0; m < 4; ++m) _Pragma("unroll") for (int k = 0; k < 2; ++k) dst[m][k] = *(const LAS bf16x8*)(lds + PG8_SA(b, h) + aoff + m * 2048 + k * 1024); } while (0)
; #define PG8_LDB(dst, b, h) do { _Pragma("unroll") for (int n = 0; n < 2; ++n) _Pragma("unroll") for (int k = 0; k < 2; ++k) dst[n][k] = *(const LAS bf16x8*)(lds + PG8_SB(b, h) + boff + n * 2048 + k * 1024); } while (0)
; #define PG8_MMA(ai, bj, At, Bt) do { __builtin_amdgcn_s_setprio(1); _Pragma("unroll") for (int m = 0; m < 4; ++m) _Pragma("unroll") for (int n = 0; n < 2; ++n) _Pragma("unroll") for (int k = 0; k < 2; ++k) \
;         acc[ai][bj][m][n] = mma16<I8>(Bt[n][k], At[m][k], acc[ai][bj][m][n]); __builtin_amdgcn_s_setprio(0); } while (0)
; #define PG8_WAIT_V(n) asm volatile("s_waitcnt vmcnt(" #n ")" ::: "memory")
; #define PG8_WAIT_L(n) asm volatile("s_waitcnt lgkmcnt(" #n ")" ::: "memory")
; #define PG8_BAR __builtin_amdgcn_s_barrier()
; #define PG8_SCHED __builtin_amdgcn_sched_barrier(0)
; template <class Epi, class Sched, bool I8 = false>
; __device__ __forceinline__ void gemm_phase(LAS unsigned char* lds, const Gemm g, const Sched& S, const Epi& E) {
;     ...
;             PG8_WAIT_V(8); PG8_WAIT_L(0); PG8_BAR; PG8_MMA(1, 0, At, B0); PG8_MMA(1, 1, At, B1); PG8_BAR; PG8_SCHED;
;             PG8_LDB(B0, 1, 0); PG8_LDB(B1, 1, 1); PG8_SCHED; PG8_LDA(At, 1, 0); PG8_STAGE(PG8_SA(0, 1), a2 + hstepA, voffA);
;             PG8_WAIT_V(8); PG8_WAIT_L(0); PG8_BAR; PG8_MMA(0, 0, At, B0); PG8_MMA(0, 1, At, B1); PG8_BAR; PG8_SCHED;
	s_setprio 1
	v_mfma_i32_16x16x64_i8 v[62:65], v[114:117], v[182:185], v[62:65]
	v_mfma_i32_16x16x64_i8 v[58:61], v[126:129], v[182:185], v[58:61]
	v_mfma_i32_16x16x64_i8 v[46:49], v[114:117], v[190:193], v[46:49]
	v_mfma_i32_16x16x64_i8 v[42:45], v[126:129], v[190:193], v[42:45]
	v_mfma_i32_16x16x64_i8 v[30:33], v[114:117], v[198:201], v[30:33]
	v_mfma_i32_16x16x64_i8 v[26:29], v[126:129], v[198:201], v[26:29]
	v_mfma_i32_16x16x64_i8 v[14:17], v[114:117], v[216:219], v[14:17]
	v_mfma_i32_16x16x64_i8 v[10:13], v[126:129], v[216:219], v[10:13]
	v_mfma_i32_16x16x64_i8 v[62:65], v[118:121], v[186:189], v[62:65]
	v_mfma_i32_16x16x64_i8 v[58:61], v[136:139], v[186:189], v[58:61]
	v_mfma_i32_16x16x64_i8 v[46:49], v[118:121], v[194:197], v[46:49]
	v_mfma_i32_16x16x64_i8 v[42:45], v[136:139], v[194:197], v[42:45]
	v_mfma_i32_16x16x64_i8 v[30:33], v[118:121], v[212:215], v[30:33]
	v_mfma_i32_16x16x64_i8 v[26:29], v[136:139], v[212:215], v[26:29]
	v_mfma_i32_16x16x64_i8 v[14:17], v[118:121], v[220:223], v[14:17]
	v_mfma_i32_16x16x64_i8 v[10:13], v[136:139], v[220:223], v[10:13]
	s_setprio 0
	s_setprio 1
	v_mfma_i32_16x16x64_i8 v[54:57], v[166:169], v[182:185], v[54:57]
	v_mfma_i32_16x16x64_i8 v[50:53], v[174:177], v[182:185], v[50:53]
	v_mfma_i32_16x16x64_i8 v[38:41], v[166:169], v[190:193], v[38:41]
	v_mfma_i32_16x16x64_i8 v[34:37], v[174:177], v[190:193], v[34:37]
	v_mfma_i32_16x16x64_i8 v[22:25], v[166:169], v[198:201], v[22:25]
	v_mfma_i32_16x16x64_i8 v[18:21], v[174:177], v[198:201], v[18:21]
	v_mfma_i32_16x16x64_i8 v[6:9], v[166:169], v[216:219], v[6:9]
	v_mfma_i32_16x16x64_i8 v[2:5], v[174:177], v[216:219], v[2:5]
	v_mfma_i32_16x16x64_i8 v[54:57], v[170:173], v[186:189], v[54:57]
	v_mfma_i32_16x16x64_i8 v[50:53], v[178:181], v[186:189], v[50:53]
	v_mfma_i32_16x16x64_i8 v[38:41], v[170:173], v[194:197], v[38:41]
	v_mfma_i32_16x16x64_i8 v[34:37], v[178:181], v[194:197], v[34:37]
	v_mfma_i32_16x16x64_i8 v[22:25], v[170:173], v[212:215], v[22:25]
	v_mfma_i32_16x16x64_i8 v[18:21], v[178:181], v[212:215], v[18:21]
	v_mfma_i32_16x16x64_i8 v[6:9], v[170:173], v[220:223], v[6:9]
	v_mfma_i32_16x16x64_i8 v[2:5], v[178:181], v[220:223], v[2:5]
	s_setprio 0
	s_barrier
	s_add_i32 s91, 0, 0x18000
	v_add_u32_e32 v130, s91, v164
	s_add_i32 s94, 0, 0x1c000
	ds_read_b128 v[114:117], v130
	ds_read_b128 v[118:121], v130 offset:1024
	ds_read_b128 v[126:129], v130 offset:2048
	ds_read_b128 v[136:139], v130 offset:3072
	v_add_u32_e32 v130, s94, v164
	ds_read_b128 v[166:169], v130
	ds_read_b128 v[170:173], v130 offset:1024
	ds_read_b128 v[174:177], v130 offset:2048
	ds_read_b128 v[178:181], v130 offset:3072
	s_add_u32 s42, s42, 0x40000
	s_addc_u32 s43, s43, 0
	s_mov_b32 m0, s29
	v_lshl_add_u64 v[228:229], s[42:43], 0, v[154:155]
	ds_read_b128 v[182:185], v165 offset:32768
	ds_read_b128 v[186:189], v165 offset:33792
	ds_read_b128 v[190:193], v165 offset:34816
	ds_read_b128 v[194:197], v165 offset:35840
	ds_read_b128 v[198:201], v165 offset:36864
	ds_read_b128 v[212:215], v165 offset:37888
	ds_read_b128 v[216:219], v165 offset:38912
	ds_read_b128 v[220:223], v165 offset:39936
	global_load_lds_dwordx4 v[228:229], off
	v_lshl_add_u64 v[228:229], s[42:43], 0, v[150:151]
	s_mov_b32 m0, s30
	s_nop 0
	global_load_lds_dwordx4 v[228:229], off
	s_waitcnt vmcnt(8)
	s_waitcnt lgkmcnt(0)
	s_barrier
	s_setprio 1
	v_mfma_i32_16x16x64_i8 v[144:147], v[114:117], v[182:185], v[144:147]
	v_mfma_i32_16x16x64_i8 v[140:143], v[126:129], v[182:185], v[140:143]
	v_mfma_i32_16x16x64_i8 v[110:113], v[114:117], v[190:193], v[110:113]
	v_mfma_i32_16x16x64_i8 v[106:109], v[126:129], v[190:193], v[106:109]
	v_mfma_i32_16x16x64_i8 v[94:97], v[114:117], v[198:201], v[94:97]
	v_mfma_i32_16x16x64_i8 v[90:93], v[126:129], v[198:201], v[90:93]
	v_mfma_i32_16x16x64_i8 v[78:81], v[114:117], v[216:219], v[78:81]
	v_mfma_i32_16x16x64_i8 v[74:77], v[126:129], v[216:219], v[74:77]
	v_mfma_i32_16x16x64_i8 v[144:147], v[118:121], v[186:189], v[144:147]
	v_mfma_i32_16x16x64_i8 v[140:143], v[136:139], v[186:189], v[140:143]
	v_mfma_i32_16x16x64_i8 v[110:113], v[118:121], v[194:197], v[110:113]
	v_mfma_i32_16x16x64_i8 v[106:109], v[136:139], v[194:197], v[106:109]
	v_mfma_i32_16x16x64_i8 v[94:97], v[118:121], v[212:215], v[94:97]
	v_mfma_i32_16x16x64_i8 v[90:93], v[136:139], v[212:215], v[90:93]
	v_mfma_i32_16x16x64_i8 v[78:81], v[118:121], v[220:223], v[78:81]
	v_mfma_i32_16x16x64_i8 v[74:77], v[136:139], v[220:223], v[74:77]
	s_setprio 0
	s_setprio 1
	v_mfma_i32_16x16x64_i8 v[132:135], v[166:169], v[182:185], v[132:135]
	v_mfma_i32_16x16x64_i8 v[122:125], v[174:177], v[182:185], v[122:125]
	v_mfma_i32_16x16x64_i8 v[102:105], v[166:169], v[190:193], v[102:105]
	v_mfma_i32_16x16x64_i8 v[98:101], v[174:177], v[190:193], v[98:101]
	v_mfma_i32_16x16x64_i8 v[86:89], v[166:169], v[198:201], v[86:89]
	v_mfma_i32_16x16x64_i8 v[82:85], v[174:177], v[198:201], v[82:85]
	v_mfma_i32_16x16x64_i8 v[70:73], v[166:169], v[216:219], v[70:73]
	v_mfma_i32_16x16x64_i8 v[66:69], v[174:177], v[216:219], v[66:69]
	v_mfma_i32_16x16x64_i8 v[132:135], v[170:173], v[186:189], v[132:135]
	v_mfma_i32_16x16x64_i8 v[122:125], v[178:181], v[186:189], v[122:125]
	v_mfma_i32_16x16x64_i8 v[102:105], v[170:173], v[194:197], v[102:105]
	v_mfma_i32_16x16x64_i8 v[98:101], v[178:181], v[194:197], v[98:101]
	v_mfma_i32_16x16x64_i8 v[86:89], v[170:173], v[212:215], v[86:89]
	v_mfma_i32_16x16x64_i8 v[82:85], v[178:181], v[212:215], v[82:85]
	v_mfma_i32_16x16x64_i8 v[70:73], v[170:173], v[220:223], v[70:73]
	v_mfma_i32_16x16x64_i8 v[66:69], v[178:181], v[220:223], v[66:69]
	s_setprio 0
	s_barrier
; #define PG8_STAGE(bufoff, gbase, voff) do { _Pragma("unroll") for (int _i = 0; _i < 2; ++_i) \
;         __builtin_amdgcn_global_load_lds((const unsigned*)((const char*)(gbase) + (voff)[_i]), (LAS unsigned*)(lds + (bufoff) + ldsw + _i * 8192), 16, 0, 0); } while (0)
; #define PG8_LDA(dst, b, h) do { _Pragma("unroll") for (int m = 0; m < 4; ++m) _Pragma("unroll") for (int k = 0; k < 2; ++k) dst[m][k] = *(const LAS bf16x8*)(lds + PG8_SA(b, h) + aoff + m * 2048 + k * 1024); } while (0)
; #define PG8_MMA(ai, bj, At, Bt) do { __builtin_amdgcn_s_setprio(1); _Pragma("unroll") for (int m = 0; m < 4; ++m) _Pragma("unroll") for (int n = 0; n < 2; ++n) _Pragma("unroll") for (int k = 0; k < 2; ++k) \
;         acc[ai][bj][m][n] = mma16<I8>(Bt[n][k], At[m][k], acc[ai][bj][m][n]); __builtin_amdgcn_s_setprio(0); } while (0)
; #define PG8_WAIT_V(n) asm volatile("s_waitcnt vmcnt(" #n ")" ::: "memory")
; #define PG8_WAIT_L(n) asm volatile("s_waitcnt lgkmcnt(" #n ")" ::: "memory")
; #define PG8_BAR __builtin_amdgcn_s_barrier()
; #define PG8_SCHED __builtin_amdgcn_sched_barrier(0)
; template <class Epi, class Sched, bool I8 = false>
; __device__ __forceinline__ void gemm_phase(LAS unsigned char* lds, const Gemm g, const Sched& S, const Epi& E) {
;     ...
;             PG8_LDA(At, 1, 1); PG8_STAGE(PG8_SB(1, 0), b3, voffB); PG8_STAGE(PG8_SB(1, 1), b3 + hstepB, voffB); PG8_STAGE(PG8_SA(1, 0), a3, voffA);
;             PG8_WAIT_V(8); PG8_WAIT_L(0); PG8_BAR; PG8_MMA(1, 0, At, B0); PG8_MMA(1, 1, At, B1); PG8_BAR; PG8_SCHED;
;     ...
;         if (PG8_ALIGN) { if (wr == 0) PG8_BAR; }
	s_add_i32 s42, s91, s21
	v_lshl_add_u64 v[160:161], v[160:161], 0, s[12:13]
	s_mov_b32 m0, s42
	ds_read_b128 v[182:185], v165 offset:49152
	ds_read_b128 v[186:189], v165 offset:50176
	ds_read_b128 v[190:193], v165 offset:51200
	ds_read_b128 v[194:197], v165 offset:52224
	ds_read_b128 v[198:201], v165 offset:53248
	ds_read_b128 v[212:215], v165 offset:54272
	ds_read_b128 v[216:219], v165 offset:55296
	ds_read_b128 v[220:223], v165 offset:56320
	global_load_lds_dwordx4 v[160:161], off
	s_add_i32 m0, s42, 0x2000
	s_add_u32 s40, s40, 0x10080
	v_lshl_add_u64 v[160:161], v[202:203], 0, s[12:13]
	s_addc_u32 s41, s41, 0
	s_add_i32 s42, s94, s21
	global_load_lds_dwordx4 v[160:161], off
	v_lshl_add_u64 v[160:161], s[40:41], 0, v[152:153]
	s_mov_b32 m0, s42
	s_nop 0
	global_load_lds_dwordx4 v[160:161], off
	v_lshl_add_u64 v[160:161], s[40:41], 0, v[148:149]
	s_add_i32 m0, s42, 0x2000
	s_nop 0
	global_load_lds_dwordx4 v[160:161], off
	v_lshl_add_u64 v[160:161], v[224:225], 0, s[12:13]
	s_mov_b32 m0, s49
	s_nop 0
	global_load_lds_dwordx4 v[160:161], off
	v_lshl_add_u64 v[160:161], v[226:227], 0, s[12:13]
	s_mov_b32 m0, s80
	s_nop 0
	global_load_lds_dwordx4 v[160:161], off
	s_waitcnt vmcnt(8)
	s_waitcnt lgkmcnt(0)
	s_barrier
	s_setprio 1
	v_mfma_i32_16x16x64_i8 v[62:65], v[114:117], v[182:185], v[62:65]
	v_mfma_i32_16x16x64_i8 v[58:61], v[126:129], v[182:185], v[58:61]
	v_mfma_i32_16x16x64_i8 v[46:49], v[114:117], v[190:193], v[46:49]
	v_mfma_i32_16x16x64_i8 v[42:45], v[126:129], v[190:193], v[42:45]
	v_mfma_i32_16x16x64_i8 v[30:33], v[114:117], v[198:201], v[30:33]
	v_mfma_i32_16x16x64_i8 v[26:29], v[126:129], v[198:201], v[26:29]
	v_mfma_i32_16x16x64_i8 v[14:17], v[114:117], v[216:219], v[14:17]
	v_mfma_i32_16x16x64_i8 v[10:13], v[126:129], v[216:219], v[10:13]
	v_mfma_i32_16x16x64_i8 v[62:65], v[118:121], v[186:189], v[62:65]
	v_mfma_i32_16x16x64_i8 v[58:61], v[136:139], v[186:189], v[58:61]
	v_mfma_i32_16x16x64_i8 v[46:49], v[118:121], v[194:197], v[46:49]
	v_mfma_i32_16x16x64_i8 v[42:45], v[136:139], v[194:197], v[42:45]
	v_mfma_i32_16x16x64_i8 v[30:33], v[118:121], v[212:215], v[30:33]
	v_mfma_i32_16x16x64_i8 v[26:29], v[136:139], v[212:215], v[26:29]
	v_mfma_i32_16x16x64_i8 v[14:17], v[118:121], v[220:223], v[14:17]
	v_mfma_i32_16x16x64_i8 v[10:13], v[136:139], v[220:223], v[10:13]
	s_setprio 0
	s_setprio 1
	v_mfma_i32_16x16x64_i8 v[54:57], v[166:169], v[182:185], v[54:57]
	v_mfma_i32_16x16x64_i8 v[50:53], v[174:177], v[182:185], v[50:53]
	v_mfma_i32_16x16x64_i8 v[38:41], v[166:169], v[190:193], v[38:41]
	v_mfma_i32_16x16x64_i8 v[34:37], v[174:177], v[190:193], v[34:37]
	v_mfma_i32_16x16x64_i8 v[22:25], v[166:169], v[198:201], v[22:25]
	v_mfma_i32_16x16x64_i8 v[18:21], v[174:177], v[198:201], v[18:21]
	v_mfma_i32_16x16x64_i8 v[6:9], v[166:169], v[216:219], v[6:9]
	v_mfma_i32_16x16x64_i8 v[2:5], v[174:177], v[216:219], v[2:5]
	v_mfma_i32_16x16x64_i8 v[54:57], v[170:173], v[186:189], v[54:57]
	v_mfma_i32_16x16x64_i8 v[50:53], v[178:181], v[186:189], v[50:53]
	v_mfma_i32_16x16x64_i8 v[38:41], v[170:173], v[194:197], v[38:41]
	v_mfma_i32_16x16x64_i8 v[34:37], v[178:181], v[194:197], v[34:37]
	v_mfma_i32_16x16x64_i8 v[22:25], v[170:173], v[212:215], v[22:25]
	v_mfma_i32_16x16x64_i8 v[18:21], v[178:181], v[212:215], v[18:21]
	v_mfma_i32_16x16x64_i8 v[6:9], v[170:173], v[220:223], v[6:9]
	v_mfma_i32_16x16x64_i8 v[2:5], v[178:181], v[220:223], v[2:5]
	s_setprio 0
	s_barrier
	s_add_i32 s90, s90, 2
	s_add_u32 s0, s0, 0x100
	s_addc_u32 s1, s1, 0
	s_add_u32 s82, s82, 0x100
	s_addc_u32 s83, s83, 0
	s_cmp_gt_u32 s90, 13
	s_cbranch_scc0 .LBB0_1336
	s_and_b64 vcc, exec, s[6:7]
	s_cbranch_vccz .LBB0_1339
	s_barrier

; #define PG8_STAGE(bufoff, gbase, voff) do { _Pragma("unroll") for (int _i = 0; _i < 2; ++_i) \
;         __builtin_amdgcn_global_load_lds((const unsigned*)((const char*)(gbase) + (voff)[_i]), (LAS unsigned*)(lds + (bufoff) + ldsw + _i * 8192), 16, 0, 0); } while (0)
; #define PG8_LDA(dst, b, h) do { _Pragma("unroll") for (int m = 0; m < 4; ++m) _Pragma("unroll") for (int k = 0; k < 2; ++k) dst[m][k] = *(const LAS bf16x8*)(lds + PG8_SA(b, h) + aoff + m * 2048 + k * 1024); } while (0)
; #define PG8_LDB(dst, b, h) do { _Pragma("unroll") for (int n = 0; n < 2; ++n) _Pragma("unroll") for (int k = 0; k < 2; ++k) dst[n][k] = *(const LAS bf16x8*)(lds + PG8_SB(b, h) + boff + n * 2048 + k * 1024); } while (0)
; #define PG8_MMA(ai, bj, At, Bt) do { __builtin_amdgcn_s_setprio(1); _Pragma("unroll") for (int m = 0; m < 4; ++m) _Pragma("unroll") for (int n = 0; n < 2; ++n) _Pragma("unroll") for (int k = 0; k < 2; ++k) \
;         acc[ai][bj][m][n] = mma16<I8>(Bt[n][k], At[m][k], acc[ai][bj][m][n]); __builtin_amdgcn_s_setprio(0); } while (0)
; template <class Epi, class Sched, bool I8 = false>
; __device__ __forceinline__ void gemm_phase(LAS unsigned char* lds, const Gemm g, const Sched& S, const Epi& E) {
;     ...
;         const char* nA = has_next ? g.A + (size_t)nxt.seg * g.segA + (size_t)nxt.pm * tstepA + nxt.koff : cA; const char* nB = has_next ? g.Bt + (size_t)nxt.seg * g.segB + (size_t)nxt.pn * tstepB + nxt.koff : cB;
;         const int nt = cur.nt;
;         for (int t = 0; t < nt; t += 2) {
;             const bool last = (t == nt - 2);
;             const char* a1 = cA + (size_t)(t + 1) * kstep;
;             const char* a2 = last ? nA : cA + (size_t)(t + 2) * kstep; const char* b2 = last ? nB : cB + (size_t)(t + 2) * kstep;
;             const char* a3 = a2 + kstep; const char* b3 = b2 + kstep;
;             if (PG8_SP2) {
;             PG8_LDB(B0, 0, 0); PG8_LDB(B1, 0, 1); PG8_SCHED; PG8_LDA(At, 0, 0); PG8_STAGE(PG8_SA(1, 1), a1 + hstepA, voffA);
;             PG8_WAIT_V(8); PG8_WAIT_L(0); PG8_BAR; PG8_MMA(0, 0, At, B0); PG8_MMA(0, 1, At, B1); PG8_BAR; PG8_SCHED;
;             PG8_LDA(At, 0, 1); PG8_STAGE(PG8_SB(0, 0), b2, voffB); PG8_STAGE(PG8_SB(0, 1), b2 + hstepB, voffB); PG8_STAGE(PG8_SA(0, 0), a2, voffA);
;             PG8_WAIT_V(8); PG8_WAIT_L(0); PG8_BAR; PG8_MMA(1, 0, At, B0); PG8_MMA(1, 1, At, B1); PG8_BAR; PG8_SCHED;
.LBB0_1574:
	s_add_i32 s80, s42, 2
	s_add_u32 s40, s0, 0xfff00080
	s_addc_u32 s41, s1, -1
	s_add_i32 s82, 0, 0x10000
	s_cmp_eq_u32 s56, s42
	s_cselect_b32 s43, s23, s41
	s_cselect_b32 s42, s44, s40
	s_cselect_b32 s41, s45, s63
	s_cselect_b32 s40, s46, s57
	s_add_i32 s91, 0, 0x14000
	v_add_u32_e32 v62, s82, v175
	v_add_u32_e32 v78, s91, v175
	ds_read_b128 v[50:53], v62
	ds_read_b128 v[54:57], v62 offset:1024
	ds_read_b128 v[58:61], v62 offset:2048
	ds_read_b128 v[62:65], v62 offset:3072
	ds_read_b128 v[66:69], v78
	ds_read_b128 v[70:73], v78 offset:1024
	ds_read_b128 v[74:77], v78 offset:2048
	ds_read_b128 v[78:81], v78 offset:3072
	v_lshl_add_u64 v[202:203], s[0:1], 0, v[178:179]
	s_add_i32 m0, s34, 0xc000
	ds_read_b128 v[182:185], v177
	ds_read_b128 v[186:189], v177 offset:1024
	ds_read_b128 v[190:193], v177 offset:2048
	ds_read_b128 v[194:197], v177 offset:3072
	ds_read_b128 v[198:201], v177 offset:4096
	ds_read_b128 v[212:215], v177 offset:5120
	ds_read_b128 v[216:219], v177 offset:6144
	ds_read_b128 v[220:223], v177 offset:7168
	global_load_lds_dwordx4 v[202:203], off
	v_lshl_add_u64 v[202:203], s[0:1], 0, v[180:181]
	s_add_i32 m0, s34, 0xe000
	s_nop 0
	global_load_lds_dwordx4 v[202:203], off
	s_waitcnt vmcnt(8)
	s_waitcnt lgkmcnt(0)
	s_barrier
	s_setprio 1
	v_mfma_i32_16x16x64_i8 v[160:163], v[50:53], v[182:185], v[160:163]
	v_mfma_i32_16x16x64_i8 v[156:159], v[58:61], v[182:185], v[156:159]
	v_mfma_i32_16x16x64_i8 v[144:147], v[50:53], v[190:193], v[144:147]
	v_mfma_i32_16x16x64_i8 v[140:143], v[58:61], v[190:193], v[140:143]
	v_mfma_i32_16x16x64_i8 v[126:129], v[50:53], v[198:201], v[126:129]
	v_mfma_i32_16x16x64_i8 v[122:125], v[58:61], v[198:201], v[122:125]
	v_mfma_i32_16x16x64_i8 v[110:113], v[50:53], v[216:219], v[110:113]
	v_mfma_i32_16x16x64_i8 v[106:109], v[58:61], v[216:219], v[106:109]
	v_mfma_i32_16x16x64_i8 v[160:163], v[54:57], v[186:189], v[160:163]
	v_mfma_i32_16x16x64_i8 v[156:159], v[62:65], v[186:189], v[156:159]
	v_mfma_i32_16x16x64_i8 v[144:147], v[54:57], v[194:197], v[144:147]
	v_mfma_i32_16x16x64_i8 v[140:143], v[62:65], v[194:197], v[140:143]
	v_mfma_i32_16x16x64_i8 v[126:129], v[54:57], v[212:215], v[126:129]
	v_mfma_i32_16x16x64_i8 v[122:125], v[62:65], v[212:215], v[122:125]
	v_mfma_i32_16x16x64_i8 v[110:113], v[54:57], v[220:223], v[110:113]
	v_mfma_i32_16x16x64_i8 v[106:109], v[62:65], v[220:223], v[106:109]
	s_setprio 0
	s_setprio 1
	v_mfma_i32_16x16x64_i8 v[152:155], v[66:69], v[182:185], v[152:155]
	v_mfma_i32_16x16x64_i8 v[148:151], v[74:77], v[182:185], v[148:151]
	v_mfma_i32_16x16x64_i8 v[136:139], v[66:69], v[190:193], v[136:139]
	v_mfma_i32_16x16x64_i8 v[132:135], v[74:77], v[190:193], v[132:135]
	v_mfma_i32_16x16x64_i8 v[118:121], v[66:69], v[198:201], v[118:121]
	v_mfma_i32_16x16x64_i8 v[114:117], v[74:77], v[198:201], v[114:117]
	v_mfma_i32_16x16x64_i8 v[102:105], v[66:69], v[216:219], v[102:105]
	v_mfma_i32_16x16x64_i8 v[98:101], v[74:77], v[216:219], v[98:101]
	v_mfma_i32_16x16x64_i8 v[152:155], v[70:73], v[186:189], v[152:155]
	v_mfma_i32_16x16x64_i8 v[148:151], v[78:81], v[186:189], v[148:151]
	v_mfma_i32_16x16x64_i8 v[136:139], v[70:73], v[194:197], v[136:139]
	v_mfma_i32_16x16x64_i8 v[132:135], v[78:81], v[194:197], v[132:135]
	v_mfma_i32_16x16x64_i8 v[118:121], v[70:73], v[212:215], v[118:121]
	v_mfma_i32_16x16x64_i8 v[114:117], v[78:81], v[212:215], v[114:117]
	v_mfma_i32_16x16x64_i8 v[102:105], v[70:73], v[220:223], v[102:105]
	v_mfma_i32_16x16x64_i8 v[98:101], v[78:81], v[220:223], v[98:101]
	s_setprio 0
	s_barrier
	s_add_i32 s82, s82, s85
	v_lshl_add_u64 v[202:203], s[40:41], 0, v[168:169]
	s_mov_b32 m0, s82
	ds_read_b128 v[182:185], v177 offset:16384
	ds_read_b128 v[186:189], v177 offset:17408
	ds_read_b128 v[190:193], v177 offset:18432
	ds_read_b128 v[194:197], v177 offset:19456
	ds_read_b128 v[198:201], v177 offset:20480
	ds_read_b128 v[212:215], v177 offset:21504
	ds_read_b128 v[216:219], v177 offset:22528
	ds_read_b128 v[220:223], v177 offset:23552
	global_load_lds_dwordx4 v[202:203], off
	s_add_i32 m0, s82, 0x2000
	s_add_u32 s82, s40, 0x40000
	v_lshl_add_u64 v[228:229], s[40:41], 0, v[164:165]
	s_addc_u32 s83, s41, 0
	s_add_i32 s91, s91, s85
	global_load_lds_dwordx4 v[228:229], off
	v_lshl_add_u64 v[224:225], s[82:83], 0, v[168:169]
	s_mov_b32 m0, s91
	v_lshl_add_u64 v[230:231], s[42:43], 0, v[170:171]
	global_load_lds_dwordx4 v[224:225], off
	v_lshl_add_u64 v[224:225], s[82:83], 0, v[164:165]
	s_add_i32 m0, s91, 0x2000
	v_lshl_add_u64 v[232:233], s[42:43], 0, v[166:167]
	global_load_lds_dwordx4 v[224:225], off
	s_mov_b32 m0, s34
	s_nop 0
	global_load_lds_dwordx4 v[230:231], off
	s_mov_b32 m0, s35
	s_nop 0
	global_load_lds_dwordx4 v[232:233], off
	s_waitcnt vmcnt(8)
	s_waitcnt lgkmcnt(0)
	s_barrier
; #define PG8_STAGE(bufoff, gbase, voff) do { _Pragma("unroll") for (int _i = 0; _i < 2; ++_i) \
;         __builtin_amdgcn_global_load_lds((const unsigned*)((const char*)(gbase) + (voff)[_i]), (LAS unsigned*)(lds + (bufoff) + ldsw + _i * 8192), 16, 0, 0); } while (0)
; #define PG8_LDA(dst, b, h) do { _Pragma("unroll") for (int m = 0; m < 4; ++m) _Pragma("unroll") for (int k = 0; k < 2; ++k) dst[m][k] = *(const LAS bf16x8*)(lds + PG8_SA(b, h) + aoff + m * 2048 + k * 1024); } while (0)
; #define PG8_LDB(dst, b, h) do { _Pragma("unroll") for (int n = 0; n < 2; ++n) _Pragma("unroll") for (int k = 0; k < 2; ++k) dst[n][k] = *(const LAS bf16x8*)(lds + PG8_SB(b, h) + boff + n * 2048 + k * 1024); } while (0)
; #define PG8_MMA(ai, bj, At, Bt) do { __builtin_amdgcn_s_setprio(1); _Pragma("unroll") for (int m = 0; m < 4; ++m) _Pragma("unroll") for (int n = 0; n < 2; ++n) _Pragma("unroll") for (int k = 0; k < 2; ++k) \
;         acc[ai][bj][m][n] = mma16<I8>(Bt[n][k], At[m][k], acc[ai][bj][m][n]); __builtin_amdgcn_s_setprio(0); } while (0)
; #define PG8_WAIT_V(n) asm volatile("s_waitcnt vmcnt(" #n ")" ::: "memory")
; #define PG8_WAIT_L(n) asm volatile("s_waitcnt lgkmcnt(" #n ")" ::: "memory")
; #define PG8_BAR __builtin_amdgcn_s_barrier()
; #define PG8_SCHED __builtin_amdgcn_sched_barrier(0)
; template <class Epi, class Sched, bool I8 = false>
; __device__ __forceinline__ void gemm_phase(LAS unsigned char* lds, const Gemm g, const Sched& S, const Epi& E) {
;     ...
;             PG8_WAIT_V(8); PG8_WAIT_L(0); PG8_BAR; PG8_MMA(1, 0, At, B0); PG8_MMA(1, 1, At, B1); PG8_BAR; PG8_SCHED;
;             PG8_LDB(B0, 1, 0); PG8_LDB(B1, 1, 1); PG8_SCHED; PG8_LDA(At, 1, 0); PG8_STAGE(PG8_SA(0, 1), a2 + hstepA, voffA);
;             PG8_WAIT_V(8); PG8_WAIT_L(0); PG8_BAR; PG8_MMA(0, 0, At, B0); PG8_MMA(0, 1, At, B1); PG8_BAR; PG8_SCHED;
	s_setprio 1
	v_mfma_i32_16x16x64_i8 v[94:97], v[50:53], v[182:185], v[94:97]
	v_mfma_i32_16x16x64_i8 v[90:93], v[58:61], v[182:185], v[90:93]
	v_mfma_i32_16x16x64_i8 v[46:49], v[50:53], v[190:193], v[46:49]
	v_mfma_i32_16x16x64_i8 v[42:45], v[58:61], v[190:193], v[42:45]
	v_mfma_i32_16x16x64_i8 v[30:33], v[50:53], v[198:201], v[30:33]
	v_mfma_i32_16x16x64_i8 v[26:29], v[58:61], v[198:201], v[26:29]
	v_mfma_i32_16x16x64_i8 v[14:17], v[50:53], v[216:219], v[14:17]
	v_mfma_i32_16x16x64_i8 v[10:13], v[58:61], v[216:219], v[10:13]
	v_mfma_i32_16x16x64_i8 v[94:97], v[54:57], v[186:189], v[94:97]
	v_mfma_i32_16x16x64_i8 v[90:93], v[62:65], v[186:189], v[90:93]
	v_mfma_i32_16x16x64_i8 v[46:49], v[54:57], v[194:197], v[46:49]
	v_mfma_i32_16x16x64_i8 v[42:45], v[62:65], v[194:197], v[42:45]
	v_mfma_i32_16x16x64_i8 v[30:33], v[54:57], v[212:215], v[30:33]
	v_mfma_i32_16x16x64_i8 v[26:29], v[62:65], v[212:215], v[26:29]
	v_mfma_i32_16x16x64_i8 v[14:17], v[54:57], v[220:223], v[14:17]
	v_mfma_i32_16x16x64_i8 v[10:13], v[62:65], v[220:223], v[10:13]
	s_setprio 0
	s_setprio 1
	v_mfma_i32_16x16x64_i8 v[38:41], v[66:69], v[190:193], v[38:41]
	v_mfma_i32_16x16x64_i8 v[34:37], v[74:77], v[190:193], v[34:37]
	v_mfma_i32_16x16x64_i8 v[22:25], v[66:69], v[198:201], v[22:25]
	v_mfma_i32_16x16x64_i8 v[18:21], v[74:77], v[198:201], v[18:21]
	v_mfma_i32_16x16x64_i8 v[6:9], v[66:69], v[216:219], v[6:9]
	v_mfma_i32_16x16x64_i8 v[2:5], v[74:77], v[216:219], v[2:5]
	v_mfma_i32_16x16x64_i8 v[50:53], v[66:69], v[182:185], v[86:89]
	v_mfma_i32_16x16x64_i8 v[54:57], v[74:77], v[182:185], v[82:85]
	v_mfma_i32_16x16x64_i8 v[38:41], v[70:73], v[194:197], v[38:41]
	v_mfma_i32_16x16x64_i8 v[34:37], v[78:81], v[194:197], v[34:37]
	v_mfma_i32_16x16x64_i8 v[22:25], v[70:73], v[212:215], v[22:25]
	v_mfma_i32_16x16x64_i8 v[18:21], v[78:81], v[212:215], v[18:21]
	v_mfma_i32_16x16x64_i8 v[6:9], v[70:73], v[220:223], v[6:9]
	v_mfma_i32_16x16x64_i8 v[2:5], v[78:81], v[220:223], v[2:5]
	v_mfma_i32_16x16x64_i8 v[50:53], v[70:73], v[186:189], v[50:53]
	v_mfma_i32_16x16x64_i8 v[54:57], v[78:81], v[186:189], v[54:57]
	s_setprio 0
	s_barrier
	s_add_i32 s82, 0, 0x18000
	s_add_i32 s83, 0, 0x1c000
	v_add_u32_e32 v70, s82, v175
	v_add_u32_e32 v82, s83, v175
	ds_read_b128 v[58:61], v70
	ds_read_b128 v[62:65], v70 offset:1024
	ds_read_b128 v[66:69], v70 offset:2048
	ds_read_b128 v[70:73], v70 offset:3072
	ds_read_b128 v[74:77], v82
	ds_read_b128 v[78:81], v82 offset:1024
	ds_read_b128 v[182:185], v82 offset:2048
	ds_read_b128 v[186:189], v82 offset:3072
	s_add_u32 s42, s42, 0x100000
	s_addc_u32 s43, s43, 0
	s_mov_b32 m0, s30
	v_lshl_add_u64 v[224:225], s[42:43], 0, v[170:171]
	ds_read_b128 v[82:85], v177 offset:32768
	ds_read_b128 v[86:89], v177 offset:33792
	ds_read_b128 v[190:193], v177 offset:34816
	ds_read_b128 v[194:197], v177 offset:35840
	ds_read_b128 v[198:201], v177 offset:36864
	ds_read_b128 v[212:215], v177 offset:37888
	ds_read_b128 v[216:219], v177 offset:38912
	ds_read_b128 v[220:223], v177 offset:39936
	global_load_lds_dwordx4 v[224:225], off
	v_lshl_add_u64 v[224:225], s[42:43], 0, v[166:167]
	s_mov_b32 m0, s31
	s_nop 0
	global_load_lds_dwordx4 v[224:225], off
	s_waitcnt vmcnt(8)
	s_waitcnt lgkmcnt(0)
	s_barrier
	s_setprio 1
	v_mfma_i32_16x16x64_i8 v[160:163], v[58:61], v[82:85], v[160:163]
	v_mfma_i32_16x16x64_i8 v[156:159], v[66:69], v[82:85], v[156:159]
	v_mfma_i32_16x16x64_i8 v[144:147], v[58:61], v[190:193], v[144:147]
	v_mfma_i32_16x16x64_i8 v[140:143], v[66:69], v[190:193], v[140:143]
	v_mfma_i32_16x16x64_i8 v[126:129], v[58:61], v[198:201], v[126:129]
	v_mfma_i32_16x16x64_i8 v[122:125], v[66:69], v[198:201], v[122:125]
	v_mfma_i32_16x16x64_i8 v[110:113], v[58:61], v[216:219], v[110:113]
	v_mfma_i32_16x16x64_i8 v[106:109], v[66:69], v[216:219], v[106:109]
	v_mfma_i32_16x16x64_i8 v[160:163], v[62:65], v[86:89], v[160:163]
	v_mfma_i32_16x16x64_i8 v[156:159], v[70:73], v[86:89], v[156:159]
	v_mfma_i32_16x16x64_i8 v[144:147], v[62:65], v[194:197], v[144:147]
	v_mfma_i32_16x16x64_i8 v[140:143], v[70:73], v[194:197], v[140:143]
	v_mfma_i32_16x16x64_i8 v[126:129], v[62:65], v[212:215], v[126:129]
	v_mfma_i32_16x16x64_i8 v[122:125], v[70:73], v[212:215], v[122:125]
	v_mfma_i32_16x16x64_i8 v[110:113], v[62:65], v[220:223], v[110:113]
	v_mfma_i32_16x16x64_i8 v[106:109], v[70:73], v[220:223], v[106:109]
	s_setprio 0
	s_setprio 1
	v_mfma_i32_16x16x64_i8 v[152:155], v[74:77], v[82:85], v[152:155]
	v_mfma_i32_16x16x64_i8 v[82:85], v[182:185], v[82:85], v[148:151]
	v_mfma_i32_16x16x64_i8 v[148:151], v[186:189], v[86:89], v[82:85]
	v_mfma_i32_16x16x64_i8 v[82:85], v[74:77], v[190:193], v[136:139]
	v_mfma_i32_16x16x64_i8 v[136:139], v[78:81], v[194:197], v[82:85]
	v_mfma_i32_16x16x64_i8 v[82:85], v[182:185], v[190:193], v[132:135]
	v_mfma_i32_16x16x64_i8 v[132:135], v[186:189], v[194:197], v[82:85]
	v_mfma_i32_16x16x64_i8 v[82:85], v[74:77], v[198:201], v[118:121]
	v_mfma_i32_16x16x64_i8 v[118:121], v[78:81], v[212:215], v[82:85]
	v_mfma_i32_16x16x64_i8 v[82:85], v[182:185], v[198:201], v[114:117]
	v_mfma_i32_16x16x64_i8 v[114:117], v[186:189], v[212:215], v[82:85]
	v_mfma_i32_16x16x64_i8 v[82:85], v[74:77], v[216:219], v[102:105]
	v_mfma_i32_16x16x64_i8 v[102:105], v[78:81], v[220:223], v[82:85]
	v_mfma_i32_16x16x64_i8 v[82:85], v[182:185], v[216:219], v[98:101]
	v_mfma_i32_16x16x64_i8 v[152:155], v[78:81], v[86:89], v[152:155]
	v_mfma_i32_16x16x64_i8 v[98:101], v[186:189], v[220:223], v[82:85]
	s_setprio 0
	s_barrier
; #define PG8_STAGE(bufoff, gbase, voff) do { _Pragma("unroll") for (int _i = 0; _i < 2; ++_i) \
;         __builtin_amdgcn_global_load_lds((const unsigned*)((const char*)(gbase) + (voff)[_i]), (LAS unsigned*)(lds + (bufoff) + ldsw + _i * 8192), 16, 0, 0); } while (0)
; #define PG8_LDA(dst, b, h) do { _Pragma("unroll") for (int m = 0; m < 4; ++m) _Pragma("unroll") for (int k = 0; k < 2; ++k) dst[m][k] = *(const LAS bf16x8*)(lds + PG8_SA(b, h) + aoff + m * 2048 + k * 1024); } while (0)
; #define PG8_MMA(ai, bj, At, Bt) do { __builtin_amdgcn_s_setprio(1); _Pragma("unroll") for (int m = 0; m < 4; ++m) _Pragma("unroll") for (int n = 0; n < 2; ++n) _Pragma("unroll") for (int k = 0; k < 2; ++k) \
;         acc[ai][bj][m][n] = mma16<I8>(Bt[n][k], At[m][k], acc[ai][bj][m][n]); __builtin_amdgcn_s_setprio(0); } while (0)
; #define PG8_WAIT_V(n) asm volatile("s_waitcnt vmcnt(" #n ")" ::: "memory")
; #define PG8_WAIT_L(n) asm volatile("s_waitcnt lgkmcnt(" #n ")" ::: "memory")
; #define PG8_BAR __builtin_amdgcn_s_barrier()
; #define PG8_SCHED __builtin_amdgcn_sched_barrier(0)
; template <class Epi, class Sched, bool I8 = false>
; __device__ __forceinline__ void gemm_phase(LAS unsigned char* lds, const Gemm g, const Sched& S, const Epi& E) {
;     ...
;             PG8_LDA(At, 1, 1); PG8_STAGE(PG8_SB(1, 0), b3, voffB); PG8_STAGE(PG8_SB(1, 1), b3 + hstepB, voffB); PG8_STAGE(PG8_SA(1, 0), a3, voffA);
;             PG8_WAIT_V(8); PG8_WAIT_L(0); PG8_BAR; PG8_MMA(1, 0, At, B0); PG8_MMA(1, 1, At, B1); PG8_BAR; PG8_SCHED;
;     ...
;         if (PG8_ALIGN) { if (wr == 0) PG8_BAR; }
	s_add_i32 s42, s82, s85
	v_lshl_add_u64 v[86:87], v[202:203], 0, s[12:13]
	s_mov_b32 m0, s42
	s_nop 0
	ds_read_b128 v[82:85], v177 offset:49152
	ds_read_b128 v[190:193], v177 offset:50176
	ds_read_b128 v[194:197], v177 offset:51200
	ds_read_b128 v[198:201], v177 offset:52224
	ds_read_b128 v[212:215], v177 offset:53248
	ds_read_b128 v[216:219], v177 offset:54272
	ds_read_b128 v[220:223], v177 offset:55296
	ds_read_b128 v[224:227], v177 offset:56320
	global_load_lds_dwordx4 v[86:87], off
	s_add_i32 m0, s42, 0x2000
	s_add_u32 s40, s40, 0x40080
	v_lshl_add_u64 v[86:87], v[228:229], 0, s[12:13]
	s_addc_u32 s41, s41, 0
	s_add_i32 s42, s83, s85
	global_load_lds_dwordx4 v[86:87], off
	v_lshl_add_u64 v[86:87], s[40:41], 0, v[168:169]
	s_mov_b32 m0, s42
	s_nop 0
	global_load_lds_dwordx4 v[86:87], off
	v_lshl_add_u64 v[86:87], s[40:41], 0, v[164:165]
	s_add_i32 m0, s42, 0x2000
	s_nop 0
	global_load_lds_dwordx4 v[86:87], off
	v_lshl_add_u64 v[86:87], v[230:231], 0, s[12:13]
	s_mov_b32 m0, s3
	s_nop 0
	global_load_lds_dwordx4 v[86:87], off
	v_lshl_add_u64 v[86:87], v[232:233], 0, s[12:13]
	s_mov_b32 m0, s2
	s_nop 0
	global_load_lds_dwordx4 v[86:87], off
	s_waitcnt vmcnt(8)
	s_waitcnt lgkmcnt(0)
	s_barrier
	s_setprio 1
	v_mfma_i32_16x16x64_i8 v[86:89], v[58:61], v[82:85], v[94:97]
	v_mfma_i32_16x16x64_i8 v[94:97], v[62:65], v[190:193], v[86:89]
	v_mfma_i32_16x16x64_i8 v[86:89], v[66:69], v[82:85], v[90:93]
	v_mfma_i32_16x16x64_i8 v[46:49], v[58:61], v[194:197], v[46:49]
	v_mfma_i32_16x16x64_i8 v[42:45], v[66:69], v[194:197], v[42:45]
	v_mfma_i32_16x16x64_i8 v[30:33], v[58:61], v[212:215], v[30:33]
	v_mfma_i32_16x16x64_i8 v[26:29], v[66:69], v[212:215], v[26:29]
	v_mfma_i32_16x16x64_i8 v[14:17], v[58:61], v[220:223], v[14:17]
	v_mfma_i32_16x16x64_i8 v[10:13], v[66:69], v[220:223], v[10:13]
	v_mfma_i32_16x16x64_i8 v[90:93], v[70:73], v[190:193], v[86:89]
	v_mfma_i32_16x16x64_i8 v[46:49], v[62:65], v[198:201], v[46:49]
	v_mfma_i32_16x16x64_i8 v[42:45], v[70:73], v[198:201], v[42:45]
	v_mfma_i32_16x16x64_i8 v[30:33], v[62:65], v[216:219], v[30:33]
	v_mfma_i32_16x16x64_i8 v[26:29], v[70:73], v[216:219], v[26:29]
	v_mfma_i32_16x16x64_i8 v[14:17], v[62:65], v[224:227], v[14:17]
	v_mfma_i32_16x16x64_i8 v[10:13], v[70:73], v[224:227], v[10:13]
	s_setprio 0
	s_setprio 1
	v_mfma_i32_16x16x64_i8 v[50:53], v[74:77], v[82:85], v[50:53]
	v_mfma_i32_16x16x64_i8 v[86:89], v[78:81], v[190:193], v[50:53]
	v_mfma_i32_16x16x64_i8 v[50:53], v[182:185], v[82:85], v[54:57]
	v_mfma_i32_16x16x64_i8 v[38:41], v[74:77], v[194:197], v[38:41]
	v_mfma_i32_16x16x64_i8 v[34:37], v[182:185], v[194:197], v[34:37]
	v_mfma_i32_16x16x64_i8 v[22:25], v[74:77], v[212:215], v[22:25]
	v_mfma_i32_16x16x64_i8 v[18:21], v[182:185], v[212:215], v[18:21]
	v_mfma_i32_16x16x64_i8 v[6:9], v[74:77], v[220:223], v[6:9]
	v_mfma_i32_16x16x64_i8 v[2:5], v[182:185], v[220:223], v[2:5]
	v_mfma_i32_16x16x64_i8 v[82:85], v[186:189], v[190:193], v[50:53]
	v_mfma_i32_16x16x64_i8 v[38:41], v[78:81], v[198:201], v[38:41]
	v_mfma_i32_16x16x64_i8 v[34:37], v[186:189], v[198:201], v[34:37]
	v_mfma_i32_16x16x64_i8 v[22:25], v[78:81], v[216:219], v[22:25]
	v_mfma_i32_16x16x64_i8 v[18:21], v[186:189], v[216:219], v[18:21]
	v_mfma_i32_16x16x64_i8 v[6:9], v[78:81], v[224:227], v[6:9]
	v_mfma_i32_16x16x64_i8 v[2:5], v[186:189], v[224:227], v[2:5]
	s_setprio 0
	s_barrier
	s_add_u32 s0, s0, 0x100
	s_addc_u32 s1, s1, 0
	s_add_u32 s57, s57, 0x100
	s_addc_u32 s63, s63, 0
	s_cmp_ge_u32 s80, s22
	s_mov_b32 s42, s80
	s_cbranch_scc0 .LBB0_1574
	s_and_b64 vcc, exec, s[36:37]
	s_cbranch_vccz .LBB0_1577
	s_barrier
